# baseline (speedup 1.0000x reference)
; template <int EPI>
; __device__ __forceinline__ void phase_gemm(const Params& p, const GemmDesc& d, char* shmc) {
;     ...
;       float cw[2][4];
; #pragma unroll
;       for (int n = 0; n < 2; ++n) {
;         const int chx = ch0 + ewc * 32 + n * 16 + efr;
;         cw[n][0] = cwp[chx]; cw[n][1] = cwp[DFF + chx]; cw[n][2] = cwp[2 * DFF + chx]; cw[n][3] = cbp[chx];
;       }
;       const float* rsl = reinterpret_cast<const float*>(shmc + 143360);
;       f32x4 rsv[2][4];
; #pragma unroll
;       for (int ai = 0; ai < 2; ++ai)
; #pragma unroll
;         for (int m = 0; m < 4; ++m)
;           rsv[ai][m] = *reinterpret_cast<const f32x4*>(rsl + ai * HALF + ewr * 64 + m * 16 + efq * 4);
; #pragma unroll
;       for (int ai = 0; ai < 2; ++ai)
; #pragma unroll
;         for (int m = 0; m < 4; ++m) {
;           const f32x4 rs4 = rsv[ai][m];
; #pragma unroll
;           for (int n = 0; n < 2; ++n) {
;             acc[ai][0][m][n] *= rs4;
;             acc[ai][1][m][n] *= rs4;
;             const int s = ai * 32 + ewr * 16 + m * 4 + efq;
;             const int col = ewc * 32 + n * 16 + efr;
;             top[s * 144 + col] = acc[ai][0][m][n][0];
;             bot[s * 144 + col] = acc[ai][0][m][n][3];
;           }
;         }
;       __syncthreads();
.LBB0_299:
	s_mov_b32 s98, 0x3e8ba43f
	s_or_b64 exec, exec, s[8:9]
	v_mov_b32_e32 v38, v1
	s_movk_i32 s8, 0x60
	v_and_b32_e32 v177, 15, v38
	v_lshrrev_b32_e32 v30, 1, v38
	s_lshl_b32 s62, s34, 7
	v_and_or_b32 v162, v30, s8, v177
	v_or_b32_e32 v200, s62, v162
	v_ashrrev_i32_e32 v201, 31, v200
	v_lshlrev_b64 v[30:31], 2, v[200:201]
	v_lshl_add_u64 v[32:33], s[44:45], 0, v[30:31]
	v_add_co_u32_e32 v34, vcc, 0x5000, v32
	v_lshl_add_u64 v[30:31], s[46:47], 0, v[30:31]
	s_nop 0
	v_addc_co_u32_e32 v35, vcc, 0, v33, vcc
	v_add_co_u32_e32 v36, vcc, 0xb000, v32
	v_ashrrev_i32_e32 v175, 4, v38
	s_nop 0
	v_addc_co_u32_e32 v37, vcc, 0, v33, vcc
	global_load_dword v215, v[32:33], off
	global_load_dword v217, v[34:35], off offset:2048
	global_load_dword v216, v[36:37], off
	global_load_dword v208, v[36:37], off offset:64
	global_load_dword v210, v[34:35], off offset:2112
	global_load_dword v209, v[32:33], off offset:64
	global_load_dword v218, v[30:31], off
	global_load_dword v207, v[30:31], off offset:64
	v_bfe_u32 v178, v38, 8, 1
	v_and_b32_e32 v179, 3, v175
	v_lshlrev_b32_e32 v30, 8, v178
	v_lshlrev_b32_e32 v31, 4, v179
	v_add3_u32 v30, s76, v30, v31
	v_lshl_or_b32 v220, v178, 4, v179
	s_movk_i32 s8, 0x90
	ds_read_b128 v[62:65], v30
	ds_read_b128 v[54:57], v30 offset:64
	ds_read_b128 v[50:53], v30 offset:128
	ds_read_b128 v[46:49], v30 offset:192
	ds_read_b128 v[42:45], v30 offset:512
	ds_read_b128 v[38:41], v30 offset:576
	ds_read_b128 v[34:37], v30 offset:640
	ds_read_b128 v[30:33], v30 offset:704
	v_mad_u32_u24 v178, v220, s8, v162
	v_lshl_add_u32 v211, v178, 2, 0
	s_waitcnt lgkmcnt(0)
	v_pk_mul_f32 v[196:197], v[144:145], v[56:57]
	v_pk_mul_f32 v[198:199], v[142:143], v[54:55]
	v_pk_mul_f32 v[144:145], v[134:135], v[54:55]
	v_add_u32_e32 v134, 0x800, v211
	v_pk_mul_f32 v[190:191], v[128:129], v[52:53]
	v_pk_mul_f32 v[188:189], v[110:111], v[46:47]
	v_pk_mul_f32 v[128:129], v[102:103], v[46:47]
	v_add_u32_e32 v102, 0x1800, v211
	v_pk_mul_f32 v[142:143], v[136:137], v[56:57]
	ds_write2_b32 v134, v198, v144 offset0:64 offset1:80
	v_add_u32_e32 v134, 0x9800, v211
	v_pk_mul_f32 v[192:193], v[126:127], v[50:51]
	v_pk_mul_f32 v[136:137], v[118:119], v[50:51]
	v_add_u32_e32 v118, 0x1000, v211
	v_pk_mul_f32 v[186:187], v[112:113], v[48:49]
	v_pk_mul_f32 v[126:127], v[104:105], v[48:49]
	ds_write2_b32 v102, v188, v128 offset0:192 offset1:208
	v_add_u32_e32 v102, 0xa800, v211
	ds_write2_b32 v134, v197, v143 offset0:64 offset1:80
	v_pk_mul_f32 v[134:135], v[120:121], v[52:53]
	ds_write2_b32 v118, v192, v136 offset0:128 offset1:144
	v_add_u32_e32 v118, 0xa000, v211
	ds_write2_b32 v102, v187, v127 offset0:192 offset1:208
	v_pk_mul_f32 v[184:185], v[154:155], v[42:43]
	v_pk_mul_f32 v[120:121], v[150:151], v[42:43]
	v_add_u32_e32 v102, 0x4800, v211
	ds_write2_b32 v118, v191, v135 offset0:128 offset1:144
	v_pk_mul_f32 v[182:183], v[156:157], v[44:45]
	v_pk_mul_f32 v[118:119], v[152:153], v[44:45]
	ds_write2_b32 v102, v184, v120 offset1:16
	v_add_u32_e32 v102, 0xd800, v211
	v_pk_mul_f32 v[154:155], v[106:107], v[30:31]
	v_pk_mul_f32 v[98:99], v[98:99], v[30:31]
	v_add_u32_e32 v106, 0x6000, v211
	ds_write2_b32 v102, v183, v119 offset1:16
	v_pk_mul_f32 v[180:181], v[138:139], v[38:39]
	v_pk_mul_f32 v[112:113], v[130:131], v[38:39]
	v_add_u32_e32 v102, 0x5000, v211
	v_pk_mul_f32 v[152:153], v[108:109], v[32:33]
	v_pk_mul_f32 v[100:101], v[100:101], v[32:33]
	ds_write2_b32 v106, v154, v98 offset0:192 offset1:208
	v_add_u32_e32 v106, 0xf000, v211
	s_movk_i32 s8, 0x240
	v_pk_mul_f32 v[202:203], v[160:161], v[64:65]
	v_pk_mul_f32 v[194:195], v[158:159], v[62:63]
	v_pk_mul_f32 v[146:147], v[146:147], v[62:63]
	v_pk_mul_f32 v[178:179], v[140:141], v[40:41]
	v_pk_mul_f32 v[110:111], v[132:133], v[40:41]
	ds_write2_b32 v102, v180, v112 offset0:64 offset1:80
	v_add_u32_e32 v102, 0xe000, v211
	v_pk_mul_f32 v[160:161], v[122:123], v[34:35]
	v_pk_mul_f32 v[104:105], v[114:115], v[34:35]
	v_add_u32_e32 v114, 0x5800, v211
	ds_write2_b32 v106, v153, v101 offset0:192 offset1:208
	v_mad_u32_u24 v106, v220, s8, 0
	v_pk_mul_f32 v[158:159], v[148:149], v[64:65]
	ds_write2_b32 v211, v194, v146 offset1:16
	v_add_u32_e32 v148, 0x9000, v211
	ds_write2_b32 v102, v179, v111 offset0:64 offset1:80
	v_pk_mul_f32 v[156:157], v[124:125], v[36:37]
	v_pk_mul_f32 v[102:103], v[116:117], v[36:37]
	ds_write2_b32 v114, v160, v104 offset0:128 offset1:144
	v_add_u32_e32 v114, 0xe800, v211
	v_cmp_eq_u32_e64 s[10:11], 0, v220
	v_cmp_ne_u32_e32 vcc, 0, v220
	v_mov_b32_e32 v213, 0
	v_lshl_add_u32 v211, v162, 2, v106
	v_mov_b32_e32 v224, 0
	ds_write2_b32 v148, v203, v159 offset1:16
	ds_write2_b32 v114, v157, v103 offset0:128 offset1:144
	s_waitcnt vmcnt(0) lgkmcnt(0)
	s_barrier
; __device__ __forceinline__ u16 f2bf(float f) { return (u16)(pack2(f, f) & 0xffffu); }
; __device__ __forceinline__ float gelu_exact(float x) { return 0.5f * x * (1.0f + erf_f32(x * 0.70710678118654752f)); }
; template <int EPI>
; __device__ __forceinline__ void phase_gemm(const Params& p, const GemmDesc& d, char* shmc) {
;     ...
;       float gp[2][4][2], gn[2][4][2];
; #pragma unroll
;       for (int ai = 0; ai < 2; ++ai)
; #pragma unroll
;         for (int m = 0; m < 4; ++m)
; #pragma unroll
;           for (int n = 0; n < 2; ++n) {
;             const int s = ai * 32 + ewr * 16 + m * 4 + efq;
;             const int col = ewc * 32 + n * 16 + efr;
;             gp[ai][m][n] = (s > 0) ? bot[(s - 1) * 144 + col] : 0.f;
;             gn[ai][m][n] = (s < 63) ? top[(s + 1) * 144 + col] : 0.f;
;           }
;       float* edge = p.edge + (size_t)pm * 6 * DFF;
; #pragma unroll
;       for (int n = 0; n < 2; ++n) {
;         const int col = ewc * 32 + n * 16 + efr;
;         const int ch = ch0 + col;
;         const float w0 = cw[n][0], w1 = cw[n][1], w2 = cw[n][2], cb = cw[n][3];
; #pragma unroll
;         for (int ai = 0; ai < 2; ++ai)
; #pragma unroll
;           for (int m = 0; m < 4; ++m) {
;             const int s = ai * 32 + ewr * 16 + m * 4 + efq;
;             const f32x4 g = acc[ai][0][m][n];
;             const f32x4 v = acc[ai][1][m][n];
;             const float c0 = w0 * gp[ai][m][n] + w1 * g[0] + w2 * g[1] + cb;
;             const float c1 = w0 * g[0] + w1 * g[1] + w2 * g[2] + cb;
;             const float c2 = w0 * g[1] + w1 * g[2] + w2 * g[3] + cb;
;             const float c3 = w0 * g[2] + w1 * g[3] + w2 * gn[ai][m][n] + cb;
;             u16* sp = stg + (s * 4) * 136 + col;
;             sp[0] = f2bf(gelu_exact(c0) * v[0]);
;             sp[136] = f2bf(gelu_exact(c1) * v[1]);
;             sp[272] = f2bf(gelu_exact(c2) * v[2]);
;             sp[408] = f2bf(gelu_exact(c3) * v[3]);
;             if (s == 0) {
;               edge[0 * DFF + ch] = c0; edge[1 * DFF + ch] = g[0]; edge[2 * DFF + ch] = v[0];
;             }
	s_and_saveexec_b64 s[8:9], vcc
	ds_read_b32 v224, v211 offset:36288
	s_or_b64 exec, exec, s[8:9]
	ds_read_b32 v223, v211 offset:576
	s_and_saveexec_b64 s[8:9], vcc
	ds_read_b32 v213, v211 offset:36352
	s_or_b64 exec, exec, s[8:9]
	v_add_u32_e32 v106, 0x9400, v211
	ds_read2_b32 v[150:151], v106 offset0:176 offset1:192
	v_add_u32_e32 v106, 0x800, v211
	ds_read2_b32 v[148:149], v106 offset0:208 offset1:224
	v_add_u32_e32 v106, 0x9e00, v211
	ds_read2_b32 v[140:141], v106 offset0:112 offset1:128
	v_add_u32_e32 v106, 0x1400, v211
	ds_read2_b32 v[138:139], v106 offset0:16 offset1:32
	v_add_u32_e32 v106, 0xa800, v211
	ds_read2_b32 v[132:133], v106 offset0:48 offset1:64
	v_add_u32_e32 v106, 0x1c00, v211
	ds_read2_b32 v[130:131], v106 offset0:80 offset1:96
	v_add_u32_e32 v106, 0xd400, v211
	ds_read2_b32 v[124:125], v106 offset0:112 offset1:128
	v_add_u32_e32 v106, 0x4800, v211
	ds_read2_b32 v[122:123], v106 offset0:144 offset1:160
	v_add_u32_e32 v106, 0xdc00, v211
	ds_read2_b32 v[116:117], v106 offset0:176 offset1:192
	v_add_u32_e32 v106, 0x5000, v211
	ds_read2_b32 v[114:115], v106 offset0:208 offset1:224
	v_add_u32_e32 v106, 0xe600, v211
	ds_read2_b32 v[108:109], v106 offset0:112 offset1:128
	v_add_u32_e32 v106, 0x5c00, v211
	ds_read2_b32 v[106:107], v106 offset0:16 offset1:32
	ds_read_b32 v214, v211 offset:640
	ds_read_b32 v221, v211 offset:61632
	v_cmp_eq_u32_e64 s[8:9], 19, v220
	v_cmp_ne_u32_e32 vcc, 19, v220
	v_add_u32_e32 v222, 0x6300, v211
	v_mov_b32_e32 v211, 0
	v_mov_b32_e32 v219, 0
	s_and_saveexec_b64 s[64:65], vcc
	ds_read_b32 v219, v222 offset:576
	s_or_b64 exec, exec, s[64:65]
	ds_read_b32 v212, v222 offset:36352
	s_and_saveexec_b64 s[64:65], vcc
	ds_read_b32 v211, v222 offset:640
	s_or_b64 exec, exec, s[64:65]
	s_mul_hi_i32 s34, s14, 0x21000
	s_mul_i32 s14, s14, 0x21000
	v_readlane_b32 s72, v246, 15
	v_readlane_b32 s73, v246, 16
	s_add_u32 s64, s72, s14
	s_addc_u32 s65, s73, s34
	v_pk_mul_f32 v[226:227], v[96:97], v[64:65]
	v_pk_mul_f32 v[96:97], v[94:95], v[62:63]
	v_lshl_add_u64 v[94:95], v[200:201], 2, s[64:65]
	s_waitcnt lgkmcnt(14)
	v_fma_f32 v200, v215, v224, v218
	v_fmac_f32_e32 v200, v217, v194
	v_mul_f32_e32 v224, v217, v202
	v_fmac_f32_e32 v200, v216, v195
	v_fma_f32 v201, v217, v195, v218
	v_fmac_f32_e32 v224, v215, v195
	v_fmac_f32_e32 v201, v215, v194
	v_fmac_f32_e32 v224, v216, v203
	v_fma_f32 v203, v217, v203, v218
	v_fmac_f32_e32 v201, v216, v202
	v_fmac_f32_e32 v203, v215, v202
	v_mul_f32_e32 v202, 0x3f596d27, v200
	v_fmac_f32_e32 v203, v216, v223
	v_fma_f32 v223, |v202|, s98, 1.0
	v_add_f32_e32 v195, v218, v224
	s_add_i32 s14, 0, 0x12000
	v_lshl_add_u32 v222, v162, 1, s14
	v_rcp_f32_e32 v223, v223
	v_mul_f32_e64 v225, |v202|, -|v202|
	v_fmamk_f32 v224, v223, 0x3f87dc22, v206
	v_fmaak_f32 v224, v224, v223, 0x3fb5f0e3
	v_exp_f32_e32 v225, v225
	v_fmaak_f32 v224, v224, v223, 0xbe91a98e
	v_fmaak_f32 v224, v224, v223, 0x3e827906
	v_mul_f32_e32 v223, v223, v224
	v_fma_f32 v202, -v225, v223, 1.0
	v_mul_f32_e32 v223, 0x3f596d27, v201
	s_movk_i32 s34, 0x440
	v_fma_f32 v224, |v223|, s98, 1.0
	v_mad_u32_u24 v228, v220, s34, v222
	v_mul_f32_e32 v229, 0.5, v200
	v_fma_f32 v202, |v229|, v202, v229
	v_mul_f32_e32 v202, v96, v202
	v_cvt_pk_bf16_f32 v202, v202, s0
	ds_write_b16 v228, v202
	v_rcp_f32_e32 v202, v224
	v_mul_f32_e64 v225, |v223|, -|v223|
	v_fmamk_f32 v224, v202, 0x3f87dc22, v206
	v_fmaak_f32 v224, v224, v202, 0x3fb5f0e3
	v_exp_f32_e32 v225, v225
	v_fmaak_f32 v224, v224, v202, 0xbe91a98e
	v_fmaak_f32 v224, v224, v202, 0x3e827906
	v_mul_f32_e32 v202, v202, v224
	v_fma_f32 v202, -v225, v202, 1.0
	v_mul_f32_e32 v201, 0.5, v201
	v_fma_f32 v201, |v201|, v202, v201
	v_mul_f32_e32 v97, v97, v201
	v_mul_f32_e32 v201, 0x3f596d27, v195
	v_fma_f32 v202, |v201|, s98, 1.0
	v_cvt_pk_bf16_f32 v97, v97, s0
	ds_write_b16 v228, v97 offset:272
	v_mul_f32_e32 v97, 0.5, v195
	v_rcp_f32_e32 v195, v202
	v_mul_f32_e64 v223, |v201|, -|v201|
	v_fmamk_f32 v202, v195, 0x3f87dc22, v206
	v_fmaak_f32 v202, v202, v195, 0x3fb5f0e3
	v_exp_f32_e32 v223, v223
	v_fmaak_f32 v202, v202, v195, 0xbe91a98e
	v_fmaak_f32 v202, v202, v195, 0x3e827906
	v_mul_f32_e32 v195, v195, v202
	v_fma_f32 v195, -v223, v195, 1.0
	v_fma_f32 v97, |v97|, v195, v97
	v_mul_f32_e32 v195, 0x3f596d27, v203
	v_fma_f32 v201, |v195|, s98, 1.0
	v_mul_f32_e32 v97, v226, v97
	v_cvt_pk_bf16_f32 v97, v97, s0
	ds_write_b16 v228, v97 offset:544
	v_mul_f32_e32 v97, 0.5, v203
	v_rcp_f32_e32 v201, v201
	v_mul_f32_e64 v203, |v195|, -|v195|
	v_fmamk_f32 v202, v201, 0x3f87dc22, v206
	v_fmaak_f32 v202, v202, v201, 0x3fb5f0e3
	v_exp_f32_e32 v203, v203
	v_fmaak_f32 v202, v202, v201, 0xbe91a98e
	v_fmaak_f32 v202, v202, v201, 0x3e827906
	v_mul_f32_e32 v201, v201, v202
	v_fma_f32 v195, -v203, v201, 1.0
	v_fma_f32 v97, |v97|, v195, v97
	v_mul_f32_e32 v97, v227, v97
	v_cvt_pk_bf16_f32 v97, v97, s0
	v_readlane_b32 s74, v246, 17
	v_readlane_b32 s75, v246, 18
	ds_write_b16 v228, v97 offset:816
	s_and_saveexec_b64 s[78:79], s[10:11]
	s_cbranch_execz .LBB0_309
	global_store_dword v[94:95], v200, off
	v_add_co_u32_e32 v200, vcc, 0x5000, v94
	s_nop 1
	v_addc_co_u32_e32 v201, vcc, 0, v95, vcc
	global_store_dword v[200:201], v194, off offset:2048
	v_add_co_u32_e32 v194, vcc, 0xb000, v94
	s_nop 1
	v_addc_co_u32_e32 v195, vcc, 0, v95, vcc
	global_store_dword v[194:195], v96, off
; __device__ __forceinline__ u16 f2bf(float f) { return (u16)(pack2(f, f) & 0xffffu); }
; __device__ __forceinline__ float gelu_exact(float x) { return 0.5f * x * (1.0f + erf_f32(x * 0.70710678118654752f)); }
; template <int EPI>
; __device__ __forceinline__ void phase_gemm(const Params& p, const GemmDesc& d, char* shmc) {
;     ...
;         for (int ai = 0; ai < 2; ++ai)
; #pragma unroll
;           for (int m = 0; m < 4; ++m) {
;             const int s = ai * 32 + ewr * 16 + m * 4 + efq;
;             const f32x4 g = acc[ai][0][m][n];
;             const f32x4 v = acc[ai][1][m][n];
;             const float c0 = w0 * gp[ai][m][n] + w1 * g[0] + w2 * g[1] + cb;
;             const float c1 = w0 * g[0] + w1 * g[1] + w2 * g[2] + cb;
;             const float c2 = w0 * g[1] + w1 * g[2] + w2 * g[3] + cb;
;             const float c3 = w0 * g[2] + w1 * g[3] + w2 * gn[ai][m][n] + cb;
;             u16* sp = stg + (s * 4) * 136 + col;
;             sp[0] = f2bf(gelu_exact(c0) * v[0]);
;             sp[136] = f2bf(gelu_exact(c1) * v[1]);
;             sp[272] = f2bf(gelu_exact(c2) * v[2]);
;             sp[408] = f2bf(gelu_exact(c3) * v[3]);
.LBB0_309:
	s_or_b64 exec, exec, s[78:79]
	v_pk_mul_f32 v[96:97], v[68:69], v[48:49]
	v_pk_mul_f32 v[68:69], v[78:79], v[30:31]
	v_fma_f32 v79, v215, v150, v218
	v_fmac_f32_e32 v79, v217, v198
	v_fmac_f32_e32 v79, v216, v199
	v_pk_mul_f32 v[200:201], v[72:73], v[52:53]
	v_pk_mul_f32 v[72:73], v[82:83], v[34:35]
	v_mul_f32_e32 v83, 0x3f596d27, v79
	v_pk_mul_f32 v[202:203], v[70:71], v[50:51]
	v_pk_mul_f32 v[70:71], v[84:85], v[36:37]
	v_fma_f32 v84, |v83|, s98, 1.0
	v_mul_f32_e32 v78, v217, v199
	v_pk_mul_f32 v[224:225], v[76:77], v[56:57]
	v_pk_mul_f32 v[76:77], v[86:87], v[38:39]
	v_fmac_f32_e32 v78, v215, v198
	v_fmac_f32_e32 v78, v216, v196
	v_pk_mul_f32 v[194:195], v[66:67], v[46:47]
	v_pk_mul_f32 v[66:67], v[80:81], v[32:33]
	v_add_f32_e32 v80, v218, v78
	v_fma_f32 v81, v217, v196, v218
	v_fmac_f32_e32 v81, v215, v199
	v_pk_mul_f32 v[226:227], v[74:75], v[54:55]
	v_pk_mul_f32 v[74:75], v[88:89], v[40:41]
	v_fmac_f32_e32 v81, v216, v197
	v_fma_f32 v82, v217, v197, v218
	v_fmac_f32_e32 v82, v215, v196
	s_waitcnt lgkmcnt(14)
	v_fmac_f32_e32 v82, v216, v148
	v_rcp_f32_e32 v84, v84
	v_mul_f32_e64 v86, |v83|, -|v83|
	v_fmamk_f32 v85, v84, 0x3f87dc22, v206
	v_fmaak_f32 v85, v85, v84, 0x3fb5f0e3
	v_exp_f32_e32 v86, v86
	v_fmaak_f32 v85, v85, v84, 0xbe91a98e
	v_fmaak_f32 v85, v85, v84, 0x3e827906
	v_mul_f32_e32 v84, v84, v85
	v_fma_f32 v83, -v86, v84, 1.0
	v_mul_f32_e32 v79, 0.5, v79
	v_fma_f32 v79, |v79|, v83, v79
	v_mul_f32_e32 v83, 0x3f596d27, v80
	v_fma_f32 v84, |v83|, s98, 1.0
	v_mul_u32_u24_e32 v220, 0x440, v220
	v_add_u32_e32 v78, 0x1100, v220
	v_mul_f32_e32 v79, v226, v79
	v_add_u32_e32 v87, v222, v78
	v_cvt_pk_bf16_f32 v79, v79, s0
	ds_write_b16 v87, v79
	v_mul_f32_e32 v79, 0.5, v80
	v_rcp_f32_e32 v80, v84
	v_mul_f32_e64 v85, |v83|, -|v83|
	v_fmamk_f32 v84, v80, 0x3f87dc22, v206
	v_fmaak_f32 v84, v84, v80, 0x3fb5f0e3
	v_exp_f32_e32 v85, v85
	v_fmaak_f32 v84, v84, v80, 0xbe91a98e
	v_fmaak_f32 v84, v84, v80, 0x3e827906
	v_mul_f32_e32 v80, v80, v84
	v_fma_f32 v80, -v85, v80, 1.0
	v_fma_f32 v79, |v79|, v80, v79
	v_mul_f32_e32 v80, 0x3f596d27, v81
	v_fma_f32 v83, |v80|, s98, 1.0
	v_mul_f32_e32 v79, v227, v79
	v_cvt_pk_bf16_f32 v79, v79, s0
	ds_write_b16 v87, v79 offset:272
	v_mul_f32_e32 v79, 0.5, v81
	v_rcp_f32_e32 v81, v83
	v_mul_f32_e64 v84, |v80|, -|v80|
	v_fmamk_f32 v83, v81, 0x3f87dc22, v206
	v_fmaak_f32 v83, v83, v81, 0x3fb5f0e3
	v_exp_f32_e32 v84, v84
	v_fmaak_f32 v83, v83, v81, 0xbe91a98e
	v_fmaak_f32 v83, v83, v81, 0x3e827906
	v_mul_f32_e32 v81, v81, v83
	v_fma_f32 v80, -v84, v81, 1.0
	v_fma_f32 v79, |v79|, v80, v79
	v_mul_f32_e32 v80, 0x3f596d27, v82
	v_fma_f32 v81, |v80|, s98, 1.0
	v_mul_f32_e32 v79, v224, v79
	v_cvt_pk_bf16_f32 v79, v79, s0
	ds_write_b16 v87, v79 offset:544
	v_mul_f32_e32 v79, 0.5, v82
	v_rcp_f32_e32 v81, v81
	v_mul_f32_e64 v83, |v80|, -|v80|
	v_fmamk_f32 v82, v81, 0x3f87dc22, v206
	v_fmaak_f32 v82, v82, v81, 0x3fb5f0e3
	v_exp_f32_e32 v83, v83
	v_fmaak_f32 v82, v82, v81, 0xbe91a98e
	v_fmaak_f32 v82, v82, v81, 0x3e827906
	v_mul_f32_e32 v81, v81, v82
	v_fma_f32 v80, -v83, v81, 1.0
	v_fma_f32 v79, |v79|, v80, v79
	v_mul_f32_e32 v79, v225, v79
	v_cvt_pk_bf16_f32 v79, v79, s0
	ds_write_b16 v87, v79 offset:816
	v_fma_f32 v80, v215, v140, v218
	v_fmac_f32_e32 v80, v217, v192
	v_fmac_f32_e32 v80, v216, v193
	v_mul_f32_e32 v84, 0x3f596d27, v80
	v_fma_f32 v81, v217, v193, v218
	v_fma_f32 v85, |v84|, s98, 1.0
	v_fmac_f32_e32 v81, v215, v192
	v_fmac_f32_e32 v81, v216, v190
	v_fma_f32 v82, v217, v190, v218
	v_fmac_f32_e32 v82, v215, v193
	v_fmac_f32_e32 v82, v216, v191
	v_fma_f32 v83, v217, v191, v218
	v_fmac_f32_e32 v83, v215, v190
	v_fmac_f32_e32 v83, v216, v138
	v_rcp_f32_e32 v85, v85
	v_mul_f32_e64 v87, |v84|, -|v84|
	v_fmamk_f32 v86, v85, 0x3f87dc22, v206
	v_fmaak_f32 v86, v86, v85, 0x3fb5f0e3
	v_exp_f32_e32 v87, v87
	v_fmaak_f32 v86, v86, v85, 0xbe91a98e
	v_fmaak_f32 v86, v86, v85, 0x3e827906
	v_mul_f32_e32 v85, v85, v86
	v_fma_f32 v84, -v87, v85, 1.0
	v_mul_f32_e32 v80, 0.5, v80
	v_fma_f32 v80, |v80|, v84, v80
	v_mul_f32_e32 v84, 0x3f596d27, v81
	v_fma_f32 v85, |v84|, s98, 1.0
	v_add_u32_e32 v79, 0x2200, v220
	v_mul_f32_e32 v80, v202, v80
	v_add_u32_e32 v88, v222, v79
	v_cvt_pk_bf16_f32 v80, v80, s0
	ds_write_b16 v88, v80
	v_mul_f32_e32 v80, 0.5, v81
	v_rcp_f32_e32 v81, v85
	v_mul_f32_e64 v86, |v84|, -|v84|
	v_fmamk_f32 v85, v81, 0x3f87dc22, v206
	v_fmaak_f32 v85, v85, v81, 0x3fb5f0e3
	v_exp_f32_e32 v86, v86
	v_fmaak_f32 v85, v85, v81, 0xbe91a98e
	v_fmaak_f32 v85, v85, v81, 0x3e827906
	v_mul_f32_e32 v81, v81, v85
	v_fma_f32 v81, -v86, v81, 1.0
	v_fma_f32 v80, |v80|, v81, v80
	v_mul_f32_e32 v81, 0x3f596d27, v82
	v_fma_f32 v84, |v81|, s98, 1.0
	v_mul_f32_e32 v80, v203, v80
	v_cvt_pk_bf16_f32 v80, v80, s0
	ds_write_b16 v88, v80 offset:272
	v_mul_f32_e32 v80, 0.5, v82
	v_rcp_f32_e32 v82, v84
	v_mul_f32_e64 v85, |v81|, -|v81|
	v_fmamk_f32 v84, v82, 0x3f87dc22, v206
	v_fmaak_f32 v84, v84, v82, 0x3fb5f0e3
	v_exp_f32_e32 v85, v85
	v_fmaak_f32 v84, v84, v82, 0xbe91a98e
	v_fmaak_f32 v84, v84, v82, 0x3e827906
	v_mul_f32_e32 v82, v82, v84
	v_fma_f32 v81, -v85, v82, 1.0
	v_fma_f32 v80, |v80|, v81, v80
	v_mul_f32_e32 v81, 0x3f596d27, v83
	v_fma_f32 v82, |v81|, s98, 1.0
	v_mul_f32_e32 v80, v200, v80
	v_cvt_pk_bf16_f32 v80, v80, s0
	ds_write_b16 v88, v80 offset:544
	v_mul_f32_e32 v80, 0.5, v83
	v_rcp_f32_e32 v82, v82
	v_mul_f32_e64 v84, |v81|, -|v81|
	v_fmamk_f32 v83, v82, 0x3f87dc22, v206
	v_fmaak_f32 v83, v83, v82, 0x3fb5f0e3
	v_exp_f32_e32 v84, v84
	v_fmaak_f32 v83, v83, v82, 0xbe91a98e
	v_fmaak_f32 v83, v83, v82, 0x3e827906
	v_mul_f32_e32 v82, v82, v83
	v_fma_f32 v81, -v84, v82, 1.0
	v_fma_f32 v80, |v80|, v81, v80
	v_mul_f32_e32 v80, v201, v80
	v_cvt_pk_bf16_f32 v80, v80, s0
	ds_write_b16 v88, v80 offset:816
	v_fma_f32 v81, v215, v132, v218
	v_fmac_f32_e32 v81, v217, v188
	v_fmac_f32_e32 v81, v216, v189
	v_fma_f32 v82, v217, v189, v218
	v_fmac_f32_e32 v82, v215, v188
	v_mul_f32_e32 v85, 0x3f596d27, v81
	v_fmac_f32_e32 v82, v216, v186
	v_fma_f32 v86, |v85|, s98, 1.0
	v_fma_f32 v83, v217, v186, v218
	v_fmac_f32_e32 v83, v215, v189
	v_fmac_f32_e32 v83, v216, v187
	v_fma_f32 v84, v217, v187, v218
	v_fmac_f32_e32 v84, v215, v186
	s_waitcnt lgkmcnt(14)
; __device__ __forceinline__ u16 f2bf(float f) { return (u16)(pack2(f, f) & 0xffffu); }
; __device__ __forceinline__ float gelu_exact(float x) { return 0.5f * x * (1.0f + erf_f32(x * 0.70710678118654752f)); }
; template <int EPI>
; __device__ __forceinline__ void phase_gemm(const Params& p, const GemmDesc& d, char* shmc) {
;     ...
;         for (int ai = 0; ai < 2; ++ai)
; #pragma unroll
;           for (int m = 0; m < 4; ++m) {
;             const int s = ai * 32 + ewr * 16 + m * 4 + efq;
;             const f32x4 g = acc[ai][0][m][n];
;             const f32x4 v = acc[ai][1][m][n];
;             const float c0 = w0 * gp[ai][m][n] + w1 * g[0] + w2 * g[1] + cb;
;             const float c1 = w0 * g[0] + w1 * g[1] + w2 * g[2] + cb;
;             const float c2 = w0 * g[1] + w1 * g[2] + w2 * g[3] + cb;
;             const float c3 = w0 * g[2] + w1 * g[3] + w2 * gn[ai][m][n] + cb;
;             u16* sp = stg + (s * 4) * 136 + col;
;             sp[0] = f2bf(gelu_exact(c0) * v[0]);
;             sp[136] = f2bf(gelu_exact(c1) * v[1]);
;             sp[272] = f2bf(gelu_exact(c2) * v[2]);
;             sp[408] = f2bf(gelu_exact(c3) * v[3]);
	v_fmac_f32_e32 v84, v216, v130
	v_rcp_f32_e32 v86, v86
	v_mul_f32_e64 v88, |v85|, -|v85|
	v_fmamk_f32 v87, v86, 0x3f87dc22, v206
	v_fmaak_f32 v87, v87, v86, 0x3fb5f0e3
	v_exp_f32_e32 v88, v88
	v_fmaak_f32 v87, v87, v86, 0xbe91a98e
	v_fmaak_f32 v87, v87, v86, 0x3e827906
	v_mul_f32_e32 v86, v86, v87
	v_fma_f32 v85, -v88, v86, 1.0
	v_mul_f32_e32 v81, 0.5, v81
	v_fma_f32 v81, |v81|, v85, v81
	v_mul_f32_e32 v85, 0x3f596d27, v82
	v_fma_f32 v86, |v85|, s98, 1.0
	v_add_u32_e32 v80, 0x3300, v220
	v_mul_f32_e32 v81, v194, v81
	v_add_u32_e32 v89, v222, v80
	v_cvt_pk_bf16_f32 v81, v81, s0
	ds_write_b16 v89, v81
	v_mul_f32_e32 v81, 0.5, v82
	v_rcp_f32_e32 v82, v86
	v_mul_f32_e64 v87, |v85|, -|v85|
	v_fmamk_f32 v86, v82, 0x3f87dc22, v206
	v_fmaak_f32 v86, v86, v82, 0x3fb5f0e3
	v_exp_f32_e32 v87, v87
	v_fmaak_f32 v86, v86, v82, 0xbe91a98e
	v_fmaak_f32 v86, v86, v82, 0x3e827906
	v_mul_f32_e32 v82, v82, v86
	v_fma_f32 v82, -v87, v82, 1.0
	v_fma_f32 v81, |v81|, v82, v81
	v_mul_f32_e32 v82, 0x3f596d27, v83
	v_fma_f32 v85, |v82|, s98, 1.0
	v_mul_f32_e32 v81, v195, v81
	v_cvt_pk_bf16_f32 v81, v81, s0
	ds_write_b16 v89, v81 offset:272
	v_mul_f32_e32 v81, 0.5, v83
	v_rcp_f32_e32 v83, v85
	v_mul_f32_e64 v86, |v82|, -|v82|
	v_fmamk_f32 v85, v83, 0x3f87dc22, v206
	v_fmaak_f32 v85, v85, v83, 0x3fb5f0e3
	v_exp_f32_e32 v86, v86
	v_fmaak_f32 v85, v85, v83, 0xbe91a98e
	v_fmaak_f32 v85, v85, v83, 0x3e827906
	v_mul_f32_e32 v83, v83, v85
	v_fma_f32 v82, -v86, v83, 1.0
	v_fma_f32 v81, |v81|, v82, v81
	v_mul_f32_e32 v82, 0x3f596d27, v84
	v_fma_f32 v83, |v82|, s98, 1.0
	v_mul_f32_e32 v81, v96, v81
	v_cvt_pk_bf16_f32 v81, v81, s0
	ds_write_b16 v89, v81 offset:544
	v_mul_f32_e32 v81, 0.5, v84
	v_rcp_f32_e32 v83, v83
	v_mul_f32_e64 v85, |v82|, -|v82|
	v_fmamk_f32 v84, v83, 0x3f87dc22, v206
	v_fmaak_f32 v84, v84, v83, 0x3fb5f0e3
	v_exp_f32_e32 v85, v85
	v_fmaak_f32 v84, v84, v83, 0xbe91a98e
	v_fmaak_f32 v84, v84, v83, 0x3e827906
	v_mul_f32_e32 v83, v83, v84
	v_fma_f32 v82, -v85, v83, 1.0
	v_fma_f32 v81, |v81|, v82, v81
	v_mul_f32_e32 v81, v97, v81
	v_cvt_pk_bf16_f32 v81, v81, s0
	ds_write_b16 v89, v81 offset:816
	v_fma_f32 v82, v215, v124, v218
	v_fmac_f32_e32 v82, v217, v184
	v_fmac_f32_e32 v82, v216, v185
	v_mul_f32_e32 v86, 0x3f596d27, v82
	v_fma_f32 v83, v217, v185, v218
	v_fma_f32 v87, |v86|, s98, 1.0
	v_fmac_f32_e32 v83, v215, v184
	v_fmac_f32_e32 v83, v216, v182
	v_fma_f32 v84, v217, v182, v218
	v_fmac_f32_e32 v84, v215, v185
	v_fmac_f32_e32 v84, v216, v183
	v_fma_f32 v85, v217, v183, v218
	v_fmac_f32_e32 v85, v215, v182
	v_fmac_f32_e32 v85, v216, v122
	v_rcp_f32_e32 v87, v87
	v_mul_f32_e64 v89, |v86|, -|v86|
	v_fmamk_f32 v88, v87, 0x3f87dc22, v206
	v_fmaak_f32 v88, v88, v87, 0x3fb5f0e3
	v_exp_f32_e32 v89, v89
	v_fmaak_f32 v88, v88, v87, 0xbe91a98e
	v_fmaak_f32 v88, v88, v87, 0x3e827906
	v_mul_f32_e32 v87, v87, v88
	v_fma_f32 v86, -v89, v87, 1.0
	v_mul_f32_e32 v82, 0.5, v82
	v_fma_f32 v82, |v82|, v86, v82
	v_mul_f32_e32 v86, 0x3f596d27, v83
	v_fma_f32 v87, |v86|, s98, 1.0
	v_pk_mul_f32 v[90:91], v[90:91], v[42:43]
	v_add_u32_e32 v81, 0x8800, v220
	v_mul_f32_e32 v82, v90, v82
	v_add_u32_e32 v96, v222, v81
	v_cvt_pk_bf16_f32 v82, v82, s0
	ds_write_b16 v96, v82
	v_mul_f32_e32 v82, 0.5, v83
	v_rcp_f32_e32 v83, v87
	v_mul_f32_e64 v88, |v86|, -|v86|
	v_fmamk_f32 v87, v83, 0x3f87dc22, v206
	v_fmaak_f32 v87, v87, v83, 0x3fb5f0e3
	v_exp_f32_e32 v88, v88
	v_fmaak_f32 v87, v87, v83, 0xbe91a98e
	v_fmaak_f32 v87, v87, v83, 0x3e827906
	v_mul_f32_e32 v83, v83, v87
	v_fma_f32 v83, -v88, v83, 1.0
	v_fma_f32 v82, |v82|, v83, v82
	v_mul_f32_e32 v83, 0x3f596d27, v84
	v_fma_f32 v86, |v83|, s98, 1.0
	v_mul_f32_e32 v82, v91, v82
	v_cvt_pk_bf16_f32 v82, v82, s0
	ds_write_b16 v96, v82 offset:272
	v_mul_f32_e32 v82, 0.5, v84
	v_rcp_f32_e32 v84, v86
	v_mul_f32_e64 v87, |v83|, -|v83|
	v_fmamk_f32 v86, v84, 0x3f87dc22, v206
	v_fmaak_f32 v86, v86, v84, 0x3fb5f0e3
	v_exp_f32_e32 v87, v87
	v_fmaak_f32 v86, v86, v84, 0xbe91a98e
	v_fmaak_f32 v86, v86, v84, 0x3e827906
	v_mul_f32_e32 v84, v84, v86
	v_fma_f32 v83, -v87, v84, 1.0
	v_fma_f32 v82, |v82|, v83, v82
	v_mul_f32_e32 v83, 0x3f596d27, v85
	v_fma_f32 v84, |v83|, s98, 1.0
	v_pk_mul_f32 v[92:93], v[92:93], v[44:45]
	s_nop 0
	v_mul_f32_e32 v82, v92, v82
	v_cvt_pk_bf16_f32 v82, v82, s0
	ds_write_b16 v96, v82 offset:544
	v_mul_f32_e32 v82, 0.5, v85
	v_rcp_f32_e32 v84, v84
	v_mul_f32_e64 v86, |v83|, -|v83|
	v_fmamk_f32 v85, v84, 0x3f87dc22, v206
	v_fmaak_f32 v85, v85, v84, 0x3fb5f0e3
	v_exp_f32_e32 v86, v86
	v_fmaak_f32 v85, v85, v84, 0xbe91a98e
	v_fmaak_f32 v85, v85, v84, 0x3e827906
	v_mul_f32_e32 v84, v84, v85
	v_fma_f32 v83, -v86, v84, 1.0
	v_fma_f32 v82, |v82|, v83, v82
	v_mul_f32_e32 v82, v93, v82
	v_cvt_pk_bf16_f32 v82, v82, s0
	ds_write_b16 v96, v82 offset:816
	v_fma_f32 v83, v215, v116, v218
	v_fmac_f32_e32 v83, v217, v180
	v_fmac_f32_e32 v83, v216, v181
	v_mul_f32_e32 v87, 0x3f596d27, v83
	v_fma_f32 v88, |v87|, s98, 1.0
	v_fma_f32 v84, v217, v181, v218
	v_fmac_f32_e32 v84, v215, v180
	v_fmac_f32_e32 v84, v216, v178
	v_rcp_f32_e32 v88, v88
	v_mul_f32_e64 v90, |v87|, -|v87|
	v_fmamk_f32 v89, v88, 0x3f87dc22, v206
	v_fmaak_f32 v89, v89, v88, 0x3fb5f0e3
	v_exp_f32_e32 v90, v90
	v_fmaak_f32 v89, v89, v88, 0xbe91a98e
	v_fmaak_f32 v89, v89, v88, 0x3e827906
	v_mul_f32_e32 v88, v88, v89
	v_fma_f32 v87, -v90, v88, 1.0
	v_mul_f32_e32 v83, 0.5, v83
	v_fma_f32 v85, v217, v178, v218
	v_fma_f32 v83, |v83|, v87, v83
	v_fmac_f32_e32 v85, v215, v181
	v_mul_f32_e32 v76, v76, v83
	v_mul_f32_e32 v83, 0x3f596d27, v84
	v_fmac_f32_e32 v85, v216, v179
	v_fma_f32 v87, |v83|, s98, 1.0
	v_fma_f32 v86, v217, v179, v218
	v_fmac_f32_e32 v86, v215, v178
	v_fmac_f32_e32 v86, v216, v114
; __device__ __forceinline__ u16 f2bf(float f) { return (u16)(pack2(f, f) & 0xffffu); }
; __device__ __forceinline__ float gelu_exact(float x) { return 0.5f * x * (1.0f + erf_f32(x * 0.70710678118654752f)); }
; template <int EPI>
; __device__ __forceinline__ void phase_gemm(const Params& p, const GemmDesc& d, char* shmc) {
;     ...
;         for (int ai = 0; ai < 2; ++ai)
; #pragma unroll
;           for (int m = 0; m < 4; ++m) {
;             const int s = ai * 32 + ewr * 16 + m * 4 + efq;
;             const f32x4 g = acc[ai][0][m][n];
;             const f32x4 v = acc[ai][1][m][n];
;             const float c0 = w0 * gp[ai][m][n] + w1 * g[0] + w2 * g[1] + cb;
;             const float c1 = w0 * g[0] + w1 * g[1] + w2 * g[2] + cb;
;             const float c2 = w0 * g[1] + w1 * g[2] + w2 * g[3] + cb;
;             const float c3 = w0 * g[2] + w1 * g[3] + w2 * gn[ai][m][n] + cb;
;             u16* sp = stg + (s * 4) * 136 + col;
;             sp[0] = f2bf(gelu_exact(c0) * v[0]);
;             sp[136] = f2bf(gelu_exact(c1) * v[1]);
;             sp[272] = f2bf(gelu_exact(c2) * v[2]);
;             sp[408] = f2bf(gelu_exact(c3) * v[3]);
;             if (s == 0) {
;               edge[0 * DFF + ch] = c0; edge[1 * DFF + ch] = g[0]; edge[2 * DFF + ch] = v[0];
;             }
;             if (s == 63) {
	v_add_u32_e32 v82, 0x9900, v220
	v_add_u32_e32 v91, v222, v82
	v_cvt_pk_bf16_f32 v76, v76, s0
	ds_write_b16 v91, v76
	v_mul_f32_e32 v76, 0.5, v84
	v_rcp_f32_e32 v84, v87
	v_mul_f32_e64 v88, |v83|, -|v83|
	v_fmamk_f32 v87, v84, 0x3f87dc22, v206
	v_fmaak_f32 v87, v87, v84, 0x3fb5f0e3
	v_exp_f32_e32 v88, v88
	v_fmaak_f32 v87, v87, v84, 0xbe91a98e
	v_fmaak_f32 v87, v87, v84, 0x3e827906
	v_mul_f32_e32 v84, v84, v87
	v_fma_f32 v83, -v88, v84, 1.0
	v_fma_f32 v76, |v76|, v83, v76
	v_mul_f32_e32 v76, v77, v76
	v_mul_f32_e32 v77, 0x3f596d27, v85
	v_fma_f32 v83, |v77|, s98, 1.0
	v_cvt_pk_bf16_f32 v76, v76, s0
	ds_write_b16 v91, v76 offset:272
	v_mul_f32_e32 v76, 0.5, v85
	v_rcp_f32_e32 v83, v83
	v_mul_f32_e64 v85, |v77|, -|v77|
	v_fmamk_f32 v84, v83, 0x3f87dc22, v206
	v_fmaak_f32 v84, v84, v83, 0x3fb5f0e3
	v_exp_f32_e32 v85, v85
	v_fmaak_f32 v84, v84, v83, 0xbe91a98e
	v_fmaak_f32 v84, v84, v83, 0x3e827906
	v_mul_f32_e32 v83, v83, v84
	v_fma_f32 v77, -v85, v83, 1.0
	v_fma_f32 v76, |v76|, v77, v76
	v_mul_f32_e32 v74, v74, v76
	v_mul_f32_e32 v76, 0x3f596d27, v86
	v_fma_f32 v77, |v76|, s98, 1.0
	v_cvt_pk_bf16_f32 v74, v74, s0
	ds_write_b16 v91, v74 offset:544
	v_mul_f32_e32 v74, 0.5, v86
	v_rcp_f32_e32 v77, v77
	v_mul_f32_e64 v84, |v76|, -|v76|
	v_fmamk_f32 v83, v77, 0x3f87dc22, v206
	v_fmaak_f32 v83, v83, v77, 0x3fb5f0e3
	v_exp_f32_e32 v84, v84
	v_fmaak_f32 v83, v83, v77, 0xbe91a98e
	v_fmaak_f32 v83, v83, v77, 0x3e827906
	v_mul_f32_e32 v77, v77, v83
	v_fma_f32 v76, -v84, v77, 1.0
	v_fma_f32 v74, |v74|, v76, v74
	v_mul_f32_e32 v74, v75, v74
	v_cvt_pk_bf16_f32 v74, v74, s0
	ds_write_b16 v91, v74 offset:816
	v_fma_f32 v75, v215, v108, v218
	v_fmac_f32_e32 v75, v217, v160
	v_fmac_f32_e32 v75, v216, v161
	v_mul_f32_e32 v84, 0x3f596d27, v75
	v_fma_f32 v85, |v84|, s98, 1.0
	v_fma_f32 v76, v217, v161, v218
	v_fmac_f32_e32 v76, v215, v160
	v_fmac_f32_e32 v76, v216, v156
	v_rcp_f32_e32 v85, v85
	v_mul_f32_e64 v87, |v84|, -|v84|
	v_fmamk_f32 v86, v85, 0x3f87dc22, v206
	v_fmaak_f32 v86, v86, v85, 0x3fb5f0e3
	v_exp_f32_e32 v87, v87
	v_fmaak_f32 v86, v86, v85, 0xbe91a98e
	v_fmaak_f32 v86, v86, v85, 0x3e827906
	v_mul_f32_e32 v85, v85, v86
	v_fma_f32 v84, -v87, v85, 1.0
	v_mul_f32_e32 v75, 0.5, v75
	v_fma_f32 v77, v217, v156, v218
	v_fma_f32 v75, |v75|, v84, v75
	v_fmac_f32_e32 v77, v215, v161
	v_mul_f32_e32 v72, v72, v75
	v_mul_f32_e32 v75, 0x3f596d27, v76
	v_fmac_f32_e32 v77, v216, v157
	v_fma_f32 v84, |v75|, s98, 1.0
	v_fma_f32 v83, v217, v157, v218
	v_fmac_f32_e32 v83, v215, v156
	v_fmac_f32_e32 v83, v216, v106
	v_add_u32_e32 v74, 0xaa00, v220
	v_add_u32_e32 v88, v222, v74
	v_cvt_pk_bf16_f32 v72, v72, s0
	ds_write_b16 v88, v72
	v_mul_f32_e32 v72, 0.5, v76
	v_rcp_f32_e32 v76, v84
	v_mul_f32_e64 v85, |v75|, -|v75|
	v_fmamk_f32 v84, v76, 0x3f87dc22, v206
	v_fmaak_f32 v84, v84, v76, 0x3fb5f0e3
	v_exp_f32_e32 v85, v85
	v_fmaak_f32 v84, v84, v76, 0xbe91a98e
	v_fmaak_f32 v84, v84, v76, 0x3e827906
	v_mul_f32_e32 v76, v76, v84
	v_fma_f32 v75, -v85, v76, 1.0
	v_fma_f32 v72, |v72|, v75, v72
	v_mul_f32_e32 v72, v73, v72
	v_mul_f32_e32 v73, 0x3f596d27, v77
	v_fma_f32 v75, |v73|, s98, 1.0
	v_cvt_pk_bf16_f32 v72, v72, s0
	ds_write_b16 v88, v72 offset:272
	v_mul_f32_e32 v72, 0.5, v77
	v_rcp_f32_e32 v75, v75
	v_mul_f32_e64 v77, |v73|, -|v73|
	v_fmamk_f32 v76, v75, 0x3f87dc22, v206
	v_fmaak_f32 v76, v76, v75, 0x3fb5f0e3
	v_exp_f32_e32 v77, v77
	v_fmaak_f32 v76, v76, v75, 0xbe91a98e
	v_fmaak_f32 v76, v76, v75, 0x3e827906
	v_mul_f32_e32 v75, v75, v76
	v_fma_f32 v73, -v77, v75, 1.0
	v_fma_f32 v72, |v72|, v73, v72
	v_mul_f32_e32 v70, v70, v72
	v_mul_f32_e32 v72, 0x3f596d27, v83
	v_fma_f32 v73, |v72|, s98, 1.0
	v_cvt_pk_bf16_f32 v70, v70, s0
	ds_write_b16 v88, v70 offset:544
	v_mul_f32_e32 v70, 0.5, v83
	v_rcp_f32_e32 v73, v73
	v_mul_f32_e64 v76, |v72|, -|v72|
	v_fmamk_f32 v75, v73, 0x3f87dc22, v206
	v_fmaak_f32 v75, v75, v73, 0x3fb5f0e3
	v_exp_f32_e32 v76, v76
	v_fmaak_f32 v75, v75, v73, 0xbe91a98e
	v_fmaak_f32 v75, v75, v73, 0x3e827906
	v_mul_f32_e32 v73, v73, v75
	v_fma_f32 v72, -v76, v73, 1.0
	v_fma_f32 v70, |v70|, v72, v70
	v_mul_f32_e32 v70, v71, v70
	v_cvt_pk_bf16_f32 v70, v70, s0
	ds_write_b16 v88, v70 offset:816
	s_waitcnt lgkmcnt(14)
	v_fma_f32 v72, v215, v221, v218
	v_fmac_f32_e32 v72, v217, v154
	v_fmac_f32_e32 v72, v216, v155
	v_mul_f32_e32 v76, 0x3f596d27, v72
	v_fma_f32 v77, |v76|, s98, 1.0
	v_fma_f32 v73, v217, v155, v218
	v_fmac_f32_e32 v73, v215, v154
	v_fmac_f32_e32 v73, v216, v152
	v_rcp_f32_e32 v77, v77
	v_mul_f32_e64 v84, |v76|, -|v76|
	v_fmamk_f32 v83, v77, 0x3f87dc22, v206
	v_fmaak_f32 v83, v83, v77, 0x3fb5f0e3
	v_exp_f32_e32 v84, v84
	v_fmaak_f32 v83, v83, v77, 0xbe91a98e
	v_fmaak_f32 v83, v83, v77, 0x3e827906
	v_mul_f32_e32 v77, v77, v83
	v_fma_f32 v76, -v84, v77, 1.0
	v_mul_f32_e32 v72, 0.5, v72
	v_fma_f32 v75, v217, v152, v218
	v_fma_f32 v72, |v72|, v76, v72
	v_fmac_f32_e32 v75, v215, v155
	v_mul_f32_e32 v68, v68, v72
	v_mul_f32_e32 v72, 0x3f596d27, v73
	v_fmac_f32_e32 v75, v216, v153
	v_fma_f32 v76, |v72|, s98, 1.0
	v_fma_f32 v71, v217, v153, v218
	v_fmac_f32_e32 v71, v215, v152
	v_fmac_f32_e32 v71, v216, v219
	v_add_u32_e32 v70, 0xbb00, v220
	v_add_u32_e32 v85, v222, v70
	v_cvt_pk_bf16_f32 v68, v68, s0
	ds_write_b16 v85, v68
	v_mul_f32_e32 v68, 0.5, v73
	v_rcp_f32_e32 v73, v76
	v_mul_f32_e64 v77, |v72|, -|v72|
	v_fmamk_f32 v76, v73, 0x3f87dc22, v206
	v_fmaak_f32 v76, v76, v73, 0x3fb5f0e3
	v_exp_f32_e32 v77, v77
	v_fmaak_f32 v76, v76, v73, 0xbe91a98e
	v_fmaak_f32 v76, v76, v73, 0x3e827906
	v_mul_f32_e32 v73, v73, v76
	v_fma_f32 v72, -v77, v73, 1.0
	v_fma_f32 v68, |v68|, v72, v68
	v_mul_f32_e32 v68, v69, v68
	v_mul_f32_e32 v69, 0x3f596d27, v75
	v_fma_f32 v72, |v69|, s98, 1.0
	v_cvt_pk_bf16_f32 v68, v68, s0
	ds_write_b16 v85, v68 offset:272
	v_mul_f32_e32 v68, 0.5, v75
	v_rcp_f32_e32 v72, v72
	v_mul_f32_e64 v75, |v69|, -|v69|
	v_fmamk_f32 v73, v72, 0x3f87dc22, v206
	v_fmaak_f32 v73, v73, v72, 0x3fb5f0e3
	v_exp_f32_e32 v75, v75
	v_fmaak_f32 v73, v73, v72, 0xbe91a98e
	v_fmaak_f32 v73, v73, v72, 0x3e827906
	v_mul_f32_e32 v72, v72, v73
	v_fma_f32 v69, -v75, v72, 1.0
	v_fma_f32 v68, |v68|, v69, v68
	v_mul_f32_e32 v66, v66, v68
	v_mul_f32_e32 v68, 0x3f596d27, v71
	v_fma_f32 v69, |v68|, s98, 1.0
	v_cvt_pk_bf16_f32 v66, v66, s0
	ds_write_b16 v85, v66 offset:544
	v_mul_f32_e32 v66, 0.5, v71
	v_rcp_f32_e32 v69, v69
	v_mul_f32_e64 v73, |v68|, -|v68|
	v_fmamk_f32 v72, v69, 0x3f87dc22, v206
	v_fmaak_f32 v72, v72, v69, 0x3fb5f0e3
	v_exp_f32_e32 v73, v73
	v_fmaak_f32 v72, v72, v69, 0xbe91a98e
	v_fmaak_f32 v72, v72, v69, 0x3e827906
	v_mul_f32_e32 v69, v69, v72
	v_fma_f32 v68, -v73, v69, 1.0
	v_fma_f32 v66, |v66|, v68, v66
	v_mul_f32_e32 v66, v67, v66
	v_cvt_pk_bf16_f32 v66, v66, s0
	ds_write_b16 v85, v66 offset:816
	s_and_saveexec_b64 s[78:79], s[8:9]
	s_cbranch_execz .LBB0_311
; __device__ __forceinline__ u16 f2bf(float f) { return (u16)(pack2(f, f) & 0xffffu); }
; __device__ __forceinline__ float gelu_exact(float x) { return 0.5f * x * (1.0f + erf_f32(x * 0.70710678118654752f)); }
; template <int EPI>
; __device__ __forceinline__ void phase_gemm(const Params& p, const GemmDesc& d, char* shmc) {
;     ...
;       for (int n = 0; n < 2; ++n) {
;         const int col = ewc * 32 + n * 16 + efr;
;         const int ch = ch0 + col;
;         const float w0 = cw[n][0], w1 = cw[n][1], w2 = cw[n][2], cb = cw[n][3];
; #pragma unroll
;         for (int ai = 0; ai < 2; ++ai)
; #pragma unroll
;           for (int m = 0; m < 4; ++m) {
;             const int s = ai * 32 + ewr * 16 + m * 4 + efq;
;             const f32x4 g = acc[ai][0][m][n];
;             const f32x4 v = acc[ai][1][m][n];
;             const float c0 = w0 * gp[ai][m][n] + w1 * g[0] + w2 * g[1] + cb;
;             const float c1 = w0 * g[0] + w1 * g[1] + w2 * g[2] + cb;
;             const float c2 = w0 * g[1] + w1 * g[2] + w2 * g[3] + cb;
;             const float c3 = w0 * g[2] + w1 * g[3] + w2 * gn[ai][m][n] + cb;
;             u16* sp = stg + (s * 4) * 136 + col;
;             sp[0] = f2bf(gelu_exact(c0) * v[0]);
;             sp[136] = f2bf(gelu_exact(c1) * v[1]);
;             sp[272] = f2bf(gelu_exact(c2) * v[2]);
;             sp[408] = f2bf(gelu_exact(c3) * v[3]);
;             if (s == 0) {
;               edge[0 * DFF + ch] = c0; edge[1 * DFF + ch] = g[0]; edge[2 * DFF + ch] = v[0];
;             }
;             if (s == 63) {
;               edge[3 * DFF + ch] = c3; edge[4 * DFF + ch] = g[3]; edge[5 * DFF + ch] = v[3];
	v_add_co_u32_e32 v68, vcc, 0x10000, v94
	s_nop 1
	v_addc_co_u32_e32 v69, vcc, 0, v95, vcc
	global_store_dword v[68:69], v71, off offset:2048
	v_add_co_u32_e32 v68, vcc, 0x16000, v94
	s_nop 1
	v_addc_co_u32_e32 v69, vcc, 0, v95, vcc
	global_store_dword v[68:69], v153, off
	v_add_co_u32_e32 v68, vcc, 0x1b000, v94
	s_nop 1
	v_addc_co_u32_e32 v69, vcc, 0, v95, vcc
	global_store_dword v[68:69], v67, off offset:2048
.LBB0_311:
	s_or_b64 exec, exec, s[78:79]
	v_pk_mul_f32 v[64:65], v[60:61], v[64:65]
	v_pk_mul_f32 v[60:61], v[58:59], v[62:63]
	v_fma_f32 v63, v209, v213, v207
	v_fmac_f32_e32 v63, v210, v146
	v_fmac_f32_e32 v63, v208, v147
	v_mul_f32_e32 v71, 0x3f596d27, v63
	v_fma_f32 v72, |v71|, s98, 1.0
	v_fma_f32 v67, v210, v147, v207
	v_fmac_f32_e32 v67, v209, v146
	v_fmac_f32_e32 v67, v208, v158
	v_rcp_f32_e32 v72, v72
	v_mul_f32_e64 v75, |v71|, -|v71|
	v_fmamk_f32 v73, v72, 0x3f87dc22, v206
	v_fmaak_f32 v73, v73, v72, 0x3fb5f0e3
	v_exp_f32_e32 v75, v75
	v_fmaak_f32 v73, v73, v72, 0xbe91a98e
	v_fmaak_f32 v73, v73, v72, 0x3e827906
	v_mul_f32_e32 v72, v72, v73
	v_fma_f32 v68, v210, v158, v207
	v_fma_f32 v71, -v75, v72, 1.0
	v_fmac_f32_e32 v68, v209, v147
	v_mul_f32_e32 v72, 0x3f596d27, v67
	v_fmac_f32_e32 v68, v208, v159
	v_fma_f32 v73, |v72|, s98, 1.0
	v_fma_f32 v69, v210, v159, v207
	v_mul_f32_e32 v76, 0.5, v63
	v_fmac_f32_e32 v69, v209, v158
	v_fma_f32 v71, |v76|, v71, v76
	v_or_b32_e32 v66, 16, v162
	v_fmac_f32_e32 v69, v208, v214
	v_lshlrev_b32_e32 v62, 1, v66
	v_mul_f32_e32 v71, v60, v71
	v_add3_u32 v66, s14, v220, v62
	v_cvt_pk_bf16_f32 v71, v71, s0
	ds_write_b16 v66, v71
	v_rcp_f32_e32 v71, v73
	v_mul_f32_e64 v75, |v72|, -|v72|
	v_fmamk_f32 v73, v71, 0x3f87dc22, v206
	v_fmaak_f32 v73, v73, v71, 0x3fb5f0e3
	v_exp_f32_e32 v75, v75
	v_fmaak_f32 v73, v73, v71, 0xbe91a98e
	v_fmaak_f32 v73, v73, v71, 0x3e827906
	v_mul_f32_e32 v71, v71, v73
	v_fma_f32 v71, -v75, v71, 1.0
	v_mul_f32_e32 v67, 0.5, v67
	v_fma_f32 v67, |v67|, v71, v67
	v_mul_f32_e32 v61, v61, v67
	v_mul_f32_e32 v67, 0x3f596d27, v68
	v_fma_f32 v71, |v67|, s98, 1.0
	v_cvt_pk_bf16_f32 v61, v61, s0
	ds_write_b16 v66, v61 offset:272
	v_mul_f32_e32 v61, 0.5, v68
	v_rcp_f32_e32 v68, v71
	v_mul_f32_e64 v72, |v67|, -|v67|
	v_fmamk_f32 v71, v68, 0x3f87dc22, v206
	v_fmaak_f32 v71, v71, v68, 0x3fb5f0e3
	v_exp_f32_e32 v72, v72
	v_fmaak_f32 v71, v71, v68, 0xbe91a98e
	v_fmaak_f32 v71, v71, v68, 0x3e827906
	v_mul_f32_e32 v68, v68, v71
	v_fma_f32 v67, -v72, v68, 1.0
	v_fma_f32 v61, |v61|, v67, v61
	v_mul_f32_e32 v61, v64, v61
	v_mul_f32_e32 v64, 0x3f596d27, v69
	v_fma_f32 v67, |v64|, s98, 1.0
	v_cvt_pk_bf16_f32 v61, v61, s0
	ds_write_b16 v66, v61 offset:544
	v_mul_f32_e32 v61, 0.5, v69
	v_rcp_f32_e32 v67, v67
	v_mul_f32_e64 v69, |v64|, -|v64|
	v_fmamk_f32 v68, v67, 0x3f87dc22, v206
	v_fmaak_f32 v68, v68, v67, 0x3fb5f0e3
	v_exp_f32_e32 v69, v69
	v_fmaak_f32 v68, v68, v67, 0xbe91a98e
	v_fmaak_f32 v68, v68, v67, 0x3e827906
	v_mul_f32_e32 v67, v67, v68
	v_fma_f32 v64, -v69, v67, 1.0
	s_ashr_i32 s63, s62, 31
	v_lshl_add_u64 v[58:59], v[162:163], 0, s[62:63]
	v_fma_f32 v61, |v61|, v64, v61
	v_lshl_add_u64 v[58:59], v[58:59], 2, s[64:65]
	v_mul_f32_e32 v61, v65, v61
	v_lshl_add_u64 v[58:59], v[58:59], 0, 64
	v_cvt_pk_bf16_f32 v61, v61, s0
	ds_write_b16 v66, v61 offset:816
	s_and_saveexec_b64 s[64:65], s[10:11]
	s_cbranch_execz .LBB0_313
	v_add_co_u32_e32 v64, vcc, 0x5000, v58
	global_store_dword v[58:59], v63, off
	s_nop 0
	v_addc_co_u32_e32 v65, vcc, 0, v59, vcc
	global_store_dword v[64:65], v146, off offset:2048
	v_add_co_u32_e32 v64, vcc, 0xb000, v58
	s_nop 1
	v_addc_co_u32_e32 v65, vcc, 0, v59, vcc
	global_store_dword v[64:65], v60, off
.LBB0_313:
	s_or_b64 exec, exec, s[64:65]
	v_pk_mul_f32 v[48:49], v[4:5], v[48:49]
	v_pk_mul_f32 v[4:5], v[14:15], v[30:31]
	v_fma_f32 v14, v209, v151, v207
	v_fmac_f32_e32 v14, v210, v144
	v_fmac_f32_e32 v14, v208, v145
	v_pk_mul_f32 v[52:53], v[8:9], v[52:53]
	v_pk_mul_f32 v[8:9], v[18:19], v[34:35]
	v_mul_f32_e32 v18, 0x3f596d27, v14
	v_fma_f32 v19, |v18|, s98, 1.0
	v_pk_mul_f32 v[50:51], v[6:7], v[50:51]
	v_pk_mul_f32 v[6:7], v[20:21], v[36:37]
	v_pk_mul_f32 v[56:57], v[12:13], v[56:57]
	v_pk_mul_f32 v[12:13], v[22:23], v[38:39]
	v_pk_mul_f32 v[54:55], v[10:11], v[54:55]
	v_pk_mul_f32 v[10:11], v[24:25], v[40:41]
	v_rcp_f32_e32 v19, v19
	v_mul_f32_e64 v21, |v18|, -|v18|
	v_fmamk_f32 v20, v19, 0x3f87dc22, v206
	v_fmaak_f32 v20, v20, v19, 0x3fb5f0e3
	v_exp_f32_e32 v21, v21
	v_fmaak_f32 v20, v20, v19, 0xbe91a98e
	v_fmaak_f32 v20, v20, v19, 0x3e827906
	v_fma_f32 v15, v210, v145, v207
	v_mul_f32_e32 v19, v19, v20
	v_fmac_f32_e32 v15, v209, v144
	v_fma_f32 v18, -v21, v19, 1.0
	v_fmac_f32_e32 v15, v208, v142
	v_mul_f32_e32 v14, 0.5, v14
	v_fma_f32 v14, |v14|, v18, v14
	v_mul_f32_e32 v18, 0x3f596d27, v15
	v_fma_f32 v19, |v18|, s98, 1.0
	v_mul_f32_e32 v14, v54, v14
	v_add3_u32 v22, s14, v78, v62
	v_cvt_pk_bf16_f32 v14, v14, s0
	ds_write_b16 v22, v14
	v_mul_f32_e32 v14, 0.5, v15
	v_rcp_f32_e32 v15, v19
	v_mul_f32_e64 v20, |v18|, -|v18|
	v_fmamk_f32 v19, v15, 0x3f87dc22, v206
	v_fmaak_f32 v19, v19, v15, 0x3fb5f0e3
	v_exp_f32_e32 v20, v20
	v_fmaak_f32 v19, v19, v15, 0xbe91a98e
	v_fmaak_f32 v19, v19, v15, 0x3e827906
	v_pk_mul_f32 v[46:47], v[2:3], v[46:47]
	v_pk_mul_f32 v[2:3], v[16:17], v[32:33]
	v_fma_f32 v16, v210, v142, v207
	v_mul_f32_e32 v15, v15, v19
	v_fmac_f32_e32 v16, v209, v145
	v_fma_f32 v15, -v20, v15, 1.0
	v_fmac_f32_e32 v16, v208, v143
	v_fma_f32 v14, |v14|, v15, v14
	v_mul_f32_e32 v15, 0x3f596d27, v16
	v_fma_f32 v18, |v15|, s98, 1.0
	v_mul_f32_e32 v14, v55, v14
	v_cvt_pk_bf16_f32 v14, v14, s0
	ds_write_b16 v22, v14 offset:272
	v_mul_f32_e32 v14, 0.5, v16
; __device__ __forceinline__ u16 f2bf(float f) { return (u16)(pack2(f, f) & 0xffffu); }
; __device__ __forceinline__ float gelu_exact(float x) { return 0.5f * x * (1.0f + erf_f32(x * 0.70710678118654752f)); }
; template <int EPI>
; __device__ __forceinline__ void phase_gemm(const Params& p, const GemmDesc& d, char* shmc) {
;     ...
;         for (int ai = 0; ai < 2; ++ai)
; #pragma unroll
;           for (int m = 0; m < 4; ++m) {
;             const int s = ai * 32 + ewr * 16 + m * 4 + efq;
;             const f32x4 g = acc[ai][0][m][n];
;             const f32x4 v = acc[ai][1][m][n];
;             const float c0 = w0 * gp[ai][m][n] + w1 * g[0] + w2 * g[1] + cb;
;             const float c1 = w0 * g[0] + w1 * g[1] + w2 * g[2] + cb;
;             const float c2 = w0 * g[1] + w1 * g[2] + w2 * g[3] + cb;
;             const float c3 = w0 * g[2] + w1 * g[3] + w2 * gn[ai][m][n] + cb;
;             u16* sp = stg + (s * 4) * 136 + col;
;             sp[0] = f2bf(gelu_exact(c0) * v[0]);
;             sp[136] = f2bf(gelu_exact(c1) * v[1]);
;             sp[272] = f2bf(gelu_exact(c2) * v[2]);
;             sp[408] = f2bf(gelu_exact(c3) * v[3]);
	v_rcp_f32_e32 v16, v18
	v_mul_f32_e64 v19, |v15|, -|v15|
	v_fmamk_f32 v18, v16, 0x3f87dc22, v206
	v_fmaak_f32 v18, v18, v16, 0x3fb5f0e3
	v_exp_f32_e32 v19, v19
	v_fmaak_f32 v18, v18, v16, 0xbe91a98e
	v_fmaak_f32 v18, v18, v16, 0x3e827906
	v_fma_f32 v17, v210, v143, v207
	v_mul_f32_e32 v16, v16, v18
	v_fmac_f32_e32 v17, v209, v142
	v_fma_f32 v15, -v19, v16, 1.0
	v_fmac_f32_e32 v17, v208, v149
	v_fma_f32 v14, |v14|, v15, v14
	v_mul_f32_e32 v15, 0x3f596d27, v17
	v_fma_f32 v16, |v15|, s98, 1.0
	v_mul_f32_e32 v14, v56, v14
	v_cvt_pk_bf16_f32 v14, v14, s0
	ds_write_b16 v22, v14 offset:544
	v_mul_f32_e32 v14, 0.5, v17
	v_rcp_f32_e32 v16, v16
	v_mul_f32_e64 v18, |v15|, -|v15|
	v_fmamk_f32 v17, v16, 0x3f87dc22, v206
	v_fmaak_f32 v17, v17, v16, 0x3fb5f0e3
	v_exp_f32_e32 v18, v18
	v_fmaak_f32 v17, v17, v16, 0xbe91a98e
	v_fmaak_f32 v17, v17, v16, 0x3e827906
	v_mul_f32_e32 v16, v16, v17
	v_fma_f32 v15, -v18, v16, 1.0
	v_fma_f32 v14, |v14|, v15, v14
	v_mul_f32_e32 v14, v57, v14
	v_cvt_pk_bf16_f32 v14, v14, s0
	ds_write_b16 v22, v14 offset:816
	v_fma_f32 v14, v209, v141, v207
	v_fmac_f32_e32 v14, v210, v136
	v_fmac_f32_e32 v14, v208, v137
	v_mul_f32_e32 v18, 0x3f596d27, v14
	v_fma_f32 v19, |v18|, s98, 1.0
	v_fma_f32 v15, v210, v137, v207
	v_fmac_f32_e32 v15, v209, v136
	v_fmac_f32_e32 v15, v208, v134
	v_rcp_f32_e32 v19, v19
	v_mul_f32_e64 v21, |v18|, -|v18|
	v_fmamk_f32 v20, v19, 0x3f87dc22, v206
	v_fmaak_f32 v20, v20, v19, 0x3fb5f0e3
	v_exp_f32_e32 v21, v21
	v_fmaak_f32 v20, v20, v19, 0xbe91a98e
	v_fmaak_f32 v20, v20, v19, 0x3e827906
	v_mul_f32_e32 v19, v19, v20
	v_fma_f32 v18, -v21, v19, 1.0
	v_mul_f32_e32 v14, 0.5, v14
	v_fma_f32 v14, |v14|, v18, v14
	v_mul_f32_e32 v18, 0x3f596d27, v15
	v_fma_f32 v19, |v18|, s98, 1.0
	v_mul_f32_e32 v14, v50, v14
	v_add3_u32 v22, s14, v79, v62
	v_cvt_pk_bf16_f32 v14, v14, s0
	ds_write_b16 v22, v14
	v_mul_f32_e32 v14, 0.5, v15
	v_rcp_f32_e32 v15, v19
	v_mul_f32_e64 v20, |v18|, -|v18|
	v_fmamk_f32 v19, v15, 0x3f87dc22, v206
	v_fmaak_f32 v19, v19, v15, 0x3fb5f0e3
	v_exp_f32_e32 v20, v20
	v_fmaak_f32 v19, v19, v15, 0xbe91a98e
	v_fmaak_f32 v19, v19, v15, 0x3e827906
	v_fma_f32 v16, v210, v134, v207
	v_mul_f32_e32 v15, v15, v19
	v_fmac_f32_e32 v16, v209, v137
	v_fma_f32 v15, -v20, v15, 1.0
	v_fmac_f32_e32 v16, v208, v135
	v_fma_f32 v14, |v14|, v15, v14
	v_mul_f32_e32 v15, 0x3f596d27, v16
	v_fma_f32 v18, |v15|, s98, 1.0
	v_mul_f32_e32 v14, v51, v14
	v_cvt_pk_bf16_f32 v14, v14, s0
	ds_write_b16 v22, v14 offset:272
	v_mul_f32_e32 v14, 0.5, v16
	v_rcp_f32_e32 v16, v18
	v_mul_f32_e64 v19, |v15|, -|v15|
	v_fmamk_f32 v18, v16, 0x3f87dc22, v206
	v_fmaak_f32 v18, v18, v16, 0x3fb5f0e3
	v_exp_f32_e32 v19, v19
	v_fmaak_f32 v18, v18, v16, 0xbe91a98e
	v_fmaak_f32 v18, v18, v16, 0x3e827906
	v_fma_f32 v17, v210, v135, v207
	v_mul_f32_e32 v16, v16, v18
	v_fmac_f32_e32 v17, v209, v134
	v_fma_f32 v15, -v19, v16, 1.0
	v_fmac_f32_e32 v17, v208, v139
	v_fma_f32 v14, |v14|, v15, v14
	v_mul_f32_e32 v15, 0x3f596d27, v17
	v_fma_f32 v16, |v15|, s98, 1.0
	v_mul_f32_e32 v14, v52, v14
	v_cvt_pk_bf16_f32 v14, v14, s0
	ds_write_b16 v22, v14 offset:544
	v_mul_f32_e32 v14, 0.5, v17
	v_rcp_f32_e32 v16, v16
	v_mul_f32_e64 v18, |v15|, -|v15|
	v_fmamk_f32 v17, v16, 0x3f87dc22, v206
	v_fmaak_f32 v17, v17, v16, 0x3fb5f0e3
	v_exp_f32_e32 v18, v18
	v_fmaak_f32 v17, v17, v16, 0xbe91a98e
	v_fmaak_f32 v17, v17, v16, 0x3e827906
	v_mul_f32_e32 v16, v16, v17
	v_fma_f32 v15, -v18, v16, 1.0
	v_fma_f32 v14, |v14|, v15, v14
	v_mul_f32_e32 v14, v53, v14
	v_cvt_pk_bf16_f32 v14, v14, s0
	ds_write_b16 v22, v14 offset:816
	v_fma_f32 v14, v209, v133, v207
	v_fmac_f32_e32 v14, v210, v128
	v_fmac_f32_e32 v14, v208, v129
	v_mul_f32_e32 v18, 0x3f596d27, v14
	v_fma_f32 v19, |v18|, s98, 1.0
	v_fma_f32 v15, v210, v129, v207
	v_fmac_f32_e32 v15, v209, v128
	v_fmac_f32_e32 v15, v208, v126
	v_rcp_f32_e32 v19, v19
	v_mul_f32_e64 v21, |v18|, -|v18|
	v_fmamk_f32 v20, v19, 0x3f87dc22, v206
	v_fmaak_f32 v20, v20, v19, 0x3fb5f0e3
	v_exp_f32_e32 v21, v21
	v_fmaak_f32 v20, v20, v19, 0xbe91a98e
	v_fmaak_f32 v20, v20, v19, 0x3e827906
	v_mul_f32_e32 v19, v19, v20
	v_fma_f32 v18, -v21, v19, 1.0
	v_mul_f32_e32 v14, 0.5, v14
	v_fma_f32 v14, |v14|, v18, v14
	v_mul_f32_e32 v18, 0x3f596d27, v15
	v_fma_f32 v19, |v18|, s98, 1.0
	v_mul_f32_e32 v14, v46, v14
	v_add3_u32 v22, s14, v80, v62
	v_cvt_pk_bf16_f32 v14, v14, s0
	ds_write_b16 v22, v14
	v_mul_f32_e32 v14, 0.5, v15
	v_rcp_f32_e32 v15, v19
	v_mul_f32_e64 v20, |v18|, -|v18|
	v_fmamk_f32 v19, v15, 0x3f87dc22, v206
	v_fmaak_f32 v19, v19, v15, 0x3fb5f0e3
	v_exp_f32_e32 v20, v20
	v_fmaak_f32 v19, v19, v15, 0xbe91a98e
	v_fmaak_f32 v19, v19, v15, 0x3e827906
	v_fma_f32 v16, v210, v126, v207
	v_mul_f32_e32 v15, v15, v19
	v_fmac_f32_e32 v16, v209, v129
	v_fma_f32 v15, -v20, v15, 1.0
	v_fmac_f32_e32 v16, v208, v127
	v_fma_f32 v14, |v14|, v15, v14
	v_mul_f32_e32 v15, 0x3f596d27, v16
	v_fma_f32 v18, |v15|, s98, 1.0
	v_mul_f32_e32 v14, v47, v14
	v_cvt_pk_bf16_f32 v14, v14, s0
	ds_write_b16 v22, v14 offset:272
	v_mul_f32_e32 v14, 0.5, v16
	v_rcp_f32_e32 v16, v18
	v_mul_f32_e64 v19, |v15|, -|v15|
	v_fmamk_f32 v18, v16, 0x3f87dc22, v206
	v_fmaak_f32 v18, v18, v16, 0x3fb5f0e3
	v_exp_f32_e32 v19, v19
	v_fmaak_f32 v18, v18, v16, 0xbe91a98e
	v_fmaak_f32 v18, v18, v16, 0x3e827906
	v_fma_f32 v17, v210, v127, v207
	v_mul_f32_e32 v16, v16, v18
	v_fmac_f32_e32 v17, v209, v126
	v_fma_f32 v15, -v19, v16, 1.0
	v_fmac_f32_e32 v17, v208, v131
	v_fma_f32 v14, |v14|, v15, v14
	v_mul_f32_e32 v15, 0x3f596d27, v17
	v_fma_f32 v16, |v15|, s98, 1.0
	v_mul_f32_e32 v14, v48, v14
	v_cvt_pk_bf16_f32 v14, v14, s0
	ds_write_b16 v22, v14 offset:544
	v_mul_f32_e32 v14, 0.5, v17
	v_rcp_f32_e32 v16, v16
; __device__ __forceinline__ u16 f2bf(float f) { return (u16)(pack2(f, f) & 0xffffu); }
; __device__ __forceinline__ float gelu_exact(float x) { return 0.5f * x * (1.0f + erf_f32(x * 0.70710678118654752f)); }
; template <int EPI>
; __device__ __forceinline__ void phase_gemm(const Params& p, const GemmDesc& d, char* shmc) {
;     ...
;         for (int ai = 0; ai < 2; ++ai)
; #pragma unroll
;           for (int m = 0; m < 4; ++m) {
;             const int s = ai * 32 + ewr * 16 + m * 4 + efq;
;             const f32x4 g = acc[ai][0][m][n];
;             const f32x4 v = acc[ai][1][m][n];
;             const float c0 = w0 * gp[ai][m][n] + w1 * g[0] + w2 * g[1] + cb;
;             const float c1 = w0 * g[0] + w1 * g[1] + w2 * g[2] + cb;
;             const float c2 = w0 * g[1] + w1 * g[2] + w2 * g[3] + cb;
;             const float c3 = w0 * g[2] + w1 * g[3] + w2 * gn[ai][m][n] + cb;
;             u16* sp = stg + (s * 4) * 136 + col;
;             sp[0] = f2bf(gelu_exact(c0) * v[0]);
;             sp[136] = f2bf(gelu_exact(c1) * v[1]);
;             sp[272] = f2bf(gelu_exact(c2) * v[2]);
;             sp[408] = f2bf(gelu_exact(c3) * v[3]);
	v_mul_f32_e64 v18, |v15|, -|v15|
	v_fmamk_f32 v17, v16, 0x3f87dc22, v206
	v_fmaak_f32 v17, v17, v16, 0x3fb5f0e3
	v_exp_f32_e32 v18, v18
	v_fmaak_f32 v17, v17, v16, 0xbe91a98e
	v_fmaak_f32 v17, v17, v16, 0x3e827906
	v_mul_f32_e32 v16, v16, v17
	v_fma_f32 v15, -v18, v16, 1.0
	v_fma_f32 v14, |v14|, v15, v14
	v_mul_f32_e32 v14, v49, v14
	v_cvt_pk_bf16_f32 v14, v14, s0
	ds_write_b16 v22, v14 offset:816
	v_fma_f32 v14, v209, v125, v207
	v_fmac_f32_e32 v14, v210, v120
	v_fmac_f32_e32 v14, v208, v121
	v_mul_f32_e32 v18, 0x3f596d27, v14
	v_fma_f32 v19, |v18|, s98, 1.0
	v_fma_f32 v15, v210, v121, v207
	v_fmac_f32_e32 v15, v209, v120
	v_fmac_f32_e32 v15, v208, v118
	v_rcp_f32_e32 v19, v19
	v_mul_f32_e64 v21, |v18|, -|v18|
	v_fmamk_f32 v20, v19, 0x3f87dc22, v206
	v_fmaak_f32 v20, v20, v19, 0x3fb5f0e3
	v_exp_f32_e32 v21, v21
	v_fmaak_f32 v20, v20, v19, 0xbe91a98e
	v_fmaak_f32 v20, v20, v19, 0x3e827906
	v_mul_f32_e32 v19, v19, v20
	v_fma_f32 v18, -v21, v19, 1.0
	v_mul_f32_e32 v14, 0.5, v14
	v_fma_f32 v14, |v14|, v18, v14
	v_mul_f32_e32 v18, 0x3f596d27, v15
	v_fma_f32 v19, |v18|, s98, 1.0
	v_pk_mul_f32 v[26:27], v[26:27], v[42:43]
	v_add3_u32 v22, s14, v81, v62
	v_mul_f32_e32 v14, v26, v14
	v_cvt_pk_bf16_f32 v14, v14, s0
	ds_write_b16 v22, v14
	v_mul_f32_e32 v14, 0.5, v15
	v_rcp_f32_e32 v15, v19
	v_mul_f32_e64 v20, |v18|, -|v18|
	v_fmamk_f32 v19, v15, 0x3f87dc22, v206
	v_fmaak_f32 v19, v19, v15, 0x3fb5f0e3
	v_exp_f32_e32 v20, v20
	v_fmaak_f32 v19, v19, v15, 0xbe91a98e
	v_fmaak_f32 v19, v19, v15, 0x3e827906
	v_fma_f32 v16, v210, v118, v207
	v_mul_f32_e32 v15, v15, v19
	v_fmac_f32_e32 v16, v209, v121
	v_fma_f32 v15, -v20, v15, 1.0
	v_fmac_f32_e32 v16, v208, v119
	v_fma_f32 v14, |v14|, v15, v14
	v_mul_f32_e32 v15, 0x3f596d27, v16
	v_fma_f32 v18, |v15|, s98, 1.0
	v_mul_f32_e32 v14, v27, v14
	v_cvt_pk_bf16_f32 v14, v14, s0
	ds_write_b16 v22, v14 offset:272
	v_mul_f32_e32 v14, 0.5, v16
	v_rcp_f32_e32 v16, v18
	v_mul_f32_e64 v19, |v15|, -|v15|
	v_fmamk_f32 v18, v16, 0x3f87dc22, v206
	v_fmaak_f32 v18, v18, v16, 0x3fb5f0e3
	v_exp_f32_e32 v19, v19
	v_fmaak_f32 v18, v18, v16, 0xbe91a98e
	v_fmaak_f32 v18, v18, v16, 0x3e827906
	v_fma_f32 v17, v210, v119, v207
	v_mul_f32_e32 v16, v16, v18
	v_fmac_f32_e32 v17, v209, v118
	v_fma_f32 v15, -v19, v16, 1.0
	v_fmac_f32_e32 v17, v208, v123
	v_fma_f32 v14, |v14|, v15, v14
	v_mul_f32_e32 v15, 0x3f596d27, v17
	v_fma_f32 v16, |v15|, s98, 1.0
	v_pk_mul_f32 v[28:29], v[28:29], v[44:45]
	s_nop 0
	v_mul_f32_e32 v14, v28, v14
	v_cvt_pk_bf16_f32 v14, v14, s0
	ds_write_b16 v22, v14 offset:544
	v_mul_f32_e32 v14, 0.5, v17
	v_rcp_f32_e32 v16, v16
	v_mul_f32_e64 v18, |v15|, -|v15|
	v_fmamk_f32 v17, v16, 0x3f87dc22, v206
	v_fmaak_f32 v17, v17, v16, 0x3fb5f0e3
	v_exp_f32_e32 v18, v18
	v_fmaak_f32 v17, v17, v16, 0xbe91a98e
	v_fmaak_f32 v17, v17, v16, 0x3e827906
	v_mul_f32_e32 v16, v16, v17
	v_fma_f32 v15, -v18, v16, 1.0
	v_fma_f32 v14, |v14|, v15, v14
	v_mul_f32_e32 v14, v29, v14
	v_cvt_pk_bf16_f32 v14, v14, s0
	ds_write_b16 v22, v14 offset:816
	v_fma_f32 v14, v209, v117, v207
	v_fmac_f32_e32 v14, v210, v112
	v_fmac_f32_e32 v14, v208, v113
	v_mul_f32_e32 v18, 0x3f596d27, v14
	v_fma_f32 v19, |v18|, s98, 1.0
	v_fma_f32 v15, v210, v113, v207
	v_fmac_f32_e32 v15, v209, v112
	v_fmac_f32_e32 v15, v208, v110
	v_rcp_f32_e32 v19, v19
	v_mul_f32_e64 v21, |v18|, -|v18|
	v_fmamk_f32 v20, v19, 0x3f87dc22, v206
	v_fmaak_f32 v20, v20, v19, 0x3fb5f0e3
	v_exp_f32_e32 v21, v21
	v_fmaak_f32 v20, v20, v19, 0xbe91a98e
	v_fmaak_f32 v20, v20, v19, 0x3e827906
	v_mul_f32_e32 v19, v19, v20
	v_fma_f32 v18, -v21, v19, 1.0
	v_mul_f32_e32 v14, 0.5, v14
	v_fma_f32 v14, |v14|, v18, v14
	v_mul_f32_e32 v12, v12, v14
	v_mul_f32_e32 v14, 0x3f596d27, v15
	v_fma_f32 v18, |v14|, s98, 1.0
	v_add3_u32 v22, s14, v82, v62
	v_cvt_pk_bf16_f32 v12, v12, s0
	ds_write_b16 v22, v12
	v_mul_f32_e32 v12, 0.5, v15
	v_rcp_f32_e32 v15, v18
	v_mul_f32_e64 v19, |v14|, -|v14|
	v_fmamk_f32 v18, v15, 0x3f87dc22, v206
	v_fmaak_f32 v18, v18, v15, 0x3fb5f0e3
	v_exp_f32_e32 v19, v19
	v_fmaak_f32 v18, v18, v15, 0xbe91a98e
	v_fmaak_f32 v18, v18, v15, 0x3e827906
	v_mul_f32_e32 v15, v15, v18
	v_fma_f32 v16, v210, v110, v207
	v_fma_f32 v14, -v19, v15, 1.0
	v_fmac_f32_e32 v16, v209, v113
	v_fmac_f32_e32 v16, v208, v111
	v_fma_f32 v12, |v12|, v14, v12
	v_mul_f32_e32 v12, v13, v12
	v_mul_f32_e32 v13, 0x3f596d27, v16
	v_fma_f32 v14, |v13|, s98, 1.0
	v_cvt_pk_bf16_f32 v12, v12, s0
	ds_write_b16 v22, v12 offset:272
	v_mul_f32_e32 v12, 0.5, v16
	v_rcp_f32_e32 v14, v14
	v_mul_f32_e64 v16, |v13|, -|v13|
	v_fmamk_f32 v15, v14, 0x3f87dc22, v206
	v_fmaak_f32 v15, v15, v14, 0x3fb5f0e3
	v_exp_f32_e32 v16, v16
	v_fmaak_f32 v15, v15, v14, 0xbe91a98e
	v_fmaak_f32 v15, v15, v14, 0x3e827906
	v_mul_f32_e32 v14, v14, v15
	v_fma_f32 v17, v210, v111, v207
	v_fma_f32 v13, -v16, v14, 1.0
	v_fmac_f32_e32 v17, v209, v110
	v_fmac_f32_e32 v17, v208, v115
	v_fma_f32 v12, |v12|, v13, v12
	v_mul_f32_e32 v10, v10, v12
	v_mul_f32_e32 v12, 0x3f596d27, v17
	v_fma_f32 v13, |v12|, s98, 1.0
	v_cvt_pk_bf16_f32 v10, v10, s0
	ds_write_b16 v22, v10 offset:544
	v_mul_f32_e32 v10, 0.5, v17
	v_rcp_f32_e32 v13, v13
	v_mul_f32_e64 v15, |v12|, -|v12|
	v_fmamk_f32 v14, v13, 0x3f87dc22, v206
	v_fmaak_f32 v14, v14, v13, 0x3fb5f0e3
	v_exp_f32_e32 v15, v15
	v_fmaak_f32 v14, v14, v13, 0xbe91a98e
	v_fmaak_f32 v14, v14, v13, 0x3e827906
	v_mul_f32_e32 v13, v13, v14
	v_fma_f32 v12, -v15, v13, 1.0
	v_fma_f32 v10, |v10|, v12, v10
; __device__ __forceinline__ u16 f2bf(float f) { return (u16)(pack2(f, f) & 0xffffu); }
; __device__ __forceinline__ float gelu_exact(float x) { return 0.5f * x * (1.0f + erf_f32(x * 0.70710678118654752f)); }
; template <int EPI>
; __device__ __forceinline__ void phase_gemm(const Params& p, const GemmDesc& d, char* shmc) {
;     ...
; #pragma unroll
;       for (int n = 0; n < 2; ++n) {
;         const int col = ewc * 32 + n * 16 + efr;
;         const int ch = ch0 + col;
;         const float w0 = cw[n][0], w1 = cw[n][1], w2 = cw[n][2], cb = cw[n][3];
; #pragma unroll
;         for (int ai = 0; ai < 2; ++ai)
; #pragma unroll
;           for (int m = 0; m < 4; ++m) {
;             const int s = ai * 32 + ewr * 16 + m * 4 + efq;
;             const f32x4 g = acc[ai][0][m][n];
;             const f32x4 v = acc[ai][1][m][n];
;             const float c0 = w0 * gp[ai][m][n] + w1 * g[0] + w2 * g[1] + cb;
;             const float c1 = w0 * g[0] + w1 * g[1] + w2 * g[2] + cb;
;             const float c2 = w0 * g[1] + w1 * g[2] + w2 * g[3] + cb;
;             const float c3 = w0 * g[2] + w1 * g[3] + w2 * gn[ai][m][n] + cb;
;             u16* sp = stg + (s * 4) * 136 + col;
;             sp[0] = f2bf(gelu_exact(c0) * v[0]);
;             sp[136] = f2bf(gelu_exact(c1) * v[1]);
;             sp[272] = f2bf(gelu_exact(c2) * v[2]);
;             sp[408] = f2bf(gelu_exact(c3) * v[3]);
;             if (s == 0) {
;               edge[0 * DFF + ch] = c0; edge[1 * DFF + ch] = g[0]; edge[2 * DFF + ch] = v[0];
;             }
;             if (s == 63) {
;               edge[3 * DFF + ch] = c3; edge[4 * DFF + ch] = g[3]; edge[5 * DFF + ch] = v[3];
;             }
;           }
	v_mul_f32_e32 v10, v11, v10
	v_cvt_pk_bf16_f32 v10, v10, s0
	ds_write_b16 v22, v10 offset:816
	v_fma_f32 v10, v209, v109, v207
	v_fmac_f32_e32 v10, v210, v104
	v_fmac_f32_e32 v10, v208, v105
	v_mul_f32_e32 v14, 0x3f596d27, v10
	v_fma_f32 v15, |v14|, s98, 1.0
	v_fma_f32 v11, v210, v105, v207
	v_fmac_f32_e32 v11, v209, v104
	v_fmac_f32_e32 v11, v208, v102
	v_rcp_f32_e32 v15, v15
	v_mul_f32_e64 v17, |v14|, -|v14|
	v_fmamk_f32 v16, v15, 0x3f87dc22, v206
	v_fmaak_f32 v16, v16, v15, 0x3fb5f0e3
	v_exp_f32_e32 v17, v17
	v_fmaak_f32 v16, v16, v15, 0xbe91a98e
	v_fmaak_f32 v16, v16, v15, 0x3e827906
	v_mul_f32_e32 v15, v15, v16
	v_fma_f32 v14, -v17, v15, 1.0
	v_mul_f32_e32 v10, 0.5, v10
	v_fma_f32 v10, |v10|, v14, v10
	v_mul_f32_e32 v8, v8, v10
	v_mul_f32_e32 v10, 0x3f596d27, v11
	v_fma_f32 v14, |v10|, s98, 1.0
	v_add3_u32 v18, s14, v74, v62
	v_cvt_pk_bf16_f32 v8, v8, s0
	ds_write_b16 v18, v8
	v_mul_f32_e32 v8, 0.5, v11
	v_rcp_f32_e32 v11, v14
	v_mul_f32_e64 v15, |v10|, -|v10|
	v_fmamk_f32 v14, v11, 0x3f87dc22, v206
	v_fmaak_f32 v14, v14, v11, 0x3fb5f0e3
	v_exp_f32_e32 v15, v15
	v_fmaak_f32 v14, v14, v11, 0xbe91a98e
	v_fmaak_f32 v14, v14, v11, 0x3e827906
	v_mul_f32_e32 v11, v11, v14
	v_fma_f32 v12, v210, v102, v207
	v_fma_f32 v10, -v15, v11, 1.0
	v_fmac_f32_e32 v12, v209, v105
	v_fmac_f32_e32 v12, v208, v103
	v_fma_f32 v8, |v8|, v10, v8
	v_mul_f32_e32 v8, v9, v8
	v_mul_f32_e32 v9, 0x3f596d27, v12
	v_fma_f32 v10, |v9|, s98, 1.0
	v_cvt_pk_bf16_f32 v8, v8, s0
	ds_write_b16 v18, v8 offset:272
	v_mul_f32_e32 v8, 0.5, v12
	v_rcp_f32_e32 v10, v10
	v_mul_f32_e64 v12, |v9|, -|v9|
	v_fmamk_f32 v11, v10, 0x3f87dc22, v206
	v_fmaak_f32 v11, v11, v10, 0x3fb5f0e3
	v_exp_f32_e32 v12, v12
	v_fmaak_f32 v11, v11, v10, 0xbe91a98e
	v_fmaak_f32 v11, v11, v10, 0x3e827906
	v_mul_f32_e32 v10, v10, v11
	v_fma_f32 v13, v210, v103, v207
	v_fma_f32 v9, -v12, v10, 1.0
	v_fmac_f32_e32 v13, v209, v102
	v_fmac_f32_e32 v13, v208, v107
	v_fma_f32 v8, |v8|, v9, v8
	v_mul_f32_e32 v6, v6, v8
	v_mul_f32_e32 v8, 0x3f596d27, v13
	v_fma_f32 v9, |v8|, s98, 1.0
	v_cvt_pk_bf16_f32 v6, v6, s0
	ds_write_b16 v18, v6 offset:544
	v_mul_f32_e32 v6, 0.5, v13
	v_rcp_f32_e32 v9, v9
	v_mul_f32_e64 v11, |v8|, -|v8|
	v_fmamk_f32 v10, v9, 0x3f87dc22, v206
	v_fmaak_f32 v10, v10, v9, 0x3fb5f0e3
	v_exp_f32_e32 v11, v11
	v_fmaak_f32 v10, v10, v9, 0xbe91a98e
	v_fmaak_f32 v10, v10, v9, 0x3e827906
	v_mul_f32_e32 v9, v9, v10
	v_fma_f32 v8, -v11, v9, 1.0
	v_fma_f32 v6, |v6|, v8, v6
	v_mul_f32_e32 v6, v7, v6
	v_cvt_pk_bf16_f32 v6, v6, s0
	ds_write_b16 v18, v6 offset:816
	v_fma_f32 v7, v209, v212, v207
	v_fmac_f32_e32 v7, v210, v98
	v_fmac_f32_e32 v7, v208, v99
	v_mul_f32_e32 v10, 0x3f596d27, v7
	v_fma_f32 v11, |v10|, s98, 1.0
	v_fma_f32 v8, v210, v99, v207
	v_fmac_f32_e32 v8, v209, v98
	v_fmac_f32_e32 v8, v208, v100
	v_rcp_f32_e32 v11, v11
	v_mul_f32_e64 v13, |v10|, -|v10|
	v_fmamk_f32 v12, v11, 0x3f87dc22, v206
	v_fmaak_f32 v12, v12, v11, 0x3fb5f0e3
	v_exp_f32_e32 v13, v13
	v_fmaak_f32 v12, v12, v11, 0xbe91a98e
	v_fmaak_f32 v12, v12, v11, 0x3e827906
	v_mul_f32_e32 v11, v11, v12
	v_fma_f32 v10, -v13, v11, 1.0
	v_mul_f32_e32 v7, 0.5, v7
	v_fma_f32 v7, |v7|, v10, v7
	v_mul_f32_e32 v4, v4, v7
	v_mul_f32_e32 v7, 0x3f596d27, v8
	v_fma_f32 v10, |v7|, s98, 1.0
	v_add3_u32 v14, s14, v70, v62
	v_cvt_pk_bf16_f32 v4, v4, s0
	ds_write_b16 v14, v4
	v_mul_f32_e32 v4, 0.5, v8
	v_rcp_f32_e32 v8, v10
	v_mul_f32_e64 v11, |v7|, -|v7|
	v_fmamk_f32 v10, v8, 0x3f87dc22, v206
	v_fmaak_f32 v10, v10, v8, 0x3fb5f0e3
	v_exp_f32_e32 v11, v11
	v_fmaak_f32 v10, v10, v8, 0xbe91a98e
	v_fmaak_f32 v10, v10, v8, 0x3e827906
	v_mul_f32_e32 v8, v8, v10
	v_fma_f32 v9, v210, v100, v207
	v_fma_f32 v7, -v11, v8, 1.0
	v_fmac_f32_e32 v9, v209, v99
	v_fmac_f32_e32 v9, v208, v101
	v_fma_f32 v4, |v4|, v7, v4
	v_mul_f32_e32 v4, v5, v4
	v_mul_f32_e32 v5, 0x3f596d27, v9
	v_fma_f32 v7, |v5|, s98, 1.0
	v_cvt_pk_bf16_f32 v4, v4, s0
	ds_write_b16 v14, v4 offset:272
	v_mul_f32_e32 v4, 0.5, v9
	v_rcp_f32_e32 v7, v7
	v_mul_f32_e64 v9, |v5|, -|v5|
	v_fmamk_f32 v8, v7, 0x3f87dc22, v206
	v_fmaak_f32 v8, v8, v7, 0x3fb5f0e3
	v_exp_f32_e32 v9, v9
	v_fmaak_f32 v8, v8, v7, 0xbe91a98e
	v_fmaak_f32 v8, v8, v7, 0x3e827906
	v_mul_f32_e32 v7, v7, v8
	v_fma_f32 v6, v210, v101, v207
	v_fma_f32 v5, -v9, v7, 1.0
	v_fmac_f32_e32 v6, v209, v100
	v_fmac_f32_e32 v6, v208, v211
	v_fma_f32 v4, |v4|, v5, v4
	v_mul_f32_e32 v2, v2, v4
	v_mul_f32_e32 v4, 0x3f596d27, v6
	v_fma_f32 v5, |v4|, s98, 1.0
	v_cvt_pk_bf16_f32 v2, v2, s0
	ds_write_b16 v14, v2 offset:544
	v_mul_f32_e32 v2, 0.5, v6
	v_rcp_f32_e32 v5, v5
	v_mul_f32_e64 v8, |v4|, -|v4|
	v_fmamk_f32 v7, v5, 0x3f87dc22, v206
	v_fmaak_f32 v7, v7, v5, 0x3fb5f0e3
	v_exp_f32_e32 v8, v8
	v_fmaak_f32 v7, v7, v5, 0xbe91a98e
	v_fmaak_f32 v7, v7, v5, 0x3e827906
	v_mul_f32_e32 v5, v5, v7
	v_fma_f32 v4, -v8, v5, 1.0
	v_fma_f32 v2, |v2|, v4, v2
	v_mul_f32_e32 v2, v3, v2
	v_cvt_pk_bf16_f32 v2, v2, s0
	ds_write_b16 v14, v2 offset:816
	s_and_saveexec_b64 s[10:11], s[8:9]
	s_cbranch_execz .LBB0_289
	v_add_co_u32_e32 v4, vcc, 0x10000, v58
	s_nop 1
	v_addc_co_u32_e32 v5, vcc, 0, v59, vcc
	global_store_dword v[4:5], v6, off offset:2048
	v_add_co_u32_e32 v4, vcc, 0x16000, v58
	s_nop 1
	v_addc_co_u32_e32 v5, vcc, 0, v59, vcc
	global_store_dword v[4:5], v101, off
	v_add_co_u32_e32 v4, vcc, 0x1b000, v58
	s_nop 1
	v_addc_co_u32_e32 v5, vcc, 0, v59, vcc
	global_store_dword v[4:5], v3, off offset:2048
	s_branch .LBB0_289

; template <int EPI>
; __device__ __forceinline__ void phase_gemm(const Params& p, const GemmDesc& d, char* shmc) {
;     ...
;       const float* cwp = p.conv_w + (size_t)d.layer * 3 * DFF;
;       const float* cbp = p.conv_b + (size_t)d.layer * DFF;
;       float cw[2][4];
; #pragma unroll
;       for (int n = 0; n < 2; ++n) {
;         const int chx = ch0 + ewc * 32 + n * 16 + efr;
;         cw[n][0] = cwp[chx]; cw[n][1] = cwp[DFF + chx]; cw[n][2] = cwp[2 * DFF + chx]; cw[n][3] = cbp[chx];
;       }
;       const float* rsl = reinterpret_cast<const float*>(shmc + 143360);
;       f32x4 rsv[2][4];
; #pragma unroll
;       for (int ai = 0; ai < 2; ++ai)
; #pragma unroll
;         for (int m = 0; m < 4; ++m)
;           rsv[ai][m] = *reinterpret_cast<const f32x4*>(rsl + ai * HALF + ewr * 64 + m * 16 + efq * 4);
; #pragma unroll
;       for (int ai = 0; ai < 2; ++ai)
; #pragma unroll
;         for (int m = 0; m < 4; ++m) {
;           const f32x4 rs4 = rsv[ai][m];
; #pragma unroll
;           for (int n = 0; n < 2; ++n) {
;             acc[ai][0][m][n] *= rs4;
;             acc[ai][1][m][n] *= rs4;
;             const int s = ai * 32 + ewr * 16 + m * 4 + efq;
;             const int col = ewc * 32 + n * 16 + efr;
;             top[s * 144 + col] = acc[ai][0][m][n][0];
;             bot[s * 144 + col] = acc[ai][0][m][n][3];
;           }
;         }
;       __syncthreads();
.LBB0_1156:
	s_mov_b32 s98, 0x3e8ba43f
	s_or_b64 exec, exec, s[8:9]
	v_mov_b32_e32 v38, v1
	s_lshl_b32 s54, s34, 7
	v_and_b32_e32 v177, 15, v38
	v_lshrrev_b32_e32 v30, 1, v38
	v_and_or_b32 v162, v30, s79, v177
	v_or_b32_e32 v200, s54, v162
	v_ashrrev_i32_e32 v201, 31, v200
	v_lshlrev_b64 v[30:31], 2, v[200:201]
	v_lshl_add_u64 v[32:33], s[22:23], 0, v[30:31]
	v_add_co_u32_e32 v34, vcc, 0x5000, v32
	v_lshl_add_u64 v[30:31], s[24:25], 0, v[30:31]
	s_nop 0
	v_addc_co_u32_e32 v35, vcc, 0, v33, vcc
	v_add_co_u32_e32 v36, vcc, 0xb000, v32
	v_ashrrev_i32_e32 v175, 4, v38
	s_nop 0
	v_addc_co_u32_e32 v37, vcc, 0, v33, vcc
	global_load_dword v215, v[32:33], off
	global_load_dword v217, v[34:35], off offset:2048
	global_load_dword v216, v[36:37], off
	global_load_dword v218, v[30:31], off
	v_or_b32_e32 v30, 16, v200
	v_ashrrev_i32_e32 v31, 31, v30
	v_lshlrev_b64 v[30:31], 2, v[30:31]
	v_lshl_add_u64 v[32:33], s[22:23], 0, v[30:31]
	v_add_co_u32_e32 v34, vcc, s80, v32
	v_lshl_add_u64 v[30:31], s[24:25], 0, v[30:31]
	s_nop 0
	v_addc_co_u32_e32 v35, vcc, 0, v33, vcc
	v_add_co_u32_e32 v36, vcc, s81, v32
	v_bfe_u32 v178, v38, 8, 1
	s_nop 0
	v_addc_co_u32_e32 v37, vcc, 0, v33, vcc
	global_load_dword v208, v[32:33], off
	global_load_dword v210, v[34:35], off offset:2048
	global_load_dword v209, v[36:37], off
	global_load_dword v207, v[30:31], off
	v_and_b32_e32 v179, 3, v175
	v_lshlrev_b32_e32 v30, 8, v178
	v_lshlrev_b32_e32 v31, 4, v179
	v_add3_u32 v30, s63, v30, v31
	v_lshl_or_b32 v220, v178, 4, v179
	ds_read_b128 v[62:65], v30
	ds_read_b128 v[54:57], v30 offset:64
	ds_read_b128 v[50:53], v30 offset:128
	ds_read_b128 v[46:49], v30 offset:192
	ds_read_b128 v[42:45], v30 offset:512
	ds_read_b128 v[38:41], v30 offset:576
	ds_read_b128 v[34:37], v30 offset:640
	ds_read_b128 v[30:33], v30 offset:704
	v_mad_u32_u24 v178, v220, s82, v162
	v_lshl_add_u32 v211, v178, 2, 0
	s_waitcnt lgkmcnt(0)
	v_pk_mul_f32 v[196:197], v[144:145], v[56:57]
	v_pk_mul_f32 v[198:199], v[142:143], v[54:55]
	v_pk_mul_f32 v[144:145], v[134:135], v[54:55]
	v_add_u32_e32 v134, 0x800, v211
	v_pk_mul_f32 v[190:191], v[128:129], v[52:53]
	v_pk_mul_f32 v[188:189], v[110:111], v[46:47]
	v_pk_mul_f32 v[128:129], v[102:103], v[46:47]
	v_add_u32_e32 v102, 0x1800, v211
	v_pk_mul_f32 v[142:143], v[136:137], v[56:57]
	ds_write2_b32 v134, v198, v144 offset0:64 offset1:80
	v_add_u32_e32 v134, 0x9800, v211
	v_pk_mul_f32 v[192:193], v[126:127], v[50:51]
	v_pk_mul_f32 v[136:137], v[118:119], v[50:51]
	v_add_u32_e32 v118, 0x1000, v211
	v_pk_mul_f32 v[186:187], v[112:113], v[48:49]
	v_pk_mul_f32 v[126:127], v[104:105], v[48:49]
	ds_write2_b32 v102, v188, v128 offset0:192 offset1:208
	v_add_u32_e32 v102, 0xa800, v211
	ds_write2_b32 v134, v197, v143 offset0:64 offset1:80
	v_pk_mul_f32 v[134:135], v[120:121], v[52:53]
	ds_write2_b32 v118, v192, v136 offset0:128 offset1:144
	v_add_u32_e32 v118, 0xa000, v211
	ds_write2_b32 v102, v187, v127 offset0:192 offset1:208
	v_pk_mul_f32 v[184:185], v[154:155], v[42:43]
	v_pk_mul_f32 v[120:121], v[150:151], v[42:43]
	v_add_u32_e32 v102, 0x4800, v211
	ds_write2_b32 v118, v191, v135 offset0:128 offset1:144
	v_pk_mul_f32 v[182:183], v[156:157], v[44:45]
	v_pk_mul_f32 v[118:119], v[152:153], v[44:45]
	ds_write2_b32 v102, v184, v120 offset1:16
	v_add_u32_e32 v102, 0xd800, v211
	v_pk_mul_f32 v[154:155], v[106:107], v[30:31]
	v_pk_mul_f32 v[98:99], v[98:99], v[30:31]
	v_add_u32_e32 v106, 0x6000, v211
	ds_write2_b32 v102, v183, v119 offset1:16
	v_pk_mul_f32 v[180:181], v[138:139], v[38:39]
	v_pk_mul_f32 v[112:113], v[130:131], v[38:39]
	v_add_u32_e32 v102, 0x5000, v211
	v_pk_mul_f32 v[152:153], v[108:109], v[32:33]
	v_pk_mul_f32 v[100:101], v[100:101], v[32:33]
	ds_write2_b32 v106, v154, v98 offset0:192 offset1:208
	v_add_u32_e32 v106, 0xf000, v211
	v_pk_mul_f32 v[202:203], v[160:161], v[64:65]
	v_pk_mul_f32 v[194:195], v[158:159], v[62:63]
	v_pk_mul_f32 v[146:147], v[146:147], v[62:63]
	v_pk_mul_f32 v[178:179], v[140:141], v[40:41]
	v_pk_mul_f32 v[110:111], v[132:133], v[40:41]
	ds_write2_b32 v102, v180, v112 offset0:64 offset1:80
	v_add_u32_e32 v102, 0xe000, v211
	v_pk_mul_f32 v[160:161], v[122:123], v[34:35]
	v_pk_mul_f32 v[104:105], v[114:115], v[34:35]
	v_add_u32_e32 v114, 0x5800, v211
	ds_write2_b32 v106, v153, v101 offset0:192 offset1:208
	v_mad_u32_u24 v106, v220, s83, 0
	v_pk_mul_f32 v[158:159], v[148:149], v[64:65]
	ds_write2_b32 v211, v194, v146 offset1:16
	v_add_u32_e32 v148, 0x9000, v211
	ds_write2_b32 v102, v179, v111 offset0:64 offset1:80
	v_pk_mul_f32 v[156:157], v[124:125], v[36:37]
	v_pk_mul_f32 v[102:103], v[116:117], v[36:37]
	ds_write2_b32 v114, v160, v104 offset0:128 offset1:144
	v_add_u32_e32 v114, 0xe800, v211
	v_cmp_eq_u32_e64 s[10:11], 0, v220
	v_cmp_ne_u32_e32 vcc, 0, v220
	v_mov_b32_e32 v213, 0
	v_lshl_add_u32 v211, v162, 2, v106
	v_mov_b32_e32 v224, 0
	ds_write2_b32 v148, v203, v159 offset1:16
	ds_write2_b32 v114, v157, v103 offset0:128 offset1:144
	s_waitcnt vmcnt(0) lgkmcnt(0)
	s_barrier
; __device__ __forceinline__ u16 f2bf(float f) { return (u16)(pack2(f, f) & 0xffffu); }
; __device__ __forceinline__ float gelu_exact(float x) { return 0.5f * x * (1.0f + erf_f32(x * 0.70710678118654752f)); }
; template <int EPI>
; __device__ __forceinline__ void phase_gemm(const Params& p, const GemmDesc& d, char* shmc) {
;     ...
;       float gp[2][4][2], gn[2][4][2];
; #pragma unroll
;       for (int ai = 0; ai < 2; ++ai)
; #pragma unroll
;         for (int m = 0; m < 4; ++m)
; #pragma unroll
;           for (int n = 0; n < 2; ++n) {
;             const int s = ai * 32 + ewr * 16 + m * 4 + efq;
;             const int col = ewc * 32 + n * 16 + efr;
;             gp[ai][m][n] = (s > 0) ? bot[(s - 1) * 144 + col] : 0.f;
;             gn[ai][m][n] = (s < 63) ? top[(s + 1) * 144 + col] : 0.f;
;           }
;       float* edge = p.edge + (size_t)pm * 6 * DFF;
; #pragma unroll
;       for (int n = 0; n < 2; ++n) {
;         const int col = ewc * 32 + n * 16 + efr;
;         const int ch = ch0 + col;
;         const float w0 = cw[n][0], w1 = cw[n][1], w2 = cw[n][2], cb = cw[n][3];
; #pragma unroll
;         for (int ai = 0; ai < 2; ++ai)
; #pragma unroll
;           for (int m = 0; m < 4; ++m) {
;             const int s = ai * 32 + ewr * 16 + m * 4 + efq;
;             const f32x4 g = acc[ai][0][m][n];
;             const f32x4 v = acc[ai][1][m][n];
;             const float c0 = w0 * gp[ai][m][n] + w1 * g[0] + w2 * g[1] + cb;
;             const float c1 = w0 * g[0] + w1 * g[1] + w2 * g[2] + cb;
;             const float c2 = w0 * g[1] + w1 * g[2] + w2 * g[3] + cb;
;             const float c3 = w0 * g[2] + w1 * g[3] + w2 * gn[ai][m][n] + cb;
;             u16* sp = stg + (s * 4) * 136 + col;
;             sp[0] = f2bf(gelu_exact(c0) * v[0]);
;             sp[136] = f2bf(gelu_exact(c1) * v[1]);
;             sp[272] = f2bf(gelu_exact(c2) * v[2]);
;             sp[408] = f2bf(gelu_exact(c3) * v[3]);
;             if (s == 0) {
;               edge[0 * DFF + ch] = c0; edge[1 * DFF + ch] = g[0]; edge[2 * DFF + ch] = v[0];
;             }
;             if (s == 63) {
;               edge[3 * DFF + ch] = c3; edge[4 * DFF + ch] = g[3]; edge[5 * DFF + ch] = v[3];
;             }
;           }
	s_and_saveexec_b64 s[8:9], vcc
	ds_read_b32 v224, v211 offset:36288
	s_or_b64 exec, exec, s[8:9]
	ds_read_b32 v223, v211 offset:576
	s_and_saveexec_b64 s[8:9], vcc
	ds_read_b32 v213, v211 offset:36352
	s_or_b64 exec, exec, s[8:9]
	v_add_u32_e32 v106, 0x9400, v211
	ds_read2_b32 v[150:151], v106 offset0:176 offset1:192
	v_add_u32_e32 v106, 0x800, v211
	ds_read2_b32 v[148:149], v106 offset0:208 offset1:224
	v_add_u32_e32 v106, 0x9e00, v211
	ds_read2_b32 v[140:141], v106 offset0:112 offset1:128
	v_add_u32_e32 v106, 0x1400, v211
	ds_read2_b32 v[138:139], v106 offset0:16 offset1:32
	v_add_u32_e32 v106, 0xa800, v211
	ds_read2_b32 v[132:133], v106 offset0:48 offset1:64
	v_add_u32_e32 v106, 0x1c00, v211
	ds_read2_b32 v[130:131], v106 offset0:80 offset1:96
	v_add_u32_e32 v106, 0xd400, v211
	ds_read2_b32 v[124:125], v106 offset0:112 offset1:128
	v_add_u32_e32 v106, 0x4800, v211
	ds_read2_b32 v[122:123], v106 offset0:144 offset1:160
	v_add_u32_e32 v106, 0xdc00, v211
	ds_read2_b32 v[116:117], v106 offset0:176 offset1:192
	v_add_u32_e32 v106, 0x5000, v211
	ds_read2_b32 v[114:115], v106 offset0:208 offset1:224
	v_add_u32_e32 v106, 0xe600, v211
	ds_read2_b32 v[108:109], v106 offset0:112 offset1:128
	v_add_u32_e32 v106, 0x5c00, v211
	ds_read2_b32 v[106:107], v106 offset0:16 offset1:32
	ds_read_b32 v214, v211 offset:640
	ds_read_b32 v221, v211 offset:61632
	v_cmp_eq_u32_e64 s[8:9], 19, v220
	v_cmp_ne_u32_e32 vcc, 19, v220
	v_add_u32_e32 v222, 0x6300, v211
	v_mov_b32_e32 v211, 0
	v_mov_b32_e32 v219, 0
	s_and_saveexec_b64 s[56:57], vcc
	ds_read_b32 v219, v222 offset:576
	s_or_b64 exec, exec, s[56:57]
	ds_read_b32 v212, v222 offset:36352
	s_and_saveexec_b64 s[56:57], vcc
	ds_read_b32 v211, v222 offset:640
	s_or_b64 exec, exec, s[56:57]
	s_mul_hi_i32 s34, s14, 0x21000
	s_mul_i32 s14, s14, 0x21000
	v_readlane_b32 s56, v246, 15
	v_readlane_b32 s57, v246, 16
	s_add_u32 s56, s56, s14
	s_addc_u32 s57, s57, s34
	v_pk_mul_f32 v[226:227], v[96:97], v[64:65]
	v_pk_mul_f32 v[96:97], v[94:95], v[62:63]
	v_lshl_add_u64 v[94:95], v[200:201], 2, s[56:57]
	s_waitcnt lgkmcnt(14)
	v_fma_f32 v200, v215, v224, v218
	v_fmac_f32_e32 v200, v217, v194
	v_mul_f32_e32 v224, v217, v202
	v_fmac_f32_e32 v200, v216, v195
	v_fma_f32 v201, v217, v195, v218
	v_fmac_f32_e32 v224, v215, v195
	v_fmac_f32_e32 v201, v215, v194
	v_fmac_f32_e32 v224, v216, v203
	v_fma_f32 v203, v217, v203, v218
	v_fmac_f32_e32 v201, v216, v202
	v_fmac_f32_e32 v203, v215, v202
	v_mul_f32_e32 v202, 0x3f596d27, v200
	v_fmac_f32_e32 v203, v216, v223
	v_fma_f32 v223, |v202|, s98, 1.0
	v_add_f32_e32 v195, v218, v224
	v_mul_f32_e32 v229, 0.5, v200
	s_add_i32 s14, 0, 0x12000
	v_rcp_f32_e32 v223, v223
	v_mul_f32_e64 v225, |v202|, -|v202|
	v_fmamk_f32 v224, v223, 0x3f87dc22, v206
	v_fmaak_f32 v224, v224, v223, 0x3fb5f0e3
	v_exp_f32_e32 v225, v225
	v_fmaak_f32 v224, v224, v223, 0xbe91a98e
	v_fmaak_f32 v224, v224, v223, 0x3e827906
	v_mul_f32_e32 v223, v223, v224
	v_fma_f32 v202, -v225, v223, 1.0
	v_mul_f32_e32 v223, 0x3f596d27, v201
	v_fma_f32 v224, |v223|, s98, 1.0
	v_fma_f32 v202, |v229|, v202, v229
	v_lshl_add_u32 v222, v162, 1, s14
	v_mul_f32_e32 v202, v96, v202
	v_mad_u32_u24 v228, v220, s84, v222
	v_cvt_pk_bf16_f32 v202, v202, s0
	ds_write_b16 v228, v202
	v_rcp_f32_e32 v202, v224
	v_mul_f32_e64 v225, |v223|, -|v223|
	v_fmamk_f32 v224, v202, 0x3f87dc22, v206
	v_fmaak_f32 v224, v224, v202, 0x3fb5f0e3
	v_exp_f32_e32 v225, v225
	v_fmaak_f32 v224, v224, v202, 0xbe91a98e
	v_fmaak_f32 v224, v224, v202, 0x3e827906
	v_mul_f32_e32 v202, v202, v224
	v_fma_f32 v202, -v225, v202, 1.0
	v_mul_f32_e32 v201, 0.5, v201
	v_fma_f32 v201, |v201|, v202, v201
	v_mul_f32_e32 v97, v97, v201
	v_mul_f32_e32 v201, 0x3f596d27, v195
	v_fma_f32 v202, |v201|, s98, 1.0
	v_cvt_pk_bf16_f32 v97, v97, s0
	ds_write_b16 v228, v97 offset:272
	v_mul_f32_e32 v97, 0.5, v195
	v_rcp_f32_e32 v195, v202
	v_mul_f32_e64 v223, |v201|, -|v201|
	v_fmamk_f32 v202, v195, 0x3f87dc22, v206
	v_fmaak_f32 v202, v202, v195, 0x3fb5f0e3
	v_exp_f32_e32 v223, v223
	v_fmaak_f32 v202, v202, v195, 0xbe91a98e
	v_fmaak_f32 v202, v202, v195, 0x3e827906
	v_mul_f32_e32 v195, v195, v202
	v_fma_f32 v195, -v223, v195, 1.0
	v_fma_f32 v97, |v97|, v195, v97
	v_mul_f32_e32 v195, 0x3f596d27, v203
	v_fma_f32 v201, |v195|, s98, 1.0
	v_mul_f32_e32 v97, v226, v97
	v_cvt_pk_bf16_f32 v97, v97, s0
	ds_write_b16 v228, v97 offset:544
	v_mul_f32_e32 v97, 0.5, v203
	v_rcp_f32_e32 v201, v201
	v_mul_f32_e64 v203, |v195|, -|v195|
	v_fmamk_f32 v202, v201, 0x3f87dc22, v206
	v_fmaak_f32 v202, v202, v201, 0x3fb5f0e3
	v_exp_f32_e32 v203, v203
	v_fmaak_f32 v202, v202, v201, 0xbe91a98e
	v_fmaak_f32 v202, v202, v201, 0x3e827906
	v_mul_f32_e32 v201, v201, v202
	v_fma_f32 v195, -v203, v201, 1.0
	v_fma_f32 v97, |v97|, v195, v97
	v_mul_f32_e32 v97, v227, v97
	v_readlane_b32 s58, v246, 17
	v_readlane_b32 s59, v246, 18
	v_cvt_pk_bf16_f32 v97, v97, s0
	ds_write_b16 v228, v97 offset:816
	s_and_saveexec_b64 s[58:59], s[10:11]
	s_cbranch_execz .LBB0_1166
	global_store_dword v[94:95], v200, off
	v_add_co_u32_e32 v200, vcc, 0x5000, v94
	s_nop 1
	v_addc_co_u32_e32 v201, vcc, 0, v95, vcc
	global_store_dword v[200:201], v194, off offset:2048
	v_add_co_u32_e32 v194, vcc, 0xb000, v94
	s_nop 1
	v_addc_co_u32_e32 v195, vcc, 0, v95, vcc
	global_store_dword v[194:195], v96, off
; __device__ __forceinline__ u16 f2bf(float f) { return (u16)(pack2(f, f) & 0xffffu); }
; __device__ __forceinline__ float gelu_exact(float x) { return 0.5f * x * (1.0f + erf_f32(x * 0.70710678118654752f)); }
; template <int EPI>
; __device__ __forceinline__ void phase_gemm(const Params& p, const GemmDesc& d, char* shmc) {
;     ...
; #pragma unroll
;       for (int n = 0; n < 2; ++n) {
;         const int col = ewc * 32 + n * 16 + efr;
;         const int ch = ch0 + col;
;         const float w0 = cw[n][0], w1 = cw[n][1], w2 = cw[n][2], cb = cw[n][3];
; #pragma unroll
;         for (int ai = 0; ai < 2; ++ai)
; #pragma unroll
;           for (int m = 0; m < 4; ++m) {
;             const int s = ai * 32 + ewr * 16 + m * 4 + efq;
;             const f32x4 g = acc[ai][0][m][n];
;             const f32x4 v = acc[ai][1][m][n];
;             const float c0 = w0 * gp[ai][m][n] + w1 * g[0] + w2 * g[1] + cb;
;             const float c1 = w0 * g[0] + w1 * g[1] + w2 * g[2] + cb;
;             const float c2 = w0 * g[1] + w1 * g[2] + w2 * g[3] + cb;
;             const float c3 = w0 * g[2] + w1 * g[3] + w2 * gn[ai][m][n] + cb;
;             u16* sp = stg + (s * 4) * 136 + col;
;             sp[0] = f2bf(gelu_exact(c0) * v[0]);
;             sp[136] = f2bf(gelu_exact(c1) * v[1]);
;             sp[272] = f2bf(gelu_exact(c2) * v[2]);
;             sp[408] = f2bf(gelu_exact(c3) * v[3]);
.LBB0_1166:
	s_or_b64 exec, exec, s[58:59]
	v_pk_mul_f32 v[96:97], v[68:69], v[48:49]
	v_pk_mul_f32 v[68:69], v[78:79], v[30:31]
	v_fma_f32 v79, v215, v150, v218
	v_fmac_f32_e32 v79, v217, v198
	v_fmac_f32_e32 v79, v216, v199
	v_pk_mul_f32 v[200:201], v[72:73], v[52:53]
	v_pk_mul_f32 v[72:73], v[82:83], v[34:35]
	v_mul_f32_e32 v83, 0x3f596d27, v79
	v_pk_mul_f32 v[202:203], v[70:71], v[50:51]
	v_pk_mul_f32 v[70:71], v[84:85], v[36:37]
	v_fma_f32 v84, |v83|, s98, 1.0
	v_mul_f32_e32 v78, v217, v199
	v_pk_mul_f32 v[224:225], v[76:77], v[56:57]
	v_pk_mul_f32 v[76:77], v[86:87], v[38:39]
	v_fmac_f32_e32 v78, v215, v198
	v_fmac_f32_e32 v78, v216, v196
	v_pk_mul_f32 v[194:195], v[66:67], v[46:47]
	v_pk_mul_f32 v[66:67], v[80:81], v[32:33]
	v_add_f32_e32 v80, v218, v78
	v_fma_f32 v81, v217, v196, v218
	v_fmac_f32_e32 v81, v215, v199
	v_pk_mul_f32 v[226:227], v[74:75], v[54:55]
	v_pk_mul_f32 v[74:75], v[88:89], v[40:41]
	v_fmac_f32_e32 v81, v216, v197
	v_fma_f32 v82, v217, v197, v218
	v_fmac_f32_e32 v82, v215, v196
	s_waitcnt lgkmcnt(14)
	v_fmac_f32_e32 v82, v216, v148
	v_rcp_f32_e32 v84, v84
	v_mul_f32_e64 v86, |v83|, -|v83|
	v_fmamk_f32 v85, v84, 0x3f87dc22, v206
	v_fmaak_f32 v85, v85, v84, 0x3fb5f0e3
	v_exp_f32_e32 v86, v86
	v_fmaak_f32 v85, v85, v84, 0xbe91a98e
	v_fmaak_f32 v85, v85, v84, 0x3e827906
	v_mul_f32_e32 v84, v84, v85
	v_fma_f32 v83, -v86, v84, 1.0
	v_mul_f32_e32 v79, 0.5, v79
	v_fma_f32 v79, |v79|, v83, v79
	v_mul_f32_e32 v83, 0x3f596d27, v80
	v_fma_f32 v84, |v83|, s98, 1.0
	v_mul_u32_u24_e32 v220, 0x440, v220
	v_add_u32_e32 v78, 0x1100, v220
	v_mul_f32_e32 v79, v226, v79
	v_add_u32_e32 v87, v222, v78
	v_cvt_pk_bf16_f32 v79, v79, s0
	ds_write_b16 v87, v79
	v_mul_f32_e32 v79, 0.5, v80
	v_rcp_f32_e32 v80, v84
	v_mul_f32_e64 v85, |v83|, -|v83|
	v_fmamk_f32 v84, v80, 0x3f87dc22, v206
	v_fmaak_f32 v84, v84, v80, 0x3fb5f0e3
	v_exp_f32_e32 v85, v85
	v_fmaak_f32 v84, v84, v80, 0xbe91a98e
	v_fmaak_f32 v84, v84, v80, 0x3e827906
	v_mul_f32_e32 v80, v80, v84
	v_fma_f32 v80, -v85, v80, 1.0
	v_fma_f32 v79, |v79|, v80, v79
	v_mul_f32_e32 v80, 0x3f596d27, v81
	v_fma_f32 v83, |v80|, s98, 1.0
	v_mul_f32_e32 v79, v227, v79
	v_cvt_pk_bf16_f32 v79, v79, s0
	ds_write_b16 v87, v79 offset:272
	v_mul_f32_e32 v79, 0.5, v81
	v_rcp_f32_e32 v81, v83
	v_mul_f32_e64 v84, |v80|, -|v80|
	v_fmamk_f32 v83, v81, 0x3f87dc22, v206
	v_fmaak_f32 v83, v83, v81, 0x3fb5f0e3
	v_exp_f32_e32 v84, v84
	v_fmaak_f32 v83, v83, v81, 0xbe91a98e
	v_fmaak_f32 v83, v83, v81, 0x3e827906
	v_mul_f32_e32 v81, v81, v83
	v_fma_f32 v80, -v84, v81, 1.0
	v_fma_f32 v79, |v79|, v80, v79
	v_mul_f32_e32 v80, 0x3f596d27, v82
	v_fma_f32 v81, |v80|, s98, 1.0
	v_mul_f32_e32 v79, v224, v79
	v_cvt_pk_bf16_f32 v79, v79, s0
	ds_write_b16 v87, v79 offset:544
	v_mul_f32_e32 v79, 0.5, v82
	v_rcp_f32_e32 v81, v81
	v_mul_f32_e64 v83, |v80|, -|v80|
	v_fmamk_f32 v82, v81, 0x3f87dc22, v206
	v_fmaak_f32 v82, v82, v81, 0x3fb5f0e3
	v_exp_f32_e32 v83, v83
	v_fmaak_f32 v82, v82, v81, 0xbe91a98e
	v_fmaak_f32 v82, v82, v81, 0x3e827906
	v_mul_f32_e32 v81, v81, v82
	v_fma_f32 v80, -v83, v81, 1.0
	v_fma_f32 v79, |v79|, v80, v79
	v_mul_f32_e32 v79, v225, v79
	v_cvt_pk_bf16_f32 v79, v79, s0
	ds_write_b16 v87, v79 offset:816
	v_fma_f32 v80, v215, v140, v218
	v_fmac_f32_e32 v80, v217, v192
	v_fmac_f32_e32 v80, v216, v193
	v_mul_f32_e32 v84, 0x3f596d27, v80
	v_fma_f32 v81, v217, v193, v218
	v_fma_f32 v85, |v84|, s98, 1.0
	v_fmac_f32_e32 v81, v215, v192
	v_fmac_f32_e32 v81, v216, v190
	v_fma_f32 v82, v217, v190, v218
	v_fmac_f32_e32 v82, v215, v193
	v_fmac_f32_e32 v82, v216, v191
	v_fma_f32 v83, v217, v191, v218
	v_fmac_f32_e32 v83, v215, v190
	v_fmac_f32_e32 v83, v216, v138
	v_rcp_f32_e32 v85, v85
	v_mul_f32_e64 v87, |v84|, -|v84|
	v_fmamk_f32 v86, v85, 0x3f87dc22, v206
	v_fmaak_f32 v86, v86, v85, 0x3fb5f0e3
	v_exp_f32_e32 v87, v87
	v_fmaak_f32 v86, v86, v85, 0xbe91a98e
	v_fmaak_f32 v86, v86, v85, 0x3e827906
	v_mul_f32_e32 v85, v85, v86
	v_fma_f32 v84, -v87, v85, 1.0
	v_mul_f32_e32 v80, 0.5, v80
	v_fma_f32 v80, |v80|, v84, v80
	v_mul_f32_e32 v84, 0x3f596d27, v81
	v_fma_f32 v85, |v84|, s98, 1.0
	v_add_u32_e32 v79, 0x2200, v220
	v_mul_f32_e32 v80, v202, v80
	v_add_u32_e32 v88, v222, v79
	v_cvt_pk_bf16_f32 v80, v80, s0
	ds_write_b16 v88, v80
	v_mul_f32_e32 v80, 0.5, v81
	v_rcp_f32_e32 v81, v85
	v_mul_f32_e64 v86, |v84|, -|v84|
	v_fmamk_f32 v85, v81, 0x3f87dc22, v206
	v_fmaak_f32 v85, v85, v81, 0x3fb5f0e3
	v_exp_f32_e32 v86, v86
	v_fmaak_f32 v85, v85, v81, 0xbe91a98e
	v_fmaak_f32 v85, v85, v81, 0x3e827906
	v_mul_f32_e32 v81, v81, v85
	v_fma_f32 v81, -v86, v81, 1.0
	v_fma_f32 v80, |v80|, v81, v80
	v_mul_f32_e32 v81, 0x3f596d27, v82
	v_fma_f32 v84, |v81|, s98, 1.0
	v_mul_f32_e32 v80, v203, v80
	v_cvt_pk_bf16_f32 v80, v80, s0
	ds_write_b16 v88, v80 offset:272
	v_mul_f32_e32 v80, 0.5, v82
	v_rcp_f32_e32 v82, v84
	v_mul_f32_e64 v85, |v81|, -|v81|
	v_fmamk_f32 v84, v82, 0x3f87dc22, v206
	v_fmaak_f32 v84, v84, v82, 0x3fb5f0e3
	v_exp_f32_e32 v85, v85
	v_fmaak_f32 v84, v84, v82, 0xbe91a98e
	v_fmaak_f32 v84, v84, v82, 0x3e827906
	v_mul_f32_e32 v82, v82, v84
	v_fma_f32 v81, -v85, v82, 1.0
	v_fma_f32 v80, |v80|, v81, v80
	v_mul_f32_e32 v81, 0x3f596d27, v83
	v_fma_f32 v82, |v81|, s98, 1.0
	v_mul_f32_e32 v80, v200, v80
	v_cvt_pk_bf16_f32 v80, v80, s0
	ds_write_b16 v88, v80 offset:544
	v_mul_f32_e32 v80, 0.5, v83
	v_rcp_f32_e32 v82, v82
	v_mul_f32_e64 v84, |v81|, -|v81|
	v_fmamk_f32 v83, v82, 0x3f87dc22, v206
	v_fmaak_f32 v83, v83, v82, 0x3fb5f0e3
	v_exp_f32_e32 v84, v84
	v_fmaak_f32 v83, v83, v82, 0xbe91a98e
	v_fmaak_f32 v83, v83, v82, 0x3e827906
	v_mul_f32_e32 v82, v82, v83
	v_fma_f32 v81, -v84, v82, 1.0
	v_fma_f32 v80, |v80|, v81, v80
	v_mul_f32_e32 v80, v201, v80
	v_cvt_pk_bf16_f32 v80, v80, s0
	ds_write_b16 v88, v80 offset:816
	v_fma_f32 v81, v215, v132, v218
	v_fmac_f32_e32 v81, v217, v188
	v_fmac_f32_e32 v81, v216, v189
	v_fma_f32 v82, v217, v189, v218
	v_fmac_f32_e32 v82, v215, v188
	v_mul_f32_e32 v85, 0x3f596d27, v81
	v_fmac_f32_e32 v82, v216, v186
	v_fma_f32 v86, |v85|, s98, 1.0
	v_fma_f32 v83, v217, v186, v218
	v_fmac_f32_e32 v83, v215, v189
	v_fmac_f32_e32 v83, v216, v187
	v_fma_f32 v84, v217, v187, v218
	v_fmac_f32_e32 v84, v215, v186
	s_waitcnt lgkmcnt(14)
; __device__ __forceinline__ u16 f2bf(float f) { return (u16)(pack2(f, f) & 0xffffu); }
; __device__ __forceinline__ float gelu_exact(float x) { return 0.5f * x * (1.0f + erf_f32(x * 0.70710678118654752f)); }
; template <int EPI>
; __device__ __forceinline__ void phase_gemm(const Params& p, const GemmDesc& d, char* shmc) {
;     ...
; #pragma unroll
;       for (int n = 0; n < 2; ++n) {
;         const int col = ewc * 32 + n * 16 + efr;
;         const int ch = ch0 + col;
;         const float w0 = cw[n][0], w1 = cw[n][1], w2 = cw[n][2], cb = cw[n][3];
; #pragma unroll
;         for (int ai = 0; ai < 2; ++ai)
; #pragma unroll
;           for (int m = 0; m < 4; ++m) {
;             const int s = ai * 32 + ewr * 16 + m * 4 + efq;
;             const f32x4 g = acc[ai][0][m][n];
;             const f32x4 v = acc[ai][1][m][n];
;             const float c0 = w0 * gp[ai][m][n] + w1 * g[0] + w2 * g[1] + cb;
;             const float c1 = w0 * g[0] + w1 * g[1] + w2 * g[2] + cb;
;             const float c2 = w0 * g[1] + w1 * g[2] + w2 * g[3] + cb;
;             const float c3 = w0 * g[2] + w1 * g[3] + w2 * gn[ai][m][n] + cb;
;             u16* sp = stg + (s * 4) * 136 + col;
;             sp[0] = f2bf(gelu_exact(c0) * v[0]);
;             sp[136] = f2bf(gelu_exact(c1) * v[1]);
;             sp[272] = f2bf(gelu_exact(c2) * v[2]);
;             sp[408] = f2bf(gelu_exact(c3) * v[3]);
	v_fmac_f32_e32 v84, v216, v130
	v_rcp_f32_e32 v86, v86
	v_mul_f32_e64 v88, |v85|, -|v85|
	v_fmamk_f32 v87, v86, 0x3f87dc22, v206
	v_fmaak_f32 v87, v87, v86, 0x3fb5f0e3
	v_exp_f32_e32 v88, v88
	v_fmaak_f32 v87, v87, v86, 0xbe91a98e
	v_fmaak_f32 v87, v87, v86, 0x3e827906
	v_mul_f32_e32 v86, v86, v87
	v_fma_f32 v85, -v88, v86, 1.0
	v_mul_f32_e32 v81, 0.5, v81
	v_fma_f32 v81, |v81|, v85, v81
	v_mul_f32_e32 v85, 0x3f596d27, v82
	v_fma_f32 v86, |v85|, s98, 1.0
	v_add_u32_e32 v80, 0x3300, v220
	v_mul_f32_e32 v81, v194, v81
	v_add_u32_e32 v89, v222, v80
	v_cvt_pk_bf16_f32 v81, v81, s0
	ds_write_b16 v89, v81
	v_mul_f32_e32 v81, 0.5, v82
	v_rcp_f32_e32 v82, v86
	v_mul_f32_e64 v87, |v85|, -|v85|
	v_fmamk_f32 v86, v82, 0x3f87dc22, v206
	v_fmaak_f32 v86, v86, v82, 0x3fb5f0e3
	v_exp_f32_e32 v87, v87
	v_fmaak_f32 v86, v86, v82, 0xbe91a98e
	v_fmaak_f32 v86, v86, v82, 0x3e827906
	v_mul_f32_e32 v82, v82, v86
	v_fma_f32 v82, -v87, v82, 1.0
	v_fma_f32 v81, |v81|, v82, v81
	v_mul_f32_e32 v82, 0x3f596d27, v83
	v_fma_f32 v85, |v82|, s98, 1.0
	v_mul_f32_e32 v81, v195, v81
	v_cvt_pk_bf16_f32 v81, v81, s0
	ds_write_b16 v89, v81 offset:272
	v_mul_f32_e32 v81, 0.5, v83
	v_rcp_f32_e32 v83, v85
	v_mul_f32_e64 v86, |v82|, -|v82|
	v_fmamk_f32 v85, v83, 0x3f87dc22, v206
	v_fmaak_f32 v85, v85, v83, 0x3fb5f0e3
	v_exp_f32_e32 v86, v86
	v_fmaak_f32 v85, v85, v83, 0xbe91a98e
	v_fmaak_f32 v85, v85, v83, 0x3e827906
	v_mul_f32_e32 v83, v83, v85
	v_fma_f32 v82, -v86, v83, 1.0
	v_fma_f32 v81, |v81|, v82, v81
	v_mul_f32_e32 v82, 0x3f596d27, v84
	v_fma_f32 v83, |v82|, s98, 1.0
	v_mul_f32_e32 v81, v96, v81
	v_cvt_pk_bf16_f32 v81, v81, s0
	ds_write_b16 v89, v81 offset:544
	v_mul_f32_e32 v81, 0.5, v84
	v_rcp_f32_e32 v83, v83
	v_mul_f32_e64 v85, |v82|, -|v82|
	v_fmamk_f32 v84, v83, 0x3f87dc22, v206
	v_fmaak_f32 v84, v84, v83, 0x3fb5f0e3
	v_exp_f32_e32 v85, v85
	v_fmaak_f32 v84, v84, v83, 0xbe91a98e
	v_fmaak_f32 v84, v84, v83, 0x3e827906
	v_mul_f32_e32 v83, v83, v84
	v_fma_f32 v82, -v85, v83, 1.0
	v_fma_f32 v81, |v81|, v82, v81
	v_mul_f32_e32 v81, v97, v81
	v_cvt_pk_bf16_f32 v81, v81, s0
	ds_write_b16 v89, v81 offset:816
	v_fma_f32 v82, v215, v124, v218
	v_fmac_f32_e32 v82, v217, v184
	v_fmac_f32_e32 v82, v216, v185
	v_mul_f32_e32 v86, 0x3f596d27, v82
	v_fma_f32 v83, v217, v185, v218
	v_fma_f32 v87, |v86|, s98, 1.0
	v_fmac_f32_e32 v83, v215, v184
	v_fmac_f32_e32 v83, v216, v182
	v_fma_f32 v84, v217, v182, v218
	v_fmac_f32_e32 v84, v215, v185
	v_fmac_f32_e32 v84, v216, v183
	v_fma_f32 v85, v217, v183, v218
	v_fmac_f32_e32 v85, v215, v182
	v_fmac_f32_e32 v85, v216, v122
	v_rcp_f32_e32 v87, v87
	v_mul_f32_e64 v89, |v86|, -|v86|
	v_fmamk_f32 v88, v87, 0x3f87dc22, v206
	v_fmaak_f32 v88, v88, v87, 0x3fb5f0e3
	v_exp_f32_e32 v89, v89
	v_fmaak_f32 v88, v88, v87, 0xbe91a98e
	v_fmaak_f32 v88, v88, v87, 0x3e827906
	v_mul_f32_e32 v87, v87, v88
	v_fma_f32 v86, -v89, v87, 1.0
	v_mul_f32_e32 v82, 0.5, v82
	v_fma_f32 v82, |v82|, v86, v82
	v_mul_f32_e32 v86, 0x3f596d27, v83
	v_fma_f32 v87, |v86|, s98, 1.0
	v_pk_mul_f32 v[90:91], v[90:91], v[42:43]
	v_add_u32_e32 v81, 0x8800, v220
	v_mul_f32_e32 v82, v90, v82
	v_add_u32_e32 v96, v222, v81
	v_cvt_pk_bf16_f32 v82, v82, s0
	ds_write_b16 v96, v82
	v_mul_f32_e32 v82, 0.5, v83
	v_rcp_f32_e32 v83, v87
	v_mul_f32_e64 v88, |v86|, -|v86|
	v_fmamk_f32 v87, v83, 0x3f87dc22, v206
	v_fmaak_f32 v87, v87, v83, 0x3fb5f0e3
	v_exp_f32_e32 v88, v88
	v_fmaak_f32 v87, v87, v83, 0xbe91a98e
	v_fmaak_f32 v87, v87, v83, 0x3e827906
	v_mul_f32_e32 v83, v83, v87
	v_fma_f32 v83, -v88, v83, 1.0
	v_fma_f32 v82, |v82|, v83, v82
	v_mul_f32_e32 v83, 0x3f596d27, v84
	v_fma_f32 v86, |v83|, s98, 1.0
	v_mul_f32_e32 v82, v91, v82
	v_cvt_pk_bf16_f32 v82, v82, s0
	ds_write_b16 v96, v82 offset:272
	v_mul_f32_e32 v82, 0.5, v84
	v_rcp_f32_e32 v84, v86
	v_mul_f32_e64 v87, |v83|, -|v83|
	v_fmamk_f32 v86, v84, 0x3f87dc22, v206
	v_fmaak_f32 v86, v86, v84, 0x3fb5f0e3
	v_exp_f32_e32 v87, v87
	v_fmaak_f32 v86, v86, v84, 0xbe91a98e
	v_fmaak_f32 v86, v86, v84, 0x3e827906
	v_mul_f32_e32 v84, v84, v86
	v_fma_f32 v83, -v87, v84, 1.0
	v_fma_f32 v82, |v82|, v83, v82
	v_mul_f32_e32 v83, 0x3f596d27, v85
	v_fma_f32 v84, |v83|, s98, 1.0
	v_pk_mul_f32 v[92:93], v[92:93], v[44:45]
	s_nop 0
	v_mul_f32_e32 v82, v92, v82
	v_cvt_pk_bf16_f32 v82, v82, s0
	ds_write_b16 v96, v82 offset:544
	v_mul_f32_e32 v82, 0.5, v85
	v_rcp_f32_e32 v84, v84
	v_mul_f32_e64 v86, |v83|, -|v83|
	v_fmamk_f32 v85, v84, 0x3f87dc22, v206
	v_fmaak_f32 v85, v85, v84, 0x3fb5f0e3
	v_exp_f32_e32 v86, v86
	v_fmaak_f32 v85, v85, v84, 0xbe91a98e
	v_fmaak_f32 v85, v85, v84, 0x3e827906
	v_mul_f32_e32 v84, v84, v85
	v_fma_f32 v83, -v86, v84, 1.0
	v_fma_f32 v82, |v82|, v83, v82
	v_mul_f32_e32 v82, v93, v82
	v_cvt_pk_bf16_f32 v82, v82, s0
	ds_write_b16 v96, v82 offset:816
	v_fma_f32 v83, v215, v116, v218
	v_fmac_f32_e32 v83, v217, v180
	v_fmac_f32_e32 v83, v216, v181
	v_mul_f32_e32 v87, 0x3f596d27, v83
	v_fma_f32 v88, |v87|, s98, 1.0
	v_fma_f32 v84, v217, v181, v218
	v_fmac_f32_e32 v84, v215, v180
	v_fmac_f32_e32 v84, v216, v178
	v_rcp_f32_e32 v88, v88
	v_mul_f32_e64 v90, |v87|, -|v87|
	v_fmamk_f32 v89, v88, 0x3f87dc22, v206
	v_fmaak_f32 v89, v89, v88, 0x3fb5f0e3
	v_exp_f32_e32 v90, v90
	v_fmaak_f32 v89, v89, v88, 0xbe91a98e
	v_fmaak_f32 v89, v89, v88, 0x3e827906
	v_mul_f32_e32 v88, v88, v89
	v_fma_f32 v87, -v90, v88, 1.0
	v_mul_f32_e32 v83, 0.5, v83
	v_fma_f32 v85, v217, v178, v218
	v_fma_f32 v83, |v83|, v87, v83
	v_fmac_f32_e32 v85, v215, v181
	v_mul_f32_e32 v76, v76, v83
	v_mul_f32_e32 v83, 0x3f596d27, v84
	v_fmac_f32_e32 v85, v216, v179
	v_fma_f32 v87, |v83|, s98, 1.0
	v_fma_f32 v86, v217, v179, v218
	v_fmac_f32_e32 v86, v215, v178
	v_fmac_f32_e32 v86, v216, v114
; __device__ __forceinline__ u16 f2bf(float f) { return (u16)(pack2(f, f) & 0xffffu); }
; __device__ __forceinline__ float gelu_exact(float x) { return 0.5f * x * (1.0f + erf_f32(x * 0.70710678118654752f)); }
; template <int EPI>
; __device__ __forceinline__ void phase_gemm(const Params& p, const GemmDesc& d, char* shmc) {
;     ...
; #pragma unroll
;       for (int n = 0; n < 2; ++n) {
;         const int col = ewc * 32 + n * 16 + efr;
;         const int ch = ch0 + col;
;         const float w0 = cw[n][0], w1 = cw[n][1], w2 = cw[n][2], cb = cw[n][3];
; #pragma unroll
;         for (int ai = 0; ai < 2; ++ai)
; #pragma unroll
;           for (int m = 0; m < 4; ++m) {
;             const int s = ai * 32 + ewr * 16 + m * 4 + efq;
;             const f32x4 g = acc[ai][0][m][n];
;             const f32x4 v = acc[ai][1][m][n];
;             const float c0 = w0 * gp[ai][m][n] + w1 * g[0] + w2 * g[1] + cb;
;             const float c1 = w0 * g[0] + w1 * g[1] + w2 * g[2] + cb;
;             const float c2 = w0 * g[1] + w1 * g[2] + w2 * g[3] + cb;
;             const float c3 = w0 * g[2] + w1 * g[3] + w2 * gn[ai][m][n] + cb;
;             u16* sp = stg + (s * 4) * 136 + col;
;             sp[0] = f2bf(gelu_exact(c0) * v[0]);
;             sp[136] = f2bf(gelu_exact(c1) * v[1]);
;             sp[272] = f2bf(gelu_exact(c2) * v[2]);
;             sp[408] = f2bf(gelu_exact(c3) * v[3]);
	v_add_u32_e32 v82, 0x9900, v220
	v_add_u32_e32 v91, v222, v82
	v_cvt_pk_bf16_f32 v76, v76, s0
	ds_write_b16 v91, v76
	v_mul_f32_e32 v76, 0.5, v84
	v_rcp_f32_e32 v84, v87
	v_mul_f32_e64 v88, |v83|, -|v83|
	v_fmamk_f32 v87, v84, 0x3f87dc22, v206
	v_fmaak_f32 v87, v87, v84, 0x3fb5f0e3
	v_exp_f32_e32 v88, v88
	v_fmaak_f32 v87, v87, v84, 0xbe91a98e
	v_fmaak_f32 v87, v87, v84, 0x3e827906
	v_mul_f32_e32 v84, v84, v87
	v_fma_f32 v83, -v88, v84, 1.0
	v_fma_f32 v76, |v76|, v83, v76
	v_mul_f32_e32 v76, v77, v76
	v_mul_f32_e32 v77, 0x3f596d27, v85
	v_fma_f32 v83, |v77|, s98, 1.0
	v_cvt_pk_bf16_f32 v76, v76, s0
	ds_write_b16 v91, v76 offset:272
	v_mul_f32_e32 v76, 0.5, v85
	v_rcp_f32_e32 v83, v83
	v_mul_f32_e64 v85, |v77|, -|v77|
	v_fmamk_f32 v84, v83, 0x3f87dc22, v206
	v_fmaak_f32 v84, v84, v83, 0x3fb5f0e3
	v_exp_f32_e32 v85, v85
	v_fmaak_f32 v84, v84, v83, 0xbe91a98e
	v_fmaak_f32 v84, v84, v83, 0x3e827906
	v_mul_f32_e32 v83, v83, v84
	v_fma_f32 v77, -v85, v83, 1.0
	v_fma_f32 v76, |v76|, v77, v76
	v_mul_f32_e32 v74, v74, v76
	v_mul_f32_e32 v76, 0x3f596d27, v86
	v_fma_f32 v77, |v76|, s98, 1.0
	v_cvt_pk_bf16_f32 v74, v74, s0
	ds_write_b16 v91, v74 offset:544
	v_mul_f32_e32 v74, 0.5, v86
	v_rcp_f32_e32 v77, v77
	v_mul_f32_e64 v84, |v76|, -|v76|
	v_fmamk_f32 v83, v77, 0x3f87dc22, v206
	v_fmaak_f32 v83, v83, v77, 0x3fb5f0e3
	v_exp_f32_e32 v84, v84
	v_fmaak_f32 v83, v83, v77, 0xbe91a98e
	v_fmaak_f32 v83, v83, v77, 0x3e827906
	v_mul_f32_e32 v77, v77, v83
	v_fma_f32 v76, -v84, v77, 1.0
	v_fma_f32 v74, |v74|, v76, v74
	v_mul_f32_e32 v74, v75, v74
	v_cvt_pk_bf16_f32 v74, v74, s0
	ds_write_b16 v91, v74 offset:816
	v_fma_f32 v75, v215, v108, v218
	v_fmac_f32_e32 v75, v217, v160
	v_fmac_f32_e32 v75, v216, v161
	v_mul_f32_e32 v84, 0x3f596d27, v75
	v_fma_f32 v85, |v84|, s98, 1.0
	v_fma_f32 v76, v217, v161, v218
	v_fmac_f32_e32 v76, v215, v160
	v_fmac_f32_e32 v76, v216, v156
	v_rcp_f32_e32 v85, v85
	v_mul_f32_e64 v87, |v84|, -|v84|
	v_fmamk_f32 v86, v85, 0x3f87dc22, v206
	v_fmaak_f32 v86, v86, v85, 0x3fb5f0e3
	v_exp_f32_e32 v87, v87
	v_fmaak_f32 v86, v86, v85, 0xbe91a98e
	v_fmaak_f32 v86, v86, v85, 0x3e827906
	v_mul_f32_e32 v85, v85, v86
	v_fma_f32 v84, -v87, v85, 1.0
	v_mul_f32_e32 v75, 0.5, v75
	v_fma_f32 v77, v217, v156, v218
	v_fma_f32 v75, |v75|, v84, v75
	v_fmac_f32_e32 v77, v215, v161
	v_mul_f32_e32 v72, v72, v75
	v_mul_f32_e32 v75, 0x3f596d27, v76
	v_fmac_f32_e32 v77, v216, v157
	v_fma_f32 v84, |v75|, s98, 1.0
	v_fma_f32 v83, v217, v157, v218
	v_fmac_f32_e32 v83, v215, v156
	v_fmac_f32_e32 v83, v216, v106
	v_add_u32_e32 v74, 0xaa00, v220
	v_add_u32_e32 v88, v222, v74
	v_cvt_pk_bf16_f32 v72, v72, s0
	ds_write_b16 v88, v72
	v_mul_f32_e32 v72, 0.5, v76
	v_rcp_f32_e32 v76, v84
	v_mul_f32_e64 v85, |v75|, -|v75|
	v_fmamk_f32 v84, v76, 0x3f87dc22, v206
	v_fmaak_f32 v84, v84, v76, 0x3fb5f0e3
	v_exp_f32_e32 v85, v85
	v_fmaak_f32 v84, v84, v76, 0xbe91a98e
	v_fmaak_f32 v84, v84, v76, 0x3e827906
	v_mul_f32_e32 v76, v76, v84
	v_fma_f32 v75, -v85, v76, 1.0
	v_fma_f32 v72, |v72|, v75, v72
	v_mul_f32_e32 v72, v73, v72
	v_mul_f32_e32 v73, 0x3f596d27, v77
	v_fma_f32 v75, |v73|, s98, 1.0
	v_cvt_pk_bf16_f32 v72, v72, s0
	ds_write_b16 v88, v72 offset:272
	v_mul_f32_e32 v72, 0.5, v77
	v_rcp_f32_e32 v75, v75
	v_mul_f32_e64 v77, |v73|, -|v73|
	v_fmamk_f32 v76, v75, 0x3f87dc22, v206
	v_fmaak_f32 v76, v76, v75, 0x3fb5f0e3
	v_exp_f32_e32 v77, v77
	v_fmaak_f32 v76, v76, v75, 0xbe91a98e
	v_fmaak_f32 v76, v76, v75, 0x3e827906
	v_mul_f32_e32 v75, v75, v76
	v_fma_f32 v73, -v77, v75, 1.0
	v_fma_f32 v72, |v72|, v73, v72
	v_mul_f32_e32 v70, v70, v72
	v_mul_f32_e32 v72, 0x3f596d27, v83
	v_fma_f32 v73, |v72|, s98, 1.0
	v_cvt_pk_bf16_f32 v70, v70, s0
	ds_write_b16 v88, v70 offset:544
	v_mul_f32_e32 v70, 0.5, v83
	v_rcp_f32_e32 v73, v73
	v_mul_f32_e64 v76, |v72|, -|v72|
	v_fmamk_f32 v75, v73, 0x3f87dc22, v206
	v_fmaak_f32 v75, v75, v73, 0x3fb5f0e3
	v_exp_f32_e32 v76, v76
	v_fmaak_f32 v75, v75, v73, 0xbe91a98e
	v_fmaak_f32 v75, v75, v73, 0x3e827906
	v_mul_f32_e32 v73, v73, v75
	v_fma_f32 v72, -v76, v73, 1.0
	v_fma_f32 v70, |v70|, v72, v70
	v_mul_f32_e32 v70, v71, v70
	v_cvt_pk_bf16_f32 v70, v70, s0
	ds_write_b16 v88, v70 offset:816
	s_waitcnt lgkmcnt(14)
	v_fma_f32 v72, v215, v221, v218
	v_fmac_f32_e32 v72, v217, v154
	v_fmac_f32_e32 v72, v216, v155
	v_mul_f32_e32 v76, 0x3f596d27, v72
	v_fma_f32 v77, |v76|, s98, 1.0
	v_fma_f32 v73, v217, v155, v218
	v_fmac_f32_e32 v73, v215, v154
	v_fmac_f32_e32 v73, v216, v152
	v_rcp_f32_e32 v77, v77
	v_mul_f32_e64 v84, |v76|, -|v76|
	v_fmamk_f32 v83, v77, 0x3f87dc22, v206
	v_fmaak_f32 v83, v83, v77, 0x3fb5f0e3
	v_exp_f32_e32 v84, v84
	v_fmaak_f32 v83, v83, v77, 0xbe91a98e
	v_fmaak_f32 v83, v83, v77, 0x3e827906
	v_mul_f32_e32 v77, v77, v83
	v_fma_f32 v76, -v84, v77, 1.0
	v_mul_f32_e32 v72, 0.5, v72
	v_fma_f32 v75, v217, v152, v218
	v_fma_f32 v72, |v72|, v76, v72
	v_fmac_f32_e32 v75, v215, v155
	v_mul_f32_e32 v68, v68, v72
	v_mul_f32_e32 v72, 0x3f596d27, v73
	v_fmac_f32_e32 v75, v216, v153
	v_fma_f32 v76, |v72|, s98, 1.0
	v_fma_f32 v71, v217, v153, v218
	v_fmac_f32_e32 v71, v215, v152
	v_fmac_f32_e32 v71, v216, v219
	v_add_u32_e32 v70, 0xbb00, v220
	v_add_u32_e32 v85, v222, v70
	v_cvt_pk_bf16_f32 v68, v68, s0
	ds_write_b16 v85, v68
	v_mul_f32_e32 v68, 0.5, v73
	v_rcp_f32_e32 v73, v76
	v_mul_f32_e64 v77, |v72|, -|v72|
	v_fmamk_f32 v76, v73, 0x3f87dc22, v206
	v_fmaak_f32 v76, v76, v73, 0x3fb5f0e3
	v_exp_f32_e32 v77, v77
	v_fmaak_f32 v76, v76, v73, 0xbe91a98e
	v_fmaak_f32 v76, v76, v73, 0x3e827906
	v_mul_f32_e32 v73, v73, v76
	v_fma_f32 v72, -v77, v73, 1.0
	v_fma_f32 v68, |v68|, v72, v68
	v_mul_f32_e32 v68, v69, v68
	v_mul_f32_e32 v69, 0x3f596d27, v75
	v_fma_f32 v72, |v69|, s98, 1.0
	v_cvt_pk_bf16_f32 v68, v68, s0
	ds_write_b16 v85, v68 offset:272
	v_mul_f32_e32 v68, 0.5, v75
	v_rcp_f32_e32 v72, v72
	v_mul_f32_e64 v75, |v69|, -|v69|
	v_fmamk_f32 v73, v72, 0x3f87dc22, v206
	v_fmaak_f32 v73, v73, v72, 0x3fb5f0e3
	v_exp_f32_e32 v75, v75
	v_fmaak_f32 v73, v73, v72, 0xbe91a98e
	v_fmaak_f32 v73, v73, v72, 0x3e827906
	v_mul_f32_e32 v72, v72, v73
	v_fma_f32 v69, -v75, v72, 1.0
	v_fma_f32 v68, |v68|, v69, v68
	v_mul_f32_e32 v66, v66, v68
	v_mul_f32_e32 v68, 0x3f596d27, v71
	v_fma_f32 v69, |v68|, s98, 1.0
	v_cvt_pk_bf16_f32 v66, v66, s0
	ds_write_b16 v85, v66 offset:544
	v_mul_f32_e32 v66, 0.5, v71
	v_rcp_f32_e32 v69, v69
	v_mul_f32_e64 v73, |v68|, -|v68|
	v_fmamk_f32 v72, v69, 0x3f87dc22, v206
	v_fmaak_f32 v72, v72, v69, 0x3fb5f0e3
	v_exp_f32_e32 v73, v73
	v_fmaak_f32 v72, v72, v69, 0xbe91a98e
	v_fmaak_f32 v72, v72, v69, 0x3e827906
	v_mul_f32_e32 v69, v69, v72
	v_fma_f32 v68, -v73, v69, 1.0
	v_fma_f32 v66, |v66|, v68, v66
	v_mul_f32_e32 v66, v67, v66
	v_cvt_pk_bf16_f32 v66, v66, s0
	ds_write_b16 v85, v66 offset:816
	s_and_saveexec_b64 s[58:59], s[8:9]
	s_cbranch_execz .LBB0_1168
; __device__ __forceinline__ u16 f2bf(float f) { return (u16)(pack2(f, f) & 0xffffu); }
; __device__ __forceinline__ float gelu_exact(float x) { return 0.5f * x * (1.0f + erf_f32(x * 0.70710678118654752f)); }
; template <int EPI>
; __device__ __forceinline__ void phase_gemm(const Params& p, const GemmDesc& d, char* shmc) {
;     ...
; #pragma unroll
;       for (int n = 0; n < 2; ++n) {
;         const int col = ewc * 32 + n * 16 + efr;
;         const int ch = ch0 + col;
;         const float w0 = cw[n][0], w1 = cw[n][1], w2 = cw[n][2], cb = cw[n][3];
; #pragma unroll
;         for (int ai = 0; ai < 2; ++ai)
; #pragma unroll
;           for (int m = 0; m < 4; ++m) {
;             const int s = ai * 32 + ewr * 16 + m * 4 + efq;
;             const f32x4 g = acc[ai][0][m][n];
;             const f32x4 v = acc[ai][1][m][n];
;             const float c0 = w0 * gp[ai][m][n] + w1 * g[0] + w2 * g[1] + cb;
;             const float c1 = w0 * g[0] + w1 * g[1] + w2 * g[2] + cb;
;             const float c2 = w0 * g[1] + w1 * g[2] + w2 * g[3] + cb;
;             const float c3 = w0 * g[2] + w1 * g[3] + w2 * gn[ai][m][n] + cb;
;             u16* sp = stg + (s * 4) * 136 + col;
;             sp[0] = f2bf(gelu_exact(c0) * v[0]);
;             sp[136] = f2bf(gelu_exact(c1) * v[1]);
;             sp[272] = f2bf(gelu_exact(c2) * v[2]);
;             sp[408] = f2bf(gelu_exact(c3) * v[3]);
;             if (s == 0) {
;               edge[0 * DFF + ch] = c0; edge[1 * DFF + ch] = g[0]; edge[2 * DFF + ch] = v[0];
;             }
;             if (s == 63) {
;               edge[3 * DFF + ch] = c3; edge[4 * DFF + ch] = g[3]; edge[5 * DFF + ch] = v[3];
;             }
;           }
	v_add_co_u32_e32 v68, vcc, 0x10000, v94
	s_nop 1
	v_addc_co_u32_e32 v69, vcc, 0, v95, vcc
	global_store_dword v[68:69], v71, off offset:2048
	v_add_co_u32_e32 v68, vcc, 0x16000, v94
	s_nop 1
	v_addc_co_u32_e32 v69, vcc, 0, v95, vcc
	global_store_dword v[68:69], v153, off
	v_add_co_u32_e32 v68, vcc, 0x1b000, v94
	s_nop 1
	v_addc_co_u32_e32 v69, vcc, 0, v95, vcc
	global_store_dword v[68:69], v67, off offset:2048
.LBB0_1168:
	s_or_b64 exec, exec, s[58:59]
	v_pk_mul_f32 v[64:65], v[60:61], v[64:65]
	v_pk_mul_f32 v[60:61], v[58:59], v[62:63]
	v_fma_f32 v63, v208, v213, v207
	v_fmac_f32_e32 v63, v210, v146
	v_fmac_f32_e32 v63, v209, v147
	v_mul_f32_e32 v71, 0x3f596d27, v63
	v_fma_f32 v72, |v71|, s98, 1.0
	v_fma_f32 v67, v210, v147, v207
	v_fmac_f32_e32 v67, v208, v146
	v_fmac_f32_e32 v67, v209, v158
	v_rcp_f32_e32 v72, v72
	v_mul_f32_e64 v75, |v71|, -|v71|
	v_fmamk_f32 v73, v72, 0x3f87dc22, v206
	v_fmaak_f32 v73, v73, v72, 0x3fb5f0e3
	v_exp_f32_e32 v75, v75
	v_fmaak_f32 v73, v73, v72, 0xbe91a98e
	v_fmaak_f32 v73, v73, v72, 0x3e827906
	v_mul_f32_e32 v72, v72, v73
	v_fma_f32 v68, v210, v158, v207
	v_fma_f32 v71, -v75, v72, 1.0
	v_fmac_f32_e32 v68, v208, v147
	v_mul_f32_e32 v72, 0x3f596d27, v67
	v_fmac_f32_e32 v68, v209, v159
	v_fma_f32 v73, |v72|, s98, 1.0
	v_fma_f32 v69, v210, v159, v207
	v_mul_f32_e32 v76, 0.5, v63
	v_fmac_f32_e32 v69, v208, v158
	v_fma_f32 v71, |v76|, v71, v76
	v_or_b32_e32 v66, 16, v162
	v_fmac_f32_e32 v69, v209, v214
	v_lshlrev_b32_e32 v62, 1, v66
	v_mul_f32_e32 v71, v60, v71
	v_add3_u32 v66, s14, v220, v62
	v_cvt_pk_bf16_f32 v71, v71, s0
	ds_write_b16 v66, v71
	v_rcp_f32_e32 v71, v73
	v_mul_f32_e64 v75, |v72|, -|v72|
	v_fmamk_f32 v73, v71, 0x3f87dc22, v206
	v_fmaak_f32 v73, v73, v71, 0x3fb5f0e3
	v_exp_f32_e32 v75, v75
	v_fmaak_f32 v73, v73, v71, 0xbe91a98e
	v_fmaak_f32 v73, v73, v71, 0x3e827906
	v_mul_f32_e32 v71, v71, v73
	v_fma_f32 v71, -v75, v71, 1.0
	v_mul_f32_e32 v67, 0.5, v67
	v_fma_f32 v67, |v67|, v71, v67
	v_mul_f32_e32 v61, v61, v67
	v_mul_f32_e32 v67, 0x3f596d27, v68
	v_fma_f32 v71, |v67|, s98, 1.0
	v_cvt_pk_bf16_f32 v61, v61, s0
	ds_write_b16 v66, v61 offset:272
	v_mul_f32_e32 v61, 0.5, v68
	v_rcp_f32_e32 v68, v71
	v_mul_f32_e64 v72, |v67|, -|v67|
	v_fmamk_f32 v71, v68, 0x3f87dc22, v206
	v_fmaak_f32 v71, v71, v68, 0x3fb5f0e3
	v_exp_f32_e32 v72, v72
	v_fmaak_f32 v71, v71, v68, 0xbe91a98e
	v_fmaak_f32 v71, v71, v68, 0x3e827906
	v_mul_f32_e32 v68, v68, v71
	v_fma_f32 v67, -v72, v68, 1.0
	v_fma_f32 v61, |v61|, v67, v61
	v_mul_f32_e32 v61, v64, v61
	v_mul_f32_e32 v64, 0x3f596d27, v69
	v_fma_f32 v67, |v64|, s98, 1.0
	v_cvt_pk_bf16_f32 v61, v61, s0
	ds_write_b16 v66, v61 offset:544
	v_mul_f32_e32 v61, 0.5, v69
	v_rcp_f32_e32 v67, v67
	v_mul_f32_e64 v69, |v64|, -|v64|
	v_fmamk_f32 v68, v67, 0x3f87dc22, v206
	v_fmaak_f32 v68, v68, v67, 0x3fb5f0e3
	v_exp_f32_e32 v69, v69
	v_fmaak_f32 v68, v68, v67, 0xbe91a98e
	v_fmaak_f32 v68, v68, v67, 0x3e827906
	v_mul_f32_e32 v67, v67, v68
	v_fma_f32 v64, -v69, v67, 1.0
	s_ashr_i32 s55, s54, 31
	v_lshl_add_u64 v[58:59], v[162:163], 0, s[54:55]
	v_fma_f32 v61, |v61|, v64, v61
	v_lshl_add_u64 v[58:59], v[58:59], 2, s[56:57]
	v_mul_f32_e32 v61, v65, v61
	v_lshl_add_u64 v[58:59], v[58:59], 0, 64
	v_cvt_pk_bf16_f32 v61, v61, s0
	ds_write_b16 v66, v61 offset:816
	s_and_saveexec_b64 s[56:57], s[10:11]
	s_cbranch_execz .LBB0_1170
	v_add_co_u32_e32 v64, vcc, 0x5000, v58
	global_store_dword v[58:59], v63, off
	s_nop 0
	v_addc_co_u32_e32 v65, vcc, 0, v59, vcc
	global_store_dword v[64:65], v146, off offset:2048
	v_add_co_u32_e32 v64, vcc, 0xb000, v58
	s_nop 1
	v_addc_co_u32_e32 v65, vcc, 0, v59, vcc
	global_store_dword v[64:65], v60, off
.LBB0_1170:
	s_or_b64 exec, exec, s[56:57]
	v_pk_mul_f32 v[48:49], v[4:5], v[48:49]
	v_pk_mul_f32 v[4:5], v[14:15], v[30:31]
	v_fma_f32 v14, v208, v151, v207
	v_fmac_f32_e32 v14, v210, v144
	v_fmac_f32_e32 v14, v209, v145
	v_pk_mul_f32 v[52:53], v[8:9], v[52:53]
	v_pk_mul_f32 v[8:9], v[18:19], v[34:35]
	v_mul_f32_e32 v18, 0x3f596d27, v14
	v_fma_f32 v19, |v18|, s98, 1.0
	v_pk_mul_f32 v[50:51], v[6:7], v[50:51]
	v_pk_mul_f32 v[6:7], v[20:21], v[36:37]
	v_pk_mul_f32 v[56:57], v[12:13], v[56:57]
	v_pk_mul_f32 v[12:13], v[22:23], v[38:39]
	v_pk_mul_f32 v[54:55], v[10:11], v[54:55]
	v_pk_mul_f32 v[10:11], v[24:25], v[40:41]
	v_rcp_f32_e32 v19, v19
	v_mul_f32_e64 v21, |v18|, -|v18|
	v_fmamk_f32 v20, v19, 0x3f87dc22, v206
	v_fmaak_f32 v20, v20, v19, 0x3fb5f0e3
	v_exp_f32_e32 v21, v21
	v_fmaak_f32 v20, v20, v19, 0xbe91a98e
	v_fmaak_f32 v20, v20, v19, 0x3e827906
	v_fma_f32 v15, v210, v145, v207
	v_mul_f32_e32 v19, v19, v20
	v_fmac_f32_e32 v15, v208, v144
	v_fma_f32 v18, -v21, v19, 1.0
	v_fmac_f32_e32 v15, v209, v142
	v_mul_f32_e32 v14, 0.5, v14
	v_fma_f32 v14, |v14|, v18, v14
	v_mul_f32_e32 v18, 0x3f596d27, v15
	v_fma_f32 v19, |v18|, s98, 1.0
	v_mul_f32_e32 v14, v54, v14
	v_add3_u32 v22, s14, v78, v62
	v_cvt_pk_bf16_f32 v14, v14, s0
	ds_write_b16 v22, v14
	v_mul_f32_e32 v14, 0.5, v15
	v_rcp_f32_e32 v15, v19
	v_mul_f32_e64 v20, |v18|, -|v18|
	v_fmamk_f32 v19, v15, 0x3f87dc22, v206
	v_fmaak_f32 v19, v19, v15, 0x3fb5f0e3
	v_exp_f32_e32 v20, v20
	v_fmaak_f32 v19, v19, v15, 0xbe91a98e
	v_fmaak_f32 v19, v19, v15, 0x3e827906
	v_pk_mul_f32 v[46:47], v[2:3], v[46:47]
	v_pk_mul_f32 v[2:3], v[16:17], v[32:33]
	v_fma_f32 v16, v210, v142, v207
	v_mul_f32_e32 v15, v15, v19
	v_fmac_f32_e32 v16, v208, v145
	v_fma_f32 v15, -v20, v15, 1.0
	v_fmac_f32_e32 v16, v209, v143
	v_fma_f32 v14, |v14|, v15, v14
	v_mul_f32_e32 v15, 0x3f596d27, v16
	v_fma_f32 v18, |v15|, s98, 1.0
	v_mul_f32_e32 v14, v55, v14
	v_cvt_pk_bf16_f32 v14, v14, s0
	ds_write_b16 v22, v14 offset:272
	v_mul_f32_e32 v14, 0.5, v16
; __device__ __forceinline__ u16 f2bf(float f) { return (u16)(pack2(f, f) & 0xffffu); }
; __device__ __forceinline__ float gelu_exact(float x) { return 0.5f * x * (1.0f + erf_f32(x * 0.70710678118654752f)); }
; template <int EPI>
; __device__ __forceinline__ void phase_gemm(const Params& p, const GemmDesc& d, char* shmc) {
;     ...
; #pragma unroll
;       for (int n = 0; n < 2; ++n) {
;         const int col = ewc * 32 + n * 16 + efr;
;         const int ch = ch0 + col;
;         const float w0 = cw[n][0], w1 = cw[n][1], w2 = cw[n][2], cb = cw[n][3];
; #pragma unroll
;         for (int ai = 0; ai < 2; ++ai)
; #pragma unroll
;           for (int m = 0; m < 4; ++m) {
;             const int s = ai * 32 + ewr * 16 + m * 4 + efq;
;             const f32x4 g = acc[ai][0][m][n];
;             const f32x4 v = acc[ai][1][m][n];
;             const float c0 = w0 * gp[ai][m][n] + w1 * g[0] + w2 * g[1] + cb;
;             const float c1 = w0 * g[0] + w1 * g[1] + w2 * g[2] + cb;
;             const float c2 = w0 * g[1] + w1 * g[2] + w2 * g[3] + cb;
;             const float c3 = w0 * g[2] + w1 * g[3] + w2 * gn[ai][m][n] + cb;
;             u16* sp = stg + (s * 4) * 136 + col;
;             sp[0] = f2bf(gelu_exact(c0) * v[0]);
;             sp[136] = f2bf(gelu_exact(c1) * v[1]);
;             sp[272] = f2bf(gelu_exact(c2) * v[2]);
;             sp[408] = f2bf(gelu_exact(c3) * v[3]);
	v_rcp_f32_e32 v16, v18
	v_mul_f32_e64 v19, |v15|, -|v15|
	v_fmamk_f32 v18, v16, 0x3f87dc22, v206
	v_fmaak_f32 v18, v18, v16, 0x3fb5f0e3
	v_exp_f32_e32 v19, v19
	v_fmaak_f32 v18, v18, v16, 0xbe91a98e
	v_fmaak_f32 v18, v18, v16, 0x3e827906
	v_fma_f32 v17, v210, v143, v207
	v_mul_f32_e32 v16, v16, v18
	v_fmac_f32_e32 v17, v208, v142
	v_fma_f32 v15, -v19, v16, 1.0
	v_fmac_f32_e32 v17, v209, v149
	v_fma_f32 v14, |v14|, v15, v14
	v_mul_f32_e32 v15, 0x3f596d27, v17
	v_fma_f32 v16, |v15|, s98, 1.0
	v_mul_f32_e32 v14, v56, v14
	v_cvt_pk_bf16_f32 v14, v14, s0
	ds_write_b16 v22, v14 offset:544
	v_mul_f32_e32 v14, 0.5, v17
	v_rcp_f32_e32 v16, v16
	v_mul_f32_e64 v18, |v15|, -|v15|
	v_fmamk_f32 v17, v16, 0x3f87dc22, v206
	v_fmaak_f32 v17, v17, v16, 0x3fb5f0e3
	v_exp_f32_e32 v18, v18
	v_fmaak_f32 v17, v17, v16, 0xbe91a98e
	v_fmaak_f32 v17, v17, v16, 0x3e827906
	v_mul_f32_e32 v16, v16, v17
	v_fma_f32 v15, -v18, v16, 1.0
	v_fma_f32 v14, |v14|, v15, v14
	v_mul_f32_e32 v14, v57, v14
	v_cvt_pk_bf16_f32 v14, v14, s0
	ds_write_b16 v22, v14 offset:816
	v_fma_f32 v14, v208, v141, v207
	v_fmac_f32_e32 v14, v210, v136
	v_fmac_f32_e32 v14, v209, v137
	v_mul_f32_e32 v18, 0x3f596d27, v14
	v_fma_f32 v19, |v18|, s98, 1.0
	v_fma_f32 v15, v210, v137, v207
	v_fmac_f32_e32 v15, v208, v136
	v_fmac_f32_e32 v15, v209, v134
	v_rcp_f32_e32 v19, v19
	v_mul_f32_e64 v21, |v18|, -|v18|
	v_fmamk_f32 v20, v19, 0x3f87dc22, v206
	v_fmaak_f32 v20, v20, v19, 0x3fb5f0e3
	v_exp_f32_e32 v21, v21
	v_fmaak_f32 v20, v20, v19, 0xbe91a98e
	v_fmaak_f32 v20, v20, v19, 0x3e827906
	v_mul_f32_e32 v19, v19, v20
	v_fma_f32 v18, -v21, v19, 1.0
	v_mul_f32_e32 v14, 0.5, v14
	v_fma_f32 v14, |v14|, v18, v14
	v_mul_f32_e32 v18, 0x3f596d27, v15
	v_fma_f32 v19, |v18|, s98, 1.0
	v_mul_f32_e32 v14, v50, v14
	v_add3_u32 v22, s14, v79, v62
	v_cvt_pk_bf16_f32 v14, v14, s0
	ds_write_b16 v22, v14
	v_mul_f32_e32 v14, 0.5, v15
	v_rcp_f32_e32 v15, v19
	v_mul_f32_e64 v20, |v18|, -|v18|
	v_fmamk_f32 v19, v15, 0x3f87dc22, v206
	v_fmaak_f32 v19, v19, v15, 0x3fb5f0e3
	v_exp_f32_e32 v20, v20
	v_fmaak_f32 v19, v19, v15, 0xbe91a98e
	v_fmaak_f32 v19, v19, v15, 0x3e827906
	v_fma_f32 v16, v210, v134, v207
	v_mul_f32_e32 v15, v15, v19
	v_fmac_f32_e32 v16, v208, v137
	v_fma_f32 v15, -v20, v15, 1.0
	v_fmac_f32_e32 v16, v209, v135
	v_fma_f32 v14, |v14|, v15, v14
	v_mul_f32_e32 v15, 0x3f596d27, v16
	v_fma_f32 v18, |v15|, s98, 1.0
	v_mul_f32_e32 v14, v51, v14
	v_cvt_pk_bf16_f32 v14, v14, s0
	ds_write_b16 v22, v14 offset:272
	v_mul_f32_e32 v14, 0.5, v16
	v_rcp_f32_e32 v16, v18
	v_mul_f32_e64 v19, |v15|, -|v15|
	v_fmamk_f32 v18, v16, 0x3f87dc22, v206
	v_fmaak_f32 v18, v18, v16, 0x3fb5f0e3
	v_exp_f32_e32 v19, v19
	v_fmaak_f32 v18, v18, v16, 0xbe91a98e
	v_fmaak_f32 v18, v18, v16, 0x3e827906
	v_fma_f32 v17, v210, v135, v207
	v_mul_f32_e32 v16, v16, v18
	v_fmac_f32_e32 v17, v208, v134
	v_fma_f32 v15, -v19, v16, 1.0
	v_fmac_f32_e32 v17, v209, v139
	v_fma_f32 v14, |v14|, v15, v14
	v_mul_f32_e32 v15, 0x3f596d27, v17
	v_fma_f32 v16, |v15|, s98, 1.0
	v_mul_f32_e32 v14, v52, v14
	v_cvt_pk_bf16_f32 v14, v14, s0
	ds_write_b16 v22, v14 offset:544
	v_mul_f32_e32 v14, 0.5, v17
	v_rcp_f32_e32 v16, v16
	v_mul_f32_e64 v18, |v15|, -|v15|
	v_fmamk_f32 v17, v16, 0x3f87dc22, v206
	v_fmaak_f32 v17, v17, v16, 0x3fb5f0e3
	v_exp_f32_e32 v18, v18
	v_fmaak_f32 v17, v17, v16, 0xbe91a98e
	v_fmaak_f32 v17, v17, v16, 0x3e827906
	v_mul_f32_e32 v16, v16, v17
	v_fma_f32 v15, -v18, v16, 1.0
	v_fma_f32 v14, |v14|, v15, v14
	v_mul_f32_e32 v14, v53, v14
	v_cvt_pk_bf16_f32 v14, v14, s0
	ds_write_b16 v22, v14 offset:816
	v_fma_f32 v14, v208, v133, v207
	v_fmac_f32_e32 v14, v210, v128
	v_fmac_f32_e32 v14, v209, v129
	v_mul_f32_e32 v18, 0x3f596d27, v14
	v_fma_f32 v19, |v18|, s98, 1.0
	v_fma_f32 v15, v210, v129, v207
	v_fmac_f32_e32 v15, v208, v128
	v_fmac_f32_e32 v15, v209, v126
	v_rcp_f32_e32 v19, v19
	v_mul_f32_e64 v21, |v18|, -|v18|
	v_fmamk_f32 v20, v19, 0x3f87dc22, v206
	v_fmaak_f32 v20, v20, v19, 0x3fb5f0e3
	v_exp_f32_e32 v21, v21
	v_fmaak_f32 v20, v20, v19, 0xbe91a98e
	v_fmaak_f32 v20, v20, v19, 0x3e827906
	v_mul_f32_e32 v19, v19, v20
	v_fma_f32 v18, -v21, v19, 1.0
	v_mul_f32_e32 v14, 0.5, v14
	v_fma_f32 v14, |v14|, v18, v14
	v_mul_f32_e32 v18, 0x3f596d27, v15
	v_fma_f32 v19, |v18|, s98, 1.0
	v_mul_f32_e32 v14, v46, v14
	v_add3_u32 v22, s14, v80, v62
	v_cvt_pk_bf16_f32 v14, v14, s0
	ds_write_b16 v22, v14
	v_mul_f32_e32 v14, 0.5, v15
	v_rcp_f32_e32 v15, v19
	v_mul_f32_e64 v20, |v18|, -|v18|
	v_fmamk_f32 v19, v15, 0x3f87dc22, v206
	v_fmaak_f32 v19, v19, v15, 0x3fb5f0e3
	v_exp_f32_e32 v20, v20
	v_fmaak_f32 v19, v19, v15, 0xbe91a98e
	v_fmaak_f32 v19, v19, v15, 0x3e827906
	v_fma_f32 v16, v210, v126, v207
	v_mul_f32_e32 v15, v15, v19
	v_fmac_f32_e32 v16, v208, v129
	v_fma_f32 v15, -v20, v15, 1.0
	v_fmac_f32_e32 v16, v209, v127
	v_fma_f32 v14, |v14|, v15, v14
	v_mul_f32_e32 v15, 0x3f596d27, v16
	v_fma_f32 v18, |v15|, s98, 1.0
	v_mul_f32_e32 v14, v47, v14
	v_cvt_pk_bf16_f32 v14, v14, s0
	ds_write_b16 v22, v14 offset:272
	v_mul_f32_e32 v14, 0.5, v16
	v_rcp_f32_e32 v16, v18
	v_mul_f32_e64 v19, |v15|, -|v15|
	v_fmamk_f32 v18, v16, 0x3f87dc22, v206
	v_fmaak_f32 v18, v18, v16, 0x3fb5f0e3
	v_exp_f32_e32 v19, v19
	v_fmaak_f32 v18, v18, v16, 0xbe91a98e
	v_fmaak_f32 v18, v18, v16, 0x3e827906
	v_fma_f32 v17, v210, v127, v207
	v_mul_f32_e32 v16, v16, v18
	v_fmac_f32_e32 v17, v208, v126
	v_fma_f32 v15, -v19, v16, 1.0
	v_fmac_f32_e32 v17, v209, v131
	v_fma_f32 v14, |v14|, v15, v14
	v_mul_f32_e32 v15, 0x3f596d27, v17
	v_fma_f32 v16, |v15|, s98, 1.0
	v_mul_f32_e32 v14, v48, v14
	v_cvt_pk_bf16_f32 v14, v14, s0
	ds_write_b16 v22, v14 offset:544
	v_mul_f32_e32 v14, 0.5, v17
	v_rcp_f32_e32 v16, v16
; __device__ __forceinline__ u16 f2bf(float f) { return (u16)(pack2(f, f) & 0xffffu); }
; __device__ __forceinline__ float gelu_exact(float x) { return 0.5f * x * (1.0f + erf_f32(x * 0.70710678118654752f)); }
; template <int EPI>
; __device__ __forceinline__ void phase_gemm(const Params& p, const GemmDesc& d, char* shmc) {
;     ...
; #pragma unroll
;       for (int n = 0; n < 2; ++n) {
;         const int col = ewc * 32 + n * 16 + efr;
;         const int ch = ch0 + col;
;         const float w0 = cw[n][0], w1 = cw[n][1], w2 = cw[n][2], cb = cw[n][3];
; #pragma unroll
;         for (int ai = 0; ai < 2; ++ai)
; #pragma unroll
;           for (int m = 0; m < 4; ++m) {
;             const int s = ai * 32 + ewr * 16 + m * 4 + efq;
;             const f32x4 g = acc[ai][0][m][n];
;             const f32x4 v = acc[ai][1][m][n];
;             const float c0 = w0 * gp[ai][m][n] + w1 * g[0] + w2 * g[1] + cb;
;             const float c1 = w0 * g[0] + w1 * g[1] + w2 * g[2] + cb;
;             const float c2 = w0 * g[1] + w1 * g[2] + w2 * g[3] + cb;
;             const float c3 = w0 * g[2] + w1 * g[3] + w2 * gn[ai][m][n] + cb;
;             u16* sp = stg + (s * 4) * 136 + col;
;             sp[0] = f2bf(gelu_exact(c0) * v[0]);
;             sp[136] = f2bf(gelu_exact(c1) * v[1]);
;             sp[272] = f2bf(gelu_exact(c2) * v[2]);
;             sp[408] = f2bf(gelu_exact(c3) * v[3]);
	v_mul_f32_e64 v18, |v15|, -|v15|
	v_fmamk_f32 v17, v16, 0x3f87dc22, v206
	v_fmaak_f32 v17, v17, v16, 0x3fb5f0e3
	v_exp_f32_e32 v18, v18
	v_fmaak_f32 v17, v17, v16, 0xbe91a98e
	v_fmaak_f32 v17, v17, v16, 0x3e827906
	v_mul_f32_e32 v16, v16, v17
	v_fma_f32 v15, -v18, v16, 1.0
	v_fma_f32 v14, |v14|, v15, v14
	v_mul_f32_e32 v14, v49, v14
	v_cvt_pk_bf16_f32 v14, v14, s0
	ds_write_b16 v22, v14 offset:816
	v_fma_f32 v14, v208, v125, v207
	v_fmac_f32_e32 v14, v210, v120
	v_fmac_f32_e32 v14, v209, v121
	v_mul_f32_e32 v18, 0x3f596d27, v14
	v_fma_f32 v19, |v18|, s98, 1.0
	v_fma_f32 v15, v210, v121, v207
	v_fmac_f32_e32 v15, v208, v120
	v_fmac_f32_e32 v15, v209, v118
	v_rcp_f32_e32 v19, v19
	v_mul_f32_e64 v21, |v18|, -|v18|
	v_fmamk_f32 v20, v19, 0x3f87dc22, v206
	v_fmaak_f32 v20, v20, v19, 0x3fb5f0e3
	v_exp_f32_e32 v21, v21
	v_fmaak_f32 v20, v20, v19, 0xbe91a98e
	v_fmaak_f32 v20, v20, v19, 0x3e827906
	v_mul_f32_e32 v19, v19, v20
	v_fma_f32 v18, -v21, v19, 1.0
	v_mul_f32_e32 v14, 0.5, v14
	v_fma_f32 v14, |v14|, v18, v14
	v_mul_f32_e32 v18, 0x3f596d27, v15
	v_fma_f32 v19, |v18|, s98, 1.0
	v_pk_mul_f32 v[26:27], v[26:27], v[42:43]
	v_add3_u32 v22, s14, v81, v62
	v_mul_f32_e32 v14, v26, v14
	v_cvt_pk_bf16_f32 v14, v14, s0
	ds_write_b16 v22, v14
	v_mul_f32_e32 v14, 0.5, v15
	v_rcp_f32_e32 v15, v19
	v_mul_f32_e64 v20, |v18|, -|v18|
	v_fmamk_f32 v19, v15, 0x3f87dc22, v206
	v_fmaak_f32 v19, v19, v15, 0x3fb5f0e3
	v_exp_f32_e32 v20, v20
	v_fmaak_f32 v19, v19, v15, 0xbe91a98e
	v_fmaak_f32 v19, v19, v15, 0x3e827906
	v_fma_f32 v16, v210, v118, v207
	v_mul_f32_e32 v15, v15, v19
	v_fmac_f32_e32 v16, v208, v121
	v_fma_f32 v15, -v20, v15, 1.0
	v_fmac_f32_e32 v16, v209, v119
	v_fma_f32 v14, |v14|, v15, v14
	v_mul_f32_e32 v15, 0x3f596d27, v16
	v_fma_f32 v18, |v15|, s98, 1.0
	v_mul_f32_e32 v14, v27, v14
	v_cvt_pk_bf16_f32 v14, v14, s0
	ds_write_b16 v22, v14 offset:272
	v_mul_f32_e32 v14, 0.5, v16
	v_rcp_f32_e32 v16, v18
	v_mul_f32_e64 v19, |v15|, -|v15|
	v_fmamk_f32 v18, v16, 0x3f87dc22, v206
	v_fmaak_f32 v18, v18, v16, 0x3fb5f0e3
	v_exp_f32_e32 v19, v19
	v_fmaak_f32 v18, v18, v16, 0xbe91a98e
	v_fmaak_f32 v18, v18, v16, 0x3e827906
	v_fma_f32 v17, v210, v119, v207
	v_mul_f32_e32 v16, v16, v18
	v_fmac_f32_e32 v17, v208, v118
	v_fma_f32 v15, -v19, v16, 1.0
	v_fmac_f32_e32 v17, v209, v123
	v_fma_f32 v14, |v14|, v15, v14
	v_mul_f32_e32 v15, 0x3f596d27, v17
	v_fma_f32 v16, |v15|, s98, 1.0
	v_pk_mul_f32 v[28:29], v[28:29], v[44:45]
	s_nop 0
	v_mul_f32_e32 v14, v28, v14
	v_cvt_pk_bf16_f32 v14, v14, s0
	ds_write_b16 v22, v14 offset:544
	v_mul_f32_e32 v14, 0.5, v17
	v_rcp_f32_e32 v16, v16
	v_mul_f32_e64 v18, |v15|, -|v15|
	v_fmamk_f32 v17, v16, 0x3f87dc22, v206
	v_fmaak_f32 v17, v17, v16, 0x3fb5f0e3
	v_exp_f32_e32 v18, v18
	v_fmaak_f32 v17, v17, v16, 0xbe91a98e
	v_fmaak_f32 v17, v17, v16, 0x3e827906
	v_mul_f32_e32 v16, v16, v17
	v_fma_f32 v15, -v18, v16, 1.0
	v_fma_f32 v14, |v14|, v15, v14
	v_mul_f32_e32 v14, v29, v14
	v_cvt_pk_bf16_f32 v14, v14, s0
	ds_write_b16 v22, v14 offset:816
	v_fma_f32 v14, v208, v117, v207
	v_fmac_f32_e32 v14, v210, v112
	v_fmac_f32_e32 v14, v209, v113
	v_mul_f32_e32 v18, 0x3f596d27, v14
	v_fma_f32 v19, |v18|, s98, 1.0
	v_fma_f32 v15, v210, v113, v207
	v_fmac_f32_e32 v15, v208, v112
	v_fmac_f32_e32 v15, v209, v110
	v_rcp_f32_e32 v19, v19
	v_mul_f32_e64 v21, |v18|, -|v18|
	v_fmamk_f32 v20, v19, 0x3f87dc22, v206
	v_fmaak_f32 v20, v20, v19, 0x3fb5f0e3
	v_exp_f32_e32 v21, v21
	v_fmaak_f32 v20, v20, v19, 0xbe91a98e
	v_fmaak_f32 v20, v20, v19, 0x3e827906
	v_mul_f32_e32 v19, v19, v20
	v_fma_f32 v18, -v21, v19, 1.0
	v_mul_f32_e32 v14, 0.5, v14
	v_fma_f32 v14, |v14|, v18, v14
	v_mul_f32_e32 v12, v12, v14
	v_mul_f32_e32 v14, 0x3f596d27, v15
	v_fma_f32 v18, |v14|, s98, 1.0
	v_add3_u32 v22, s14, v82, v62
	v_cvt_pk_bf16_f32 v12, v12, s0
	ds_write_b16 v22, v12
	v_mul_f32_e32 v12, 0.5, v15
	v_rcp_f32_e32 v15, v18
	v_mul_f32_e64 v19, |v14|, -|v14|
	v_fmamk_f32 v18, v15, 0x3f87dc22, v206
	v_fmaak_f32 v18, v18, v15, 0x3fb5f0e3
	v_exp_f32_e32 v19, v19
	v_fmaak_f32 v18, v18, v15, 0xbe91a98e
	v_fmaak_f32 v18, v18, v15, 0x3e827906
	v_mul_f32_e32 v15, v15, v18
	v_fma_f32 v16, v210, v110, v207
	v_fma_f32 v14, -v19, v15, 1.0
	v_fmac_f32_e32 v16, v208, v113
	v_fmac_f32_e32 v16, v209, v111
	v_fma_f32 v12, |v12|, v14, v12
	v_mul_f32_e32 v12, v13, v12
	v_mul_f32_e32 v13, 0x3f596d27, v16
	v_fma_f32 v14, |v13|, s98, 1.0
	v_cvt_pk_bf16_f32 v12, v12, s0
	ds_write_b16 v22, v12 offset:272
	v_mul_f32_e32 v12, 0.5, v16
	v_rcp_f32_e32 v14, v14
	v_mul_f32_e64 v16, |v13|, -|v13|
	v_fmamk_f32 v15, v14, 0x3f87dc22, v206
	v_fmaak_f32 v15, v15, v14, 0x3fb5f0e3
	v_exp_f32_e32 v16, v16
	v_fmaak_f32 v15, v15, v14, 0xbe91a98e
	v_fmaak_f32 v15, v15, v14, 0x3e827906
	v_mul_f32_e32 v14, v14, v15
	v_fma_f32 v17, v210, v111, v207
	v_fma_f32 v13, -v16, v14, 1.0
	v_fmac_f32_e32 v17, v208, v110
	v_fmac_f32_e32 v17, v209, v115
	v_fma_f32 v12, |v12|, v13, v12
	v_mul_f32_e32 v10, v10, v12
	v_mul_f32_e32 v12, 0x3f596d27, v17
	v_fma_f32 v13, |v12|, s98, 1.0
	v_cvt_pk_bf16_f32 v10, v10, s0
	ds_write_b16 v22, v10 offset:544
	v_mul_f32_e32 v10, 0.5, v17
	v_rcp_f32_e32 v13, v13
	v_mul_f32_e64 v15, |v12|, -|v12|
	v_fmamk_f32 v14, v13, 0x3f87dc22, v206
	v_fmaak_f32 v14, v14, v13, 0x3fb5f0e3
	v_exp_f32_e32 v15, v15
	v_fmaak_f32 v14, v14, v13, 0xbe91a98e
	v_fmaak_f32 v14, v14, v13, 0x3e827906
	v_mul_f32_e32 v13, v13, v14
	v_fma_f32 v12, -v15, v13, 1.0
	v_fma_f32 v10, |v10|, v12, v10
; __device__ __forceinline__ u16 f2bf(float f) { return (u16)(pack2(f, f) & 0xffffu); }
; __device__ __forceinline__ float gelu_exact(float x) { return 0.5f * x * (1.0f + erf_f32(x * 0.70710678118654752f)); }
; template <int EPI>
; __device__ __forceinline__ void phase_gemm(const Params& p, const GemmDesc& d, char* shmc) {
;     ...
; #pragma unroll
;       for (int n = 0; n < 2; ++n) {
;         const int col = ewc * 32 + n * 16 + efr;
;         const int ch = ch0 + col;
;         const float w0 = cw[n][0], w1 = cw[n][1], w2 = cw[n][2], cb = cw[n][3];
; #pragma unroll
;         for (int ai = 0; ai < 2; ++ai)
; #pragma unroll
;           for (int m = 0; m < 4; ++m) {
;             const int s = ai * 32 + ewr * 16 + m * 4 + efq;
;             const f32x4 g = acc[ai][0][m][n];
;             const f32x4 v = acc[ai][1][m][n];
;             const float c0 = w0 * gp[ai][m][n] + w1 * g[0] + w2 * g[1] + cb;
;             const float c1 = w0 * g[0] + w1 * g[1] + w2 * g[2] + cb;
;             const float c2 = w0 * g[1] + w1 * g[2] + w2 * g[3] + cb;
;             const float c3 = w0 * g[2] + w1 * g[3] + w2 * gn[ai][m][n] + cb;
;             u16* sp = stg + (s * 4) * 136 + col;
;             sp[0] = f2bf(gelu_exact(c0) * v[0]);
;             sp[136] = f2bf(gelu_exact(c1) * v[1]);
;             sp[272] = f2bf(gelu_exact(c2) * v[2]);
;             sp[408] = f2bf(gelu_exact(c3) * v[3]);
;             if (s == 0) {
;               edge[0 * DFF + ch] = c0; edge[1 * DFF + ch] = g[0]; edge[2 * DFF + ch] = v[0];
;             }
;             if (s == 63) {
;               edge[3 * DFF + ch] = c3; edge[4 * DFF + ch] = g[3]; edge[5 * DFF + ch] = v[3];
;             }
;           }
	v_mul_f32_e32 v10, v11, v10
	v_cvt_pk_bf16_f32 v10, v10, s0
	ds_write_b16 v22, v10 offset:816
	v_fma_f32 v10, v208, v109, v207
	v_fmac_f32_e32 v10, v210, v104
	v_fmac_f32_e32 v10, v209, v105
	v_mul_f32_e32 v14, 0x3f596d27, v10
	v_fma_f32 v15, |v14|, s98, 1.0
	v_fma_f32 v11, v210, v105, v207
	v_fmac_f32_e32 v11, v208, v104
	v_fmac_f32_e32 v11, v209, v102
	v_rcp_f32_e32 v15, v15
	v_mul_f32_e64 v17, |v14|, -|v14|
	v_fmamk_f32 v16, v15, 0x3f87dc22, v206
	v_fmaak_f32 v16, v16, v15, 0x3fb5f0e3
	v_exp_f32_e32 v17, v17
	v_fmaak_f32 v16, v16, v15, 0xbe91a98e
	v_fmaak_f32 v16, v16, v15, 0x3e827906
	v_mul_f32_e32 v15, v15, v16
	v_fma_f32 v14, -v17, v15, 1.0
	v_mul_f32_e32 v10, 0.5, v10
	v_fma_f32 v10, |v10|, v14, v10
	v_mul_f32_e32 v8, v8, v10
	v_mul_f32_e32 v10, 0x3f596d27, v11
	v_fma_f32 v14, |v10|, s98, 1.0
	v_add3_u32 v18, s14, v74, v62
	v_cvt_pk_bf16_f32 v8, v8, s0
	ds_write_b16 v18, v8
	v_mul_f32_e32 v8, 0.5, v11
	v_rcp_f32_e32 v11, v14
	v_mul_f32_e64 v15, |v10|, -|v10|
	v_fmamk_f32 v14, v11, 0x3f87dc22, v206
	v_fmaak_f32 v14, v14, v11, 0x3fb5f0e3
	v_exp_f32_e32 v15, v15
	v_fmaak_f32 v14, v14, v11, 0xbe91a98e
	v_fmaak_f32 v14, v14, v11, 0x3e827906
	v_mul_f32_e32 v11, v11, v14
	v_fma_f32 v12, v210, v102, v207
	v_fma_f32 v10, -v15, v11, 1.0
	v_fmac_f32_e32 v12, v208, v105
	v_fmac_f32_e32 v12, v209, v103
	v_fma_f32 v8, |v8|, v10, v8
	v_mul_f32_e32 v8, v9, v8
	v_mul_f32_e32 v9, 0x3f596d27, v12
	v_fma_f32 v10, |v9|, s98, 1.0
	v_cvt_pk_bf16_f32 v8, v8, s0
	ds_write_b16 v18, v8 offset:272
	v_mul_f32_e32 v8, 0.5, v12
	v_rcp_f32_e32 v10, v10
	v_mul_f32_e64 v12, |v9|, -|v9|
	v_fmamk_f32 v11, v10, 0x3f87dc22, v206
	v_fmaak_f32 v11, v11, v10, 0x3fb5f0e3
	v_exp_f32_e32 v12, v12
	v_fmaak_f32 v11, v11, v10, 0xbe91a98e
	v_fmaak_f32 v11, v11, v10, 0x3e827906
	v_mul_f32_e32 v10, v10, v11
	v_fma_f32 v13, v210, v103, v207
	v_fma_f32 v9, -v12, v10, 1.0
	v_fmac_f32_e32 v13, v208, v102
	v_fmac_f32_e32 v13, v209, v107
	v_fma_f32 v8, |v8|, v9, v8
	v_mul_f32_e32 v6, v6, v8
	v_mul_f32_e32 v8, 0x3f596d27, v13
	v_fma_f32 v9, |v8|, s98, 1.0
	v_cvt_pk_bf16_f32 v6, v6, s0
	ds_write_b16 v18, v6 offset:544
	v_mul_f32_e32 v6, 0.5, v13
	v_rcp_f32_e32 v9, v9
	v_mul_f32_e64 v11, |v8|, -|v8|
	v_fmamk_f32 v10, v9, 0x3f87dc22, v206
	v_fmaak_f32 v10, v10, v9, 0x3fb5f0e3
	v_exp_f32_e32 v11, v11
	v_fmaak_f32 v10, v10, v9, 0xbe91a98e
	v_fmaak_f32 v10, v10, v9, 0x3e827906
	v_mul_f32_e32 v9, v9, v10
	v_fma_f32 v8, -v11, v9, 1.0
	v_fma_f32 v6, |v6|, v8, v6
	v_mul_f32_e32 v6, v7, v6
	v_cvt_pk_bf16_f32 v6, v6, s0
	ds_write_b16 v18, v6 offset:816
	v_fma_f32 v7, v208, v212, v207
	v_fmac_f32_e32 v7, v210, v98
	v_fmac_f32_e32 v7, v209, v99
	v_mul_f32_e32 v10, 0x3f596d27, v7
	v_fma_f32 v11, |v10|, s98, 1.0
	v_fma_f32 v8, v210, v99, v207
	v_fmac_f32_e32 v8, v208, v98
	v_fmac_f32_e32 v8, v209, v100
	v_rcp_f32_e32 v11, v11
	v_mul_f32_e64 v13, |v10|, -|v10|
	v_fmamk_f32 v12, v11, 0x3f87dc22, v206
	v_fmaak_f32 v12, v12, v11, 0x3fb5f0e3
	v_exp_f32_e32 v13, v13
	v_fmaak_f32 v12, v12, v11, 0xbe91a98e
	v_fmaak_f32 v12, v12, v11, 0x3e827906
	v_mul_f32_e32 v11, v11, v12
	v_fma_f32 v10, -v13, v11, 1.0
	v_mul_f32_e32 v7, 0.5, v7
	v_fma_f32 v7, |v7|, v10, v7
	v_mul_f32_e32 v4, v4, v7
	v_mul_f32_e32 v7, 0x3f596d27, v8
	v_fma_f32 v10, |v7|, s98, 1.0
	v_add3_u32 v14, s14, v70, v62
	v_cvt_pk_bf16_f32 v4, v4, s0
	ds_write_b16 v14, v4
	v_mul_f32_e32 v4, 0.5, v8
	v_rcp_f32_e32 v8, v10
	v_mul_f32_e64 v11, |v7|, -|v7|
	v_fmamk_f32 v10, v8, 0x3f87dc22, v206
	v_fmaak_f32 v10, v10, v8, 0x3fb5f0e3
	v_exp_f32_e32 v11, v11
	v_fmaak_f32 v10, v10, v8, 0xbe91a98e
	v_fmaak_f32 v10, v10, v8, 0x3e827906
	v_mul_f32_e32 v8, v8, v10
	v_fma_f32 v9, v210, v100, v207
	v_fma_f32 v7, -v11, v8, 1.0
	v_fmac_f32_e32 v9, v208, v99
	v_fmac_f32_e32 v9, v209, v101
	v_fma_f32 v4, |v4|, v7, v4
	v_mul_f32_e32 v4, v5, v4
	v_mul_f32_e32 v5, 0x3f596d27, v9
	v_fma_f32 v7, |v5|, s98, 1.0
	v_cvt_pk_bf16_f32 v4, v4, s0
	ds_write_b16 v14, v4 offset:272
	v_mul_f32_e32 v4, 0.5, v9
	v_rcp_f32_e32 v7, v7
	v_mul_f32_e64 v9, |v5|, -|v5|
	v_fmamk_f32 v8, v7, 0x3f87dc22, v206
	v_fmaak_f32 v8, v8, v7, 0x3fb5f0e3
	v_exp_f32_e32 v9, v9
	v_fmaak_f32 v8, v8, v7, 0xbe91a98e
	v_fmaak_f32 v8, v8, v7, 0x3e827906
	v_mul_f32_e32 v7, v7, v8
	v_fma_f32 v6, v210, v101, v207
	v_fma_f32 v5, -v9, v7, 1.0
	v_fmac_f32_e32 v6, v208, v100
	v_fmac_f32_e32 v6, v209, v211
	v_fma_f32 v4, |v4|, v5, v4
	v_mul_f32_e32 v2, v2, v4
	v_mul_f32_e32 v4, 0x3f596d27, v6
	v_fma_f32 v5, |v4|, s98, 1.0
	v_cvt_pk_bf16_f32 v2, v2, s0
	ds_write_b16 v14, v2 offset:544
	v_mul_f32_e32 v2, 0.5, v6
	v_rcp_f32_e32 v5, v5
	v_mul_f32_e64 v8, |v4|, -|v4|
	v_fmamk_f32 v7, v5, 0x3f87dc22, v206
	v_fmaak_f32 v7, v7, v5, 0x3fb5f0e3
	v_exp_f32_e32 v8, v8
	v_fmaak_f32 v7, v7, v5, 0xbe91a98e
	v_fmaak_f32 v7, v7, v5, 0x3e827906
	v_mul_f32_e32 v5, v5, v7
	v_fma_f32 v4, -v8, v5, 1.0
	v_fma_f32 v2, |v2|, v4, v2
	v_mul_f32_e32 v2, v3, v2
	v_cvt_pk_bf16_f32 v2, v2, s0
	ds_write_b16 v14, v2 offset:816
	s_and_saveexec_b64 s[10:11], s[8:9]
	s_cbranch_execz .LBB0_1146
	v_add_co_u32_e32 v4, vcc, 0x10000, v58
	s_nop 1
	v_addc_co_u32_e32 v5, vcc, 0, v59, vcc
	global_store_dword v[4:5], v6, off offset:2048
	v_add_co_u32_e32 v4, vcc, 0x16000, v58
	s_nop 1
	v_addc_co_u32_e32 v5, vcc, 0, v59, vcc
	global_store_dword v[4:5], v101, off
	v_add_co_u32_e32 v4, vcc, 0x1b000, v58
	s_nop 1
	v_addc_co_u32_e32 v5, vcc, 0, v59, vcc
	global_store_dword v[4:5], v3, off offset:2048
	s_branch .LBB0_1146
